# s_setprio: static raise for workgroups >= 256 in the GEMM phases plus priority 1 during MFMA groups 0-6 of every K-stage (0 in the last group); nt epilogue stores kept
# speedup vs baseline: 1.0139x; 1.0139x over previous
; template <class Epi>
; DI void gemm_tile(char* smem, const bf16_t* __restrict__ A0, int lda0, int ksplit, const bf16_t* __restrict__ A1, int lda1,
;                   const bf16_t* __restrict__ Bt, int K, int row0, int col0, const Epi& epi, int tid) {
;   constexpr int BK = 32, PITCH = 40, BUF = (256 + 128) * PITCH;
;   bf16_t* sbase = (bf16_t*)smem;
;   const int lane = tid & 63, wid = tid >> 6, wr = wid >> 1, wc = wid & 1, fr = lane & 15, fq = lane >> 4;
;   f32x4 acc[8][4];
; #pragma unroll
;   for (int m = 0; m < 8; ++m)
; #pragma unroll
;     for (int n = 0; n < 4; ++n) acc[m][n] = (f32x4){0.f, 0.f, 0.f, 0.f};
;   u32x4 ra[2][4], rb[2][2];
;   const int nk = K / BK;
;   const int sr = tid >> 2, scv = tid & 3;
; template <class Epi>
; DI void gemm_phase(char* smem, const bf16_t* A0, int lda0, int ksplit, const bf16_t* A1, int lda1, const bf16_t* Bt, int K, int nN, const Epi& epi, int tid) {
;   const int G = gridDim.x;
;   if ((G & 7) == 0) {
;     const int x = blockIdx.x & 7, l = blockIdx.x >> 3, L = G >> 3, per = 8 * nN, tot = 2 * per;
;     for (int q = l; q < tot; q += L) { const int rgl = q / per, rem = q % per, ct = rem >> 3, rt = (x * 2 + rgl) * 8 + (rem & 7);
;       gemm_tile(smem, A0, lda0, ksplit, A1, lda1, Bt, K, rt * 256, ct * 128, epi, tid); }
.LBB0_60:
	s_load_dwordx4 s[52:55], s[74:75], 0x160
	s_load_dwordx8 s[0:7], s[74:75], 0x140
	s_load_dwordx16 s[36:51], s[74:75], 0x80
	s_cmp_gt_i32 s94, 1
	v_mbcnt_lo_u32_b32 v194, -1, 0
	s_waitcnt lgkmcnt(0)
	v_writelane_b32 v253, s0, 48
	s_nop 1
	v_writelane_b32 v253, s1, 49
	v_writelane_b32 v253, s2, 50
	v_writelane_b32 v253, s3, 51
	v_writelane_b32 v253, s4, 52
	v_writelane_b32 v253, s5, 53
	v_writelane_b32 v253, s6, 54
	v_writelane_b32 v253, s7, 55
	s_cselect_b64 s[0:1], -1, 0
	s_cmp_lt_i32 s95, 2
	s_cselect_b64 s[2:3], -1, 0
	s_or_b64 s[0:1], s[0:1], s[2:3]
	s_and_b64 vcc, exec, s[0:1]
	s_cbranch_vccnz .LBB0_344
	s_load_dword s26, s[74:75], 0x180
	s_add_u32 s0, s92, 0x3800000
	s_addc_u32 s1, s93, 0
	s_and_b32 s28, s72, 0xffffffc0
	v_mbcnt_hi_u32_b32 v195, -1, v194
	s_waitcnt lgkmcnt(0)
	s_and_b32 s27, s26, 7
	s_cmp_lg_u32 s27, 0
	v_add_u32_e32 v196, s28, v195
	v_mbcnt_lo_u32_b32 v240, -1, 0
	v_mbcnt_hi_u32_b32 v240, -1, v240
	s_lshr_b32 s23, s72, 6
	s_lshl_b32 s100, s23, 10
	v_and_b32_e32 v241, 15, v240
	v_lshrrev_b32_e32 v242, 4, v240
	v_bfe_u32 v243, v240, 3, 1
	v_mul_u32_u24_e32 v243, 3, v243
	v_xor_b32_e32 v243, v242, v243
	v_lshlrev_b32_e32 v243, 4, v243
	v_lshl_add_u32 v243, v241, 6, v243
	s_lshr_b32 s22, s23, 1
	s_lshl_b32 s22, s22, 13
	v_add_u32_e32 v230, s22, v243
	s_and_b32 s22, s23, 1
	s_lshl_b32 s22, s22, 12
	s_add_u32 s22, s22, 16384
	v_add_u32_e32 v231, s22, v243
	s_lshr_b32 s22, s23, 1
	s_lshl_b32 s22, s22, 7
	v_add_u32_e32 v244, s22, v241
	s_and_b32 s22, s23, 1
	s_lshl_b32 s22, s22, 6
	v_lshl_add_u32 v245, v242, 2, s22
	s_movk_i32 s22, 3584
	v_mul_lo_u32 v246, v244, s22
	v_lshl_add_u32 v234, v245, 1, v246
	s_movk_i32 s22, 5184
	v_mul_lo_u32 v246, v244, s22
	v_lshl_add_u32 v235, v245, 1, v246
	s_mul_i32 s22, s23, 18432
	v_mul_u32_u24_e32 v246, 144, v241
	v_lshl_add_u32 v246, v242, 3, v246
	v_add_u32_e32 v236, s22, v246
	v_lshrrev_b32_e32 v246, 3, v240
	v_mul_u32_u24_e32 v246, 144, v246
	v_and_b32_e32 v247, 7, v240
	v_lshl_add_u32 v246, v247, 4, v246
	v_add_u32_e32 v237, s22, v246
	s_lshr_b32 s22, s23, 1
	s_lshl_b32 s22, s22, 7
	v_lshrrev_b32_e32 v246, 3, v240
	v_add_u32_e32 v246, s22, v246
	s_and_b32 s22, s23, 1
	s_lshl_b32 s22, s22, 6
	v_lshl_add_u32 v248, v247, 3, s22
	s_movk_i32 s22, 3584
	v_mul_lo_u32 v247, v246, s22
	v_lshl_add_u32 v238, v248, 1, v247
	s_movk_i32 s22, 5184
	v_mul_lo_u32 v247, v246, s22
	v_lshl_add_u32 v239, v248, 1, v247
	v_lshrrev_b32_e32 v241, 2, v240
	s_lshl_b32 s22, s23, 4
	v_add_u32_e32 v241, s22, v241
	v_bfe_u32 v242, v240, 5, 1
	v_mul_u32_u24_e32 v242, 3, v242
	v_and_b32_e32 v243, 3, v240
	v_xor_b32_e32 v243, v243, v242
	v_lshlrev_b32_e32 v243, 4, v243
	s_mov_b32 s22, 2048
	v_mad_u32_u24 v224, v241, s22, v243
	v_add_u32_e32 v225, 0x20000, v224
	v_add_u32_e32 v226, 0x40000, v224
	v_add_u32_e32 v227, 0x60000, v224
	s_mov_b32 s22, 2048
	v_mad_u32_u24 v228, v241, s22, v243
	v_add_u32_e32 v229, 0x20000, v228
	s_cmpk_gt_u32 s96, 0xff
	s_cbranch_scc0 .Lg1_prio
	s_setprio 1
.Lg1_prio:
	s_lshr_b32 s29, s96, 3
	s_and_b32 s101, s96, 7
	s_lshl_b32 s101, s101, 1
	s_waitcnt lgkmcnt(0)

; #define LWRITE(S, buf) do { bf16_t* sA_ = sbase + (buf) * BUF; bf16_t* sB_ = sA_ + 256 * PITCH; \
;     _Pragma("unroll") for (int i_ = 0; i_ < 4; ++i_) *(u32x4*)(sA_ + (sr + i_ * 64) * PITCH + scv * 8) = ra[S][i_]; \
;     _Pragma("unroll") for (int i_ = 0; i_ < 2; ++i_) *(u32x4*)(sB_ + (sr + i_ * 64) * PITCH + scv * 8) = rb[S][i_]; } while (0)
; template <class Epi>
; DI void gemm_tile(char* smem, const bf16_t* __restrict__ A0, int lda0, int ksplit, const bf16_t* __restrict__ A1, int lda1,
;                   const bf16_t* __restrict__ Bt, int K, int row0, int col0, const Epi& epi, int tid) {
;     ...
;     for (int kt = 0; kt < nk; kt += 2) {
;       LWRITE(1, 1);
;       __builtin_amdgcn_sched_barrier(0);
;       GLOAD(1, (kt + 3 < last ? kt + 3 : last));
;       __builtin_amdgcn_sched_barrier(0);
;       COMPUTE(0);
;       __syncthreads();
;       LWRITE(0, 0);
;       __builtin_amdgcn_sched_barrier(0);
;       GLOAD(0, (kt + 4 < last ? kt + 4 : last));
;       __builtin_amdgcn_sched_barrier(0);
;       COMPUTE(1);
;       __syncthreads();
;     }
.Lg1_kloop:
	s_waitcnt vmcnt(6)
	s_waitcnt lgkmcnt(0)
	s_barrier
	v_add_u32_e32 v232, s31, v230
	v_add_u32_e32 v233, s31, v231
	s_add_u32 s22, s30, s100
	s_setprio 1
	v_mfma_f32_16x16x32_bf16 v[0:3], v[128:131], v[144:147], v[0:3]
	v_mfma_f32_16x16x32_bf16 v[4:7], v[132:135], v[144:147], v[4:7]
	v_mfma_f32_16x16x32_bf16 v[8:11], v[136:139], v[144:147], v[8:11]
	v_mfma_f32_16x16x32_bf16 v[12:15], v[140:143], v[144:147], v[12:15]
	ds_read_b128 v[176:179], v233 offset:0
	ds_read_b128 v[180:183], v233 offset:1024
	s_add_u32 m0, s22, 0
	s_nop 0
	global_load_lds_dwordx4 v224, s[0:1]
	v_mfma_f32_16x16x32_bf16 v[16:19], v[128:131], v[148:151], v[16:19]
	v_mfma_f32_16x16x32_bf16 v[20:23], v[132:135], v[148:151], v[20:23]
	v_mfma_f32_16x16x32_bf16 v[24:27], v[136:139], v[148:151], v[24:27]
	v_mfma_f32_16x16x32_bf16 v[28:31], v[140:143], v[148:151], v[28:31]
	ds_read_b128 v[184:187], v233 offset:2048
	ds_read_b128 v[188:191], v233 offset:3072
	s_add_u32 m0, s22, 4096
	s_nop 0
	global_load_lds_dwordx4 v225, s[0:1]
	v_mfma_f32_16x16x32_bf16 v[32:35], v[128:131], v[152:155], v[32:35]
	v_mfma_f32_16x16x32_bf16 v[36:39], v[132:135], v[152:155], v[36:39]
	v_mfma_f32_16x16x32_bf16 v[40:43], v[136:139], v[152:155], v[40:43]
	v_mfma_f32_16x16x32_bf16 v[44:47], v[140:143], v[152:155], v[44:47]
	ds_read_b128 v[192:195], v232 offset:0
	ds_read_b128 v[196:199], v232 offset:1024
	s_add_u32 m0, s22, 8192
	s_nop 0
	global_load_lds_dwordx4 v226, s[0:1]
	v_mfma_f32_16x16x32_bf16 v[48:51], v[128:131], v[156:159], v[48:51]
	v_mfma_f32_16x16x32_bf16 v[52:55], v[132:135], v[156:159], v[52:55]
	v_mfma_f32_16x16x32_bf16 v[56:59], v[136:139], v[156:159], v[56:59]
	v_mfma_f32_16x16x32_bf16 v[60:63], v[140:143], v[156:159], v[60:63]
	ds_read_b128 v[200:203], v232 offset:2048
	ds_read_b128 v[204:207], v232 offset:3072
	s_add_u32 m0, s22, 12288
	s_nop 0
	global_load_lds_dwordx4 v227, s[0:1]
	v_mfma_f32_16x16x32_bf16 v[64:67], v[128:131], v[160:163], v[64:67]
	v_mfma_f32_16x16x32_bf16 v[68:71], v[132:135], v[160:163], v[68:71]
	v_mfma_f32_16x16x32_bf16 v[72:75], v[136:139], v[160:163], v[72:75]
	v_mfma_f32_16x16x32_bf16 v[76:79], v[140:143], v[160:163], v[76:79]
	ds_read_b128 v[208:211], v232 offset:4096
	s_add_u32 m0, s22, 16384
	s_nop 0
	global_load_lds_dwordx4 v228, s[2:3]
	v_mfma_f32_16x16x32_bf16 v[80:83], v[128:131], v[164:167], v[80:83]
	v_mfma_f32_16x16x32_bf16 v[84:87], v[132:135], v[164:167], v[84:87]
	v_mfma_f32_16x16x32_bf16 v[88:91], v[136:139], v[164:167], v[88:91]
	v_mfma_f32_16x16x32_bf16 v[92:95], v[140:143], v[164:167], v[92:95]
	ds_read_b128 v[212:215], v232 offset:5120
	s_add_u32 m0, s22, 20480
	s_nop 0
	global_load_lds_dwordx4 v229, s[2:3]
	v_mfma_f32_16x16x32_bf16 v[96:99], v[128:131], v[168:171], v[96:99]
	v_mfma_f32_16x16x32_bf16 v[100:103], v[132:135], v[168:171], v[100:103]
	v_mfma_f32_16x16x32_bf16 v[104:107], v[136:139], v[168:171], v[104:107]
	v_mfma_f32_16x16x32_bf16 v[108:111], v[140:143], v[168:171], v[108:111]
	ds_read_b128 v[216:219], v232 offset:6144
	s_add_u32 s0, s0, 64
	s_addc_u32 s1, s1, 0
	s_add_u32 s2, s2, 64
	s_addc_u32 s3, s3, 0
	s_add_u32 s99, s99, 1
	s_add_u32 s30, s30, 24576
	s_cmp_eq_u32 s30, 73728
	s_cselect_b32 s30, 0, s30
	s_add_u32 s31, s31, 24576
	s_cmp_eq_u32 s31, 73728
	s_cselect_b32 s31, 0, s31
	v_mfma_f32_16x16x32_bf16 v[112:115], v[128:131], v[172:175], v[112:115]
	v_mfma_f32_16x16x32_bf16 v[116:119], v[132:135], v[172:175], v[116:119]
	v_mfma_f32_16x16x32_bf16 v[120:123], v[136:139], v[172:175], v[120:123]
	v_mfma_f32_16x16x32_bf16 v[124:127], v[140:143], v[172:175], v[124:127]
	ds_read_b128 v[220:223], v232 offset:7168
	s_setprio 0
	s_waitcnt vmcnt(6)
	s_waitcnt lgkmcnt(0)
	s_barrier
	v_add_u32_e32 v232, s31, v230
	v_add_u32_e32 v233, s31, v231
	s_add_u32 s22, s30, s100
	s_setprio 1
	v_mfma_f32_16x16x32_bf16 v[0:3], v[176:179], v[192:195], v[0:3]
	v_mfma_f32_16x16x32_bf16 v[4:7], v[180:183], v[192:195], v[4:7]
	v_mfma_f32_16x16x32_bf16 v[8:11], v[184:187], v[192:195], v[8:11]
	v_mfma_f32_16x16x32_bf16 v[12:15], v[188:191], v[192:195], v[12:15]
	ds_read_b128 v[128:131], v233 offset:0
	ds_read_b128 v[132:135], v233 offset:1024
	s_add_u32 m0, s22, 0
	s_nop 0
	global_load_lds_dwordx4 v224, s[0:1]
	v_mfma_f32_16x16x32_bf16 v[16:19], v[176:179], v[196:199], v[16:19]
	v_mfma_f32_16x16x32_bf16 v[20:23], v[180:183], v[196:199], v[20:23]
	v_mfma_f32_16x16x32_bf16 v[24:27], v[184:187], v[196:199], v[24:27]
	v_mfma_f32_16x16x32_bf16 v[28:31], v[188:191], v[196:199], v[28:31]
	ds_read_b128 v[136:139], v233 offset:2048
	ds_read_b128 v[140:143], v233 offset:3072
	s_add_u32 m0, s22, 4096
	s_nop 0
	global_load_lds_dwordx4 v225, s[0:1]
	v_mfma_f32_16x16x32_bf16 v[32:35], v[176:179], v[200:203], v[32:35]
	v_mfma_f32_16x16x32_bf16 v[36:39], v[180:183], v[200:203], v[36:39]
	v_mfma_f32_16x16x32_bf16 v[40:43], v[184:187], v[200:203], v[40:43]
	v_mfma_f32_16x16x32_bf16 v[44:47], v[188:191], v[200:203], v[44:47]
	ds_read_b128 v[144:147], v232 offset:0
	ds_read_b128 v[148:151], v232 offset:1024
	s_add_u32 m0, s22, 8192
	s_nop 0
	global_load_lds_dwordx4 v226, s[0:1]
	v_mfma_f32_16x16x32_bf16 v[48:51], v[176:179], v[204:207], v[48:51]
	v_mfma_f32_16x16x32_bf16 v[52:55], v[180:183], v[204:207], v[52:55]
	v_mfma_f32_16x16x32_bf16 v[56:59], v[184:187], v[204:207], v[56:59]
	v_mfma_f32_16x16x32_bf16 v[60:63], v[188:191], v[204:207], v[60:63]
	ds_read_b128 v[152:155], v232 offset:2048
	ds_read_b128 v[156:159], v232 offset:3072
	s_add_u32 m0, s22, 12288
	s_nop 0
	global_load_lds_dwordx4 v227, s[0:1]
	v_mfma_f32_16x16x32_bf16 v[64:67], v[176:179], v[208:211], v[64:67]
	v_mfma_f32_16x16x32_bf16 v[68:71], v[180:183], v[208:211], v[68:71]
; #define LWRITE(S, buf) do { bf16_t* sA_ = sbase + (buf) * BUF; bf16_t* sB_ = sA_ + 256 * PITCH; \
;     _Pragma("unroll") for (int i_ = 0; i_ < 4; ++i_) *(u32x4*)(sA_ + (sr + i_ * 64) * PITCH + scv * 8) = ra[S][i_]; \
;     _Pragma("unroll") for (int i_ = 0; i_ < 2; ++i_) *(u32x4*)(sB_ + (sr + i_ * 64) * PITCH + scv * 8) = rb[S][i_]; } while (0)
; template <class Epi>
; DI void gemm_tile(char* smem, const bf16_t* __restrict__ A0, int lda0, int ksplit, const bf16_t* __restrict__ A1, int lda1,
;                   const bf16_t* __restrict__ Bt, int K, int row0, int col0, const Epi& epi, int tid) {
;     ...
;   __syncthreads();
;   {
;     const int last = nk - 1;
;     GLOAD(0, 0);
;     __builtin_amdgcn_sched_barrier(0);
;     GLOAD(1, 1);
;     __builtin_amdgcn_sched_barrier(0);
;     LWRITE(0, 0);
;     __builtin_amdgcn_sched_barrier(0);
;     GLOAD(0, (2 < last ? 2 : last));
;     __builtin_amdgcn_sched_barrier(0);
;     __syncthreads();
;     for (int kt = 0; kt < nk; kt += 2) {
;       LWRITE(1, 1);
;       __builtin_amdgcn_sched_barrier(0);
;       GLOAD(1, (kt + 3 < last ? kt + 3 : last));
;       __builtin_amdgcn_sched_barrier(0);
;       COMPUTE(0);
;       __syncthreads();
;       LWRITE(0, 0);
;       __builtin_amdgcn_sched_barrier(0);
;       GLOAD(0, (kt + 4 < last ? kt + 4 : last));
;       __builtin_amdgcn_sched_barrier(0);
;       COMPUTE(1);
;       __syncthreads();
	v_mfma_f32_16x16x32_bf16 v[72:75], v[184:187], v[208:211], v[72:75]
	v_mfma_f32_16x16x32_bf16 v[76:79], v[188:191], v[208:211], v[76:79]
	ds_read_b128 v[160:163], v232 offset:4096
	s_add_u32 m0, s22, 16384
	s_nop 0
	global_load_lds_dwordx4 v228, s[2:3]
	v_mfma_f32_16x16x32_bf16 v[80:83], v[176:179], v[212:215], v[80:83]
	v_mfma_f32_16x16x32_bf16 v[84:87], v[180:183], v[212:215], v[84:87]
	v_mfma_f32_16x16x32_bf16 v[88:91], v[184:187], v[212:215], v[88:91]
	v_mfma_f32_16x16x32_bf16 v[92:95], v[188:191], v[212:215], v[92:95]
	ds_read_b128 v[164:167], v232 offset:5120
	s_add_u32 m0, s22, 20480
	s_nop 0
	global_load_lds_dwordx4 v229, s[2:3]
	v_mfma_f32_16x16x32_bf16 v[96:99], v[176:179], v[216:219], v[96:99]
	v_mfma_f32_16x16x32_bf16 v[100:103], v[180:183], v[216:219], v[100:103]
	v_mfma_f32_16x16x32_bf16 v[104:107], v[184:187], v[216:219], v[104:107]
	v_mfma_f32_16x16x32_bf16 v[108:111], v[188:191], v[216:219], v[108:111]
	ds_read_b128 v[168:171], v232 offset:6144
	s_add_u32 s0, s0, 64
	s_addc_u32 s1, s1, 0
	s_add_u32 s2, s2, 64
	s_addc_u32 s3, s3, 0
	s_add_u32 s99, s99, 1
	s_add_u32 s30, s30, 24576
	s_cmp_eq_u32 s30, 73728
	s_cselect_b32 s30, 0, s30
	s_add_u32 s31, s31, 24576
	s_cmp_eq_u32 s31, 73728
	s_cselect_b32 s31, 0, s31
	v_mfma_f32_16x16x32_bf16 v[112:115], v[176:179], v[220:223], v[112:115]
	v_mfma_f32_16x16x32_bf16 v[116:119], v[180:183], v[220:223], v[116:119]
	v_mfma_f32_16x16x32_bf16 v[120:123], v[184:187], v[220:223], v[120:123]
	v_mfma_f32_16x16x32_bf16 v[124:127], v[188:191], v[220:223], v[124:127]
	ds_read_b128 v[172:175], v232 offset:7168
	s_setprio 0
	s_add_u32 s98, s98, 2
	s_cmp_lt_u32 s98, 28
	s_cbranch_scc1 .Lg1_kloop
	s_waitcnt vmcnt(6)
	s_waitcnt lgkmcnt(0)
	s_barrier
	v_add_u32_e32 v232, s31, v230
	v_add_u32_e32 v233, s31, v231
	s_add_u32 s22, s30, s100
	s_setprio 1
	v_mfma_f32_16x16x32_bf16 v[0:3], v[128:131], v[144:147], v[0:3]
	v_mfma_f32_16x16x32_bf16 v[4:7], v[132:135], v[144:147], v[4:7]
	v_mfma_f32_16x16x32_bf16 v[8:11], v[136:139], v[144:147], v[8:11]
	v_mfma_f32_16x16x32_bf16 v[12:15], v[140:143], v[144:147], v[12:15]
	ds_read_b128 v[176:179], v233 offset:0
	ds_read_b128 v[180:183], v233 offset:1024
	s_add_u32 m0, s22, 0
	s_nop 0
	global_load_lds_dwordx4 v224, s[0:1]
	v_mfma_f32_16x16x32_bf16 v[16:19], v[128:131], v[148:151], v[16:19]
	v_mfma_f32_16x16x32_bf16 v[20:23], v[132:135], v[148:151], v[20:23]
	v_mfma_f32_16x16x32_bf16 v[24:27], v[136:139], v[148:151], v[24:27]
	v_mfma_f32_16x16x32_bf16 v[28:31], v[140:143], v[148:151], v[28:31]
	ds_read_b128 v[184:187], v233 offset:2048
	ds_read_b128 v[188:191], v233 offset:3072
	s_add_u32 m0, s22, 4096
	s_nop 0
	global_load_lds_dwordx4 v225, s[0:1]
	v_mfma_f32_16x16x32_bf16 v[32:35], v[128:131], v[152:155], v[32:35]
	v_mfma_f32_16x16x32_bf16 v[36:39], v[132:135], v[152:155], v[36:39]
	v_mfma_f32_16x16x32_bf16 v[40:43], v[136:139], v[152:155], v[40:43]
	v_mfma_f32_16x16x32_bf16 v[44:47], v[140:143], v[152:155], v[44:47]
	ds_read_b128 v[192:195], v232 offset:0
	ds_read_b128 v[196:199], v232 offset:1024
	s_add_u32 m0, s22, 8192
	s_nop 0
	global_load_lds_dwordx4 v226, s[0:1]
	v_mfma_f32_16x16x32_bf16 v[48:51], v[128:131], v[156:159], v[48:51]
	v_mfma_f32_16x16x32_bf16 v[52:55], v[132:135], v[156:159], v[52:55]
	v_mfma_f32_16x16x32_bf16 v[56:59], v[136:139], v[156:159], v[56:59]
	v_mfma_f32_16x16x32_bf16 v[60:63], v[140:143], v[156:159], v[60:63]
	ds_read_b128 v[200:203], v232 offset:2048
	ds_read_b128 v[204:207], v232 offset:3072
	s_add_u32 m0, s22, 12288
	s_nop 0
	global_load_lds_dwordx4 v227, s[0:1]
	v_mfma_f32_16x16x32_bf16 v[64:67], v[128:131], v[160:163], v[64:67]
	v_mfma_f32_16x16x32_bf16 v[68:71], v[132:135], v[160:163], v[68:71]
	v_mfma_f32_16x16x32_bf16 v[72:75], v[136:139], v[160:163], v[72:75]
	v_mfma_f32_16x16x32_bf16 v[76:79], v[140:143], v[160:163], v[76:79]
	ds_read_b128 v[208:211], v232 offset:4096
	s_add_u32 m0, s22, 16384
	s_nop 0
	global_load_lds_dwordx4 v228, s[2:3]
	v_mfma_f32_16x16x32_bf16 v[80:83], v[128:131], v[164:167], v[80:83]
	v_mfma_f32_16x16x32_bf16 v[84:87], v[132:135], v[164:167], v[84:87]
	v_mfma_f32_16x16x32_bf16 v[88:91], v[136:139], v[164:167], v[88:91]
	v_mfma_f32_16x16x32_bf16 v[92:95], v[140:143], v[164:167], v[92:95]
	ds_read_b128 v[212:215], v232 offset:5120
	s_add_u32 m0, s22, 20480
	s_nop 0
	global_load_lds_dwordx4 v229, s[2:3]
	v_mfma_f32_16x16x32_bf16 v[96:99], v[128:131], v[168:171], v[96:99]
	v_mfma_f32_16x16x32_bf16 v[100:103], v[132:135], v[168:171], v[100:103]
	v_mfma_f32_16x16x32_bf16 v[104:107], v[136:139], v[168:171], v[104:107]
	v_mfma_f32_16x16x32_bf16 v[108:111], v[140:143], v[168:171], v[108:111]
	ds_read_b128 v[216:219], v232 offset:6144
	s_add_u32 s0, s0, 64
	s_addc_u32 s1, s1, 0
	s_add_u32 s2, s2, 64
	s_addc_u32 s3, s3, 0
	s_add_u32 s99, s99, 1
	s_add_u32 s30, s30, 24576
	s_cmp_eq_u32 s30, 73728
	s_cselect_b32 s30, 0, s30
	s_add_u32 s31, s31, 24576
	s_cmp_eq_u32 s31, 73728
	s_cselect_b32 s31, 0, s31
	v_mfma_f32_16x16x32_bf16 v[112:115], v[128:131], v[172:175], v[112:115]
	v_mfma_f32_16x16x32_bf16 v[116:119], v[132:135], v[172:175], v[116:119]
	v_mfma_f32_16x16x32_bf16 v[120:123], v[136:139], v[172:175], v[120:123]
	v_mfma_f32_16x16x32_bf16 v[124:127], v[140:143], v[172:175], v[124:127]
	ds_read_b128 v[220:223], v232 offset:7168
	s_setprio 0
	s_waitcnt vmcnt(6)
	s_waitcnt lgkmcnt(0)
	s_barrier
; #define LWRITE(S, buf) do { bf16_t* sA_ = sbase + (buf) * BUF; bf16_t* sB_ = sA_ + 256 * PITCH; \
;     _Pragma("unroll") for (int i_ = 0; i_ < 4; ++i_) *(u32x4*)(sA_ + (sr + i_ * 64) * PITCH + scv * 8) = ra[S][i_]; \
;     _Pragma("unroll") for (int i_ = 0; i_ < 2; ++i_) *(u32x4*)(sB_ + (sr + i_ * 64) * PITCH + scv * 8) = rb[S][i_]; } while (0)
; template <class Epi>
; DI void gemm_tile(char* smem, const bf16_t* __restrict__ A0, int lda0, int ksplit, const bf16_t* __restrict__ A1, int lda1,
;                   const bf16_t* __restrict__ Bt, int K, int row0, int col0, const Epi& epi, int tid) {
;     ...
;   __syncthreads();
;   {
;     const int last = nk - 1;
;     GLOAD(0, 0);
;     __builtin_amdgcn_sched_barrier(0);
;     GLOAD(1, 1);
;     __builtin_amdgcn_sched_barrier(0);
;     LWRITE(0, 0);
;     __builtin_amdgcn_sched_barrier(0);
;     GLOAD(0, (2 < last ? 2 : last));
;     __builtin_amdgcn_sched_barrier(0);
;     __syncthreads();
;     for (int kt = 0; kt < nk; kt += 2) {
;       LWRITE(1, 1);
;       __builtin_amdgcn_sched_barrier(0);
;       GLOAD(1, (kt + 3 < last ? kt + 3 : last));
;       __builtin_amdgcn_sched_barrier(0);
;       COMPUTE(0);
;       __syncthreads();
;       LWRITE(0, 0);
;       __builtin_amdgcn_sched_barrier(0);
;       GLOAD(0, (kt + 4 < last ? kt + 4 : last));
;       __builtin_amdgcn_sched_barrier(0);
;       COMPUTE(1);
;       __syncthreads();
	v_add_u32_e32 v232, s31, v230
	v_add_u32_e32 v233, s31, v231
	s_setprio 1
	v_mfma_f32_16x16x32_bf16 v[0:3], v[176:179], v[192:195], v[0:3]
	v_mfma_f32_16x16x32_bf16 v[4:7], v[180:183], v[192:195], v[4:7]
	v_mfma_f32_16x16x32_bf16 v[8:11], v[184:187], v[192:195], v[8:11]
	v_mfma_f32_16x16x32_bf16 v[12:15], v[188:191], v[192:195], v[12:15]
	ds_read_b128 v[128:131], v233 offset:0
	ds_read_b128 v[132:135], v233 offset:1024
	v_mfma_f32_16x16x32_bf16 v[16:19], v[176:179], v[196:199], v[16:19]
	v_mfma_f32_16x16x32_bf16 v[20:23], v[180:183], v[196:199], v[20:23]
	v_mfma_f32_16x16x32_bf16 v[24:27], v[184:187], v[196:199], v[24:27]
	v_mfma_f32_16x16x32_bf16 v[28:31], v[188:191], v[196:199], v[28:31]
	ds_read_b128 v[136:139], v233 offset:2048
	ds_read_b128 v[140:143], v233 offset:3072
	v_mfma_f32_16x16x32_bf16 v[32:35], v[176:179], v[200:203], v[32:35]
	v_mfma_f32_16x16x32_bf16 v[36:39], v[180:183], v[200:203], v[36:39]
	v_mfma_f32_16x16x32_bf16 v[40:43], v[184:187], v[200:203], v[40:43]
	v_mfma_f32_16x16x32_bf16 v[44:47], v[188:191], v[200:203], v[44:47]
	ds_read_b128 v[144:147], v232 offset:0
	ds_read_b128 v[148:151], v232 offset:1024
	v_mfma_f32_16x16x32_bf16 v[48:51], v[176:179], v[204:207], v[48:51]
	v_mfma_f32_16x16x32_bf16 v[52:55], v[180:183], v[204:207], v[52:55]
	v_mfma_f32_16x16x32_bf16 v[56:59], v[184:187], v[204:207], v[56:59]
	v_mfma_f32_16x16x32_bf16 v[60:63], v[188:191], v[204:207], v[60:63]
	ds_read_b128 v[152:155], v232 offset:2048
	ds_read_b128 v[156:159], v232 offset:3072
	v_mfma_f32_16x16x32_bf16 v[64:67], v[176:179], v[208:211], v[64:67]
	v_mfma_f32_16x16x32_bf16 v[68:71], v[180:183], v[208:211], v[68:71]
	v_mfma_f32_16x16x32_bf16 v[72:75], v[184:187], v[208:211], v[72:75]
	v_mfma_f32_16x16x32_bf16 v[76:79], v[188:191], v[208:211], v[76:79]
	ds_read_b128 v[160:163], v232 offset:4096
	v_mfma_f32_16x16x32_bf16 v[80:83], v[176:179], v[212:215], v[80:83]
	v_mfma_f32_16x16x32_bf16 v[84:87], v[180:183], v[212:215], v[84:87]
	v_mfma_f32_16x16x32_bf16 v[88:91], v[184:187], v[212:215], v[88:91]
	v_mfma_f32_16x16x32_bf16 v[92:95], v[188:191], v[212:215], v[92:95]
	ds_read_b128 v[164:167], v232 offset:5120
	v_mfma_f32_16x16x32_bf16 v[96:99], v[176:179], v[216:219], v[96:99]
	v_mfma_f32_16x16x32_bf16 v[100:103], v[180:183], v[216:219], v[100:103]
	v_mfma_f32_16x16x32_bf16 v[104:107], v[184:187], v[216:219], v[104:107]
	v_mfma_f32_16x16x32_bf16 v[108:111], v[188:191], v[216:219], v[108:111]
	ds_read_b128 v[168:171], v232 offset:6144
	s_add_u32 s31, s31, 24576
	s_cmp_eq_u32 s31, 73728
	s_cselect_b32 s31, 0, s31
	v_mfma_f32_16x16x32_bf16 v[112:115], v[176:179], v[220:223], v[112:115]
	v_mfma_f32_16x16x32_bf16 v[116:119], v[180:183], v[220:223], v[116:119]
	v_mfma_f32_16x16x32_bf16 v[120:123], v[184:187], v[220:223], v[120:123]
	v_mfma_f32_16x16x32_bf16 v[124:127], v[188:191], v[220:223], v[124:127]
	ds_read_b128 v[172:175], v232 offset:7168
	s_setprio 0
	s_waitcnt vmcnt(0)
	s_waitcnt lgkmcnt(0)
	s_barrier
; #define LWRITE(S, buf) do { bf16_t* sA_ = sbase + (buf) * BUF; bf16_t* sB_ = sA_ + 256 * PITCH; \
;     _Pragma("unroll") for (int i_ = 0; i_ < 4; ++i_) *(u32x4*)(sA_ + (sr + i_ * 64) * PITCH + scv * 8) = ra[S][i_]; \
;     _Pragma("unroll") for (int i_ = 0; i_ < 2; ++i_) *(u32x4*)(sB_ + (sr + i_ * 64) * PITCH + scv * 8) = rb[S][i_]; } while (0)
; template <class Epi>
; DI void gemm_tile(char* smem, const bf16_t* __restrict__ A0, int lda0, int ksplit, const bf16_t* __restrict__ A1, int lda1,
;                   const bf16_t* __restrict__ Bt, int K, int row0, int col0, const Epi& epi, int tid) {
;     ...
;   __syncthreads();
;   {
;     const int last = nk - 1;
;     GLOAD(0, 0);
;     __builtin_amdgcn_sched_barrier(0);
;     GLOAD(1, 1);
;     __builtin_amdgcn_sched_barrier(0);
;     LWRITE(0, 0);
;     __builtin_amdgcn_sched_barrier(0);
;     GLOAD(0, (2 < last ? 2 : last));
;     __builtin_amdgcn_sched_barrier(0);
;     __syncthreads();
;     for (int kt = 0; kt < nk; kt += 2) {
;       LWRITE(1, 1);
;       __builtin_amdgcn_sched_barrier(0);
;       GLOAD(1, (kt + 3 < last ? kt + 3 : last));
;       __builtin_amdgcn_sched_barrier(0);
;       COMPUTE(0);
;       __syncthreads();
;       LWRITE(0, 0);
;       __builtin_amdgcn_sched_barrier(0);
;       GLOAD(0, (kt + 4 < last ? kt + 4 : last));
;       __builtin_amdgcn_sched_barrier(0);
;       COMPUTE(1);
;       __syncthreads();
	v_add_u32_e32 v232, s31, v230
	v_add_u32_e32 v233, s31, v231
	s_setprio 1
	v_mfma_f32_16x16x32_bf16 v[0:3], v[128:131], v[144:147], v[0:3]
	v_mfma_f32_16x16x32_bf16 v[4:7], v[132:135], v[144:147], v[4:7]
	v_mfma_f32_16x16x32_bf16 v[8:11], v[136:139], v[144:147], v[8:11]
	v_mfma_f32_16x16x32_bf16 v[12:15], v[140:143], v[144:147], v[12:15]
	ds_read_b128 v[176:179], v233 offset:0
	ds_read_b128 v[180:183], v233 offset:1024
	v_mfma_f32_16x16x32_bf16 v[16:19], v[128:131], v[148:151], v[16:19]
	v_mfma_f32_16x16x32_bf16 v[20:23], v[132:135], v[148:151], v[20:23]
	v_mfma_f32_16x16x32_bf16 v[24:27], v[136:139], v[148:151], v[24:27]
	v_mfma_f32_16x16x32_bf16 v[28:31], v[140:143], v[148:151], v[28:31]
	ds_read_b128 v[184:187], v233 offset:2048
	ds_read_b128 v[188:191], v233 offset:3072
	v_mfma_f32_16x16x32_bf16 v[32:35], v[128:131], v[152:155], v[32:35]
	v_mfma_f32_16x16x32_bf16 v[36:39], v[132:135], v[152:155], v[36:39]
	v_mfma_f32_16x16x32_bf16 v[40:43], v[136:139], v[152:155], v[40:43]
	v_mfma_f32_16x16x32_bf16 v[44:47], v[140:143], v[152:155], v[44:47]
	ds_read_b128 v[192:195], v232 offset:0
	ds_read_b128 v[196:199], v232 offset:1024
	v_mfma_f32_16x16x32_bf16 v[48:51], v[128:131], v[156:159], v[48:51]
	v_mfma_f32_16x16x32_bf16 v[52:55], v[132:135], v[156:159], v[52:55]
	v_mfma_f32_16x16x32_bf16 v[56:59], v[136:139], v[156:159], v[56:59]
	v_mfma_f32_16x16x32_bf16 v[60:63], v[140:143], v[156:159], v[60:63]
	ds_read_b128 v[200:203], v232 offset:2048
	ds_read_b128 v[204:207], v232 offset:3072
	v_mfma_f32_16x16x32_bf16 v[64:67], v[128:131], v[160:163], v[64:67]
	v_mfma_f32_16x16x32_bf16 v[68:71], v[132:135], v[160:163], v[68:71]
	v_mfma_f32_16x16x32_bf16 v[72:75], v[136:139], v[160:163], v[72:75]
	v_mfma_f32_16x16x32_bf16 v[76:79], v[140:143], v[160:163], v[76:79]
	ds_read_b128 v[208:211], v232 offset:4096
	v_mfma_f32_16x16x32_bf16 v[80:83], v[128:131], v[164:167], v[80:83]
	v_mfma_f32_16x16x32_bf16 v[84:87], v[132:135], v[164:167], v[84:87]
	v_mfma_f32_16x16x32_bf16 v[88:91], v[136:139], v[164:167], v[88:91]
	v_mfma_f32_16x16x32_bf16 v[92:95], v[140:143], v[164:167], v[92:95]
	ds_read_b128 v[212:215], v232 offset:5120
	v_mfma_f32_16x16x32_bf16 v[96:99], v[128:131], v[168:171], v[96:99]
	v_mfma_f32_16x16x32_bf16 v[100:103], v[132:135], v[168:171], v[100:103]
	v_mfma_f32_16x16x32_bf16 v[104:107], v[136:139], v[168:171], v[104:107]
	v_mfma_f32_16x16x32_bf16 v[108:111], v[140:143], v[168:171], v[108:111]
	ds_read_b128 v[216:219], v232 offset:6144
	s_add_u32 s31, s31, 24576
	s_cmp_eq_u32 s31, 73728
	s_cselect_b32 s31, 0, s31
	v_mfma_f32_16x16x32_bf16 v[112:115], v[128:131], v[172:175], v[112:115]
	v_mfma_f32_16x16x32_bf16 v[116:119], v[132:135], v[172:175], v[116:119]
	v_mfma_f32_16x16x32_bf16 v[120:123], v[136:139], v[172:175], v[120:123]
	v_mfma_f32_16x16x32_bf16 v[124:127], v[140:143], v[172:175], v[124:127]
	ds_read_b128 v[220:223], v232 offset:7168
	s_setprio 0
	s_waitcnt lgkmcnt(0)
	s_barrier
	s_setprio 1
	v_mfma_f32_16x16x32_bf16 v[0:3], v[176:179], v[192:195], v[0:3]
	v_mfma_f32_16x16x32_bf16 v[4:7], v[180:183], v[192:195], v[4:7]
	v_mfma_f32_16x16x32_bf16 v[8:11], v[184:187], v[192:195], v[8:11]
	v_mfma_f32_16x16x32_bf16 v[12:15], v[188:191], v[192:195], v[12:15]
	v_mfma_f32_16x16x32_bf16 v[16:19], v[176:179], v[196:199], v[16:19]
	v_mfma_f32_16x16x32_bf16 v[20:23], v[180:183], v[196:199], v[20:23]
	v_mfma_f32_16x16x32_bf16 v[24:27], v[184:187], v[196:199], v[24:27]
	v_mfma_f32_16x16x32_bf16 v[28:31], v[188:191], v[196:199], v[28:31]
	v_mfma_f32_16x16x32_bf16 v[32:35], v[176:179], v[200:203], v[32:35]
	v_mfma_f32_16x16x32_bf16 v[36:39], v[180:183], v[200:203], v[36:39]
	v_mfma_f32_16x16x32_bf16 v[40:43], v[184:187], v[200:203], v[40:43]
	v_mfma_f32_16x16x32_bf16 v[44:47], v[188:191], v[200:203], v[44:47]
	v_mfma_f32_16x16x32_bf16 v[48:51], v[176:179], v[204:207], v[48:51]
	v_mfma_f32_16x16x32_bf16 v[52:55], v[180:183], v[204:207], v[52:55]
	v_mfma_f32_16x16x32_bf16 v[56:59], v[184:187], v[204:207], v[56:59]
	v_mfma_f32_16x16x32_bf16 v[60:63], v[188:191], v[204:207], v[60:63]
	v_mfma_f32_16x16x32_bf16 v[64:67], v[176:179], v[208:211], v[64:67]
	v_mfma_f32_16x16x32_bf16 v[68:71], v[180:183], v[208:211], v[68:71]
	v_mfma_f32_16x16x32_bf16 v[72:75], v[184:187], v[208:211], v[72:75]
	v_mfma_f32_16x16x32_bf16 v[76:79], v[188:191], v[208:211], v[76:79]
	v_mfma_f32_16x16x32_bf16 v[80:83], v[176:179], v[212:215], v[80:83]
	v_mfma_f32_16x16x32_bf16 v[84:87], v[180:183], v[212:215], v[84:87]
	v_mfma_f32_16x16x32_bf16 v[88:91], v[184:187], v[212:215], v[88:91]
	v_mfma_f32_16x16x32_bf16 v[92:95], v[188:191], v[212:215], v[92:95]
	v_mfma_f32_16x16x32_bf16 v[96:99], v[176:179], v[216:219], v[96:99]
	v_mfma_f32_16x16x32_bf16 v[100:103], v[180:183], v[216:219], v[100:103]
	v_mfma_f32_16x16x32_bf16 v[104:107], v[184:187], v[216:219], v[104:107]
	v_mfma_f32_16x16x32_bf16 v[108:111], v[188:191], v[216:219], v[108:111]
	v_mfma_f32_16x16x32_bf16 v[112:115], v[176:179], v[220:223], v[112:115]
	v_mfma_f32_16x16x32_bf16 v[116:119], v[180:183], v[220:223], v[116:119]
	v_mfma_f32_16x16x32_bf16 v[120:123], v[184:187], v[220:223], v[120:123]
	v_mfma_f32_16x16x32_bf16 v[124:127], v[188:191], v[220:223], v[124:127]
	s_setprio 0
	s_branch .Lg1_epi

; template <class Epi>
; DI void gemm_phase(char* smem, const bf16_t* A0, int lda0, int ksplit, const bf16_t* A1, int lda1, const bf16_t* Bt, int K, int nN, const Epi& epi, int tid) {
;   const int G = gridDim.x;
;   if ((G & 7) == 0) {
;     const int x = blockIdx.x & 7, l = blockIdx.x >> 3, L = G >> 3, per = 8 * nN, tot = 2 * per;
;     for (int q = l; q < tot; q += L) { const int rgl = q / per, rem = q % per, ct = rem >> 3, rt = (x * 2 + rgl) * 8 + (rem & 7);
;       gemm_tile(smem, A0, lda0, ksplit, A1, lda1, Bt, K, rt * 256, ct * 128, epi, tid); }
;   } else {
;     const int ntiles = (NTOK / 256) * nN;
;     for (int u = blockIdx.x; u < ntiles; u += G) { const int rt = u / nN, ct = u % nN; gemm_tile(smem, A0, lda0, ksplit, A1, lda1, Bt, K, rt * 256, ct * 128, epi, tid); }
;   }
; }
.Lg1_done:
	s_setprio 0
	v_mbcnt_lo_u32_b32 v194, -1, 0
	v_mbcnt_hi_u32_b32 v195, -1, v194

; #define LWRITE(S, buf) do { bf16_t* sA_ = sbase + (buf) * BUF; bf16_t* sB_ = sA_ + 256 * PITCH; \
;     _Pragma("unroll") for (int i_ = 0; i_ < 4; ++i_) *(u32x4*)(sA_ + (sr + i_ * 64) * PITCH + scv * 8) = ra[S][i_]; \
;     _Pragma("unroll") for (int i_ = 0; i_ < 2; ++i_) *(u32x4*)(sB_ + (sr + i_ * 64) * PITCH + scv * 8) = rb[S][i_]; } while (0)
; template <class Epi>
; DI void gemm_tile(char* smem, const bf16_t* __restrict__ A0, int lda0, int ksplit, const bf16_t* __restrict__ A1, int lda1,
;                   const bf16_t* __restrict__ Bt, int K, int row0, int col0, const Epi& epi, int tid) {
;   constexpr int BK = 32, PITCH = 40, BUF = (256 + 128) * PITCH;
;   bf16_t* sbase = (bf16_t*)smem;
;   const int lane = tid & 63, wid = tid >> 6, wr = wid >> 1, wc = wid & 1, fr = lane & 15, fq = lane >> 4;
;   f32x4 acc[8][4];
; #pragma unroll
;   for (int m = 0; m < 8; ++m)
; #pragma unroll
;     for (int n = 0; n < 4; ++n) acc[m][n] = (f32x4){0.f, 0.f, 0.f, 0.f};
;   u32x4 ra[2][4], rb[2][2];
;   const int nk = K / BK;
;   const int sr = tid >> 2, scv = tid & 3;
;     ...
;   __syncthreads();
;   {
;     const int last = nk - 1;
;     GLOAD(0, 0);
;     __builtin_amdgcn_sched_barrier(0);
;     GLOAD(1, 1);
;     __builtin_amdgcn_sched_barrier(0);
;     LWRITE(0, 0);
;     __builtin_amdgcn_sched_barrier(0);
;     GLOAD(0, (2 < last ? 2 : last));
;     __builtin_amdgcn_sched_barrier(0);
;     __syncthreads();
; template <class Epi>
; DI void gemm_phase(char* smem, const bf16_t* A0, int lda0, int ksplit, const bf16_t* A1, int lda1, const bf16_t* Bt, int K, int nN, const Epi& epi, int tid) {
;   const int G = gridDim.x;
;   if ((G & 7) == 0) {
;     const int x = blockIdx.x & 7, l = blockIdx.x >> 3, L = G >> 3, per = 8 * nN, tot = 2 * per;
;     for (int q = l; q < tot; q += L) { const int rgl = q / per, rem = q % per, ct = rem >> 3, rt = (x * 2 + rgl) * 8 + (rem & 7);
;       gemm_tile(smem, A0, lda0, ksplit, A1, lda1, Bt, K, rt * 256, ct * 128, epi, tid); }
; DI void phase_rw_small_gemms(const Ctx& c, char* smem) {
;     ...
;   gemm_phase(smem, sm, 256, 1 << 30, sm, 256, W2, 64, 4, EpiSmall{0, p.rw_w0, E0}, tid);
.LBB0_549:
	s_cmp_gt_i32 s94, 3
	s_cselect_b64 s[0:1], -1, 0
	s_cmp_lt_i32 s95, 4
	s_cselect_b64 s[2:3], -1, 0
	s_or_b64 s[0:1], s[0:1], s[2:3]
	s_and_b64 vcc, exec, s[0:1]
	s_cbranch_vccnz .LBB0_600
	s_and_b32 s14, s72, 0xffffffc0
	s_add_u32 s4, s92, 0x1ea00000
	s_load_dword s12, s[74:75], 0x180
	s_addc_u32 s5, s93, 0
	s_add_u32 s0, s92, 0x7800000
	s_addc_u32 s1, s93, 0
	s_add_u32 s6, s92, 0x34a0000
	s_addc_u32 s7, s93, 0
	s_waitcnt lgkmcnt(0)
	s_and_b32 s13, s12, 7
	s_cmp_lg_u32 s13, 0
	s_waitcnt vmcnt(7)
	v_mbcnt_hi_u32_b32 v136, -1, v194
	s_cselect_b64 s[2:3], -1, 0
	v_add_u32_e32 v137, s14, v136
	s_and_b64 vcc, exec, s[2:3]
	v_mbcnt_lo_u32_b32 v240, -1, 0
	v_mbcnt_hi_u32_b32 v240, -1, v240
	s_lshr_b32 s27, s72, 6
	s_lshl_b32 s100, s27, 10
	v_and_b32_e32 v241, 15, v240
	v_lshrrev_b32_e32 v242, 4, v240
	v_bfe_u32 v243, v240, 3, 1
	v_mul_u32_u24_e32 v243, 3, v243
	v_xor_b32_e32 v243, v242, v243
	v_lshlrev_b32_e32 v243, 4, v243
	v_lshl_add_u32 v243, v241, 6, v243
	s_lshr_b32 s26, s27, 1
	s_lshl_b32 s26, s26, 13
	v_add_u32_e32 v230, s26, v243
	s_and_b32 s26, s27, 1
	s_lshl_b32 s26, s26, 12
	s_add_u32 s26, s26, 16384
	v_add_u32_e32 v231, s26, v243
	s_lshr_b32 s26, s27, 1
	s_lshl_b32 s26, s26, 7
	v_add_u32_e32 v244, s26, v241
	s_and_b32 s26, s27, 1
	s_lshl_b32 s26, s26, 6
	v_lshl_add_u32 v245, v242, 2, s26
	v_lshlrev_b32_e32 v235, 2, v245
	s_mul_i32 s26, s27, 18432
	v_mul_u32_u24_e32 v246, 144, v241
	v_lshl_add_u32 v246, v242, 3, v246
	v_add_u32_e32 v236, s26, v246
	v_lshrrev_b32_e32 v246, 3, v240
	v_mul_u32_u24_e32 v246, 144, v246
	v_and_b32_e32 v247, 7, v240
	v_lshl_add_u32 v246, v247, 4, v246
	v_add_u32_e32 v237, s26, v246
	s_lshr_b32 s26, s27, 1
	s_lshl_b32 s26, s26, 7
	v_lshrrev_b32_e32 v246, 3, v240
	v_add_u32_e32 v246, s26, v246
	s_and_b32 s26, s27, 1
	s_lshl_b32 s26, s26, 6
	v_lshl_add_u32 v248, v247, 3, s26
	s_movk_i32 s26, 1024
	v_mul_lo_u32 v247, v246, s26
	v_lshl_add_u32 v238, v248, 1, v247
	v_lshrrev_b32_e32 v241, 2, v240
	s_lshl_b32 s26, s27, 4
	v_add_u32_e32 v241, s26, v241
	v_bfe_u32 v242, v240, 5, 1
	v_mul_u32_u24_e32 v242, 3, v242
	v_and_b32_e32 v243, 3, v240
	v_xor_b32_e32 v243, v243, v242
	v_lshlrev_b32_e32 v243, 4, v243
	s_mov_b32 s26, 512
	v_mad_u32_u24 v224, v241, s26, v243
	v_add_u32_e32 v225, 0x8000, v224
	v_add_u32_e32 v226, 0x10000, v224
	v_add_u32_e32 v227, 0x18000, v224
	s_mov_b32 s26, 128
	v_mad_u32_u24 v228, v241, s26, v243
	v_add_u32_e32 v229, 0x2000, v228
	s_load_dwordx2 s[6:7], s[74:75], 0x48
	s_cmpk_gt_u32 s96, 0xff
	s_cbranch_scc0 .Lg3a_prio
	s_setprio 1
.Lg3a_prio:
	s_lshr_b32 s15, s96, 3
	s_and_b32 s101, s96, 7
	s_lshl_b32 s101, s101, 1
	s_waitcnt lgkmcnt(0)
.Lg3a_tile:
	s_cmpk_ge_u32 s15, 64
	s_cbranch_scc1 .Lg3a_done
	s_cmpk_ge_u32 s15, 32
	s_cselect_b32 s27, 1, 0
	s_cselect_b32 s26, 32, 0
	s_sub_u32 s26, s15, s26
	s_add_u32 s27, s27, s101
	s_lshl_b32 s27, s27, 3
	s_and_b32 s29, s26, 7
	s_add_u32 s29, s29, s27
	s_lshl_b32 s29, s29, 8
	s_lshr_b32 s28, s26, 3
	s_lshl_b32 s28, s28, 7
	s_mul_i32 s27, s29, 512
	s_add_u32 s27, s27, 0x1ea00000
	s_add_u32 s0, s92, s27
	s_addc_u32 s1, s93, 0
	s_mul_i32 s27, s28, 128
	s_add_u32 s27, s27, 0x34a0000
	s_add_u32 s2, s92, s27
	s_addc_u32 s3, s93, 0
	s_waitcnt lgkmcnt(0)
	s_barrier
	s_mov_b32 s99, 0
	s_mov_b32 s30, 0
	s_add_u32 s26, s30, s100
	s_add_u32 m0, s26, 0
	s_nop 0
	global_load_lds_dwordx4 v224, s[0:1]
	s_add_u32 m0, s26, 4096
	s_nop 0
	global_load_lds_dwordx4 v225, s[0:1]
	s_add_u32 m0, s26, 8192
	s_nop 0
	global_load_lds_dwordx4 v226, s[0:1]
	s_add_u32 m0, s26, 12288
	s_nop 0
	global_load_lds_dwordx4 v227, s[0:1]
	s_add_u32 m0, s26, 16384
	s_nop 0
	global_load_lds_dwordx4 v228, s[2:3]
	s_add_u32 m0, s26, 20480
	s_nop 0
	global_load_lds_dwordx4 v229, s[2:3]
	s_add_u32 s0, s0, 64
	s_addc_u32 s1, s1, 0
	s_add_u32 s2, s2, 64
	s_addc_u32 s3, s3, 0
	s_add_u32 s99, s99, 1
	s_add_u32 s30, s30, 24576
	s_cmp_eq_u32 s30, 73728
	s_cselect_b32 s30, 0, s30
	s_add_u32 s26, s30, s100
	s_add_u32 m0, s26, 0
	s_nop 0
	global_load_lds_dwordx4 v224, s[0:1]
	s_add_u32 m0, s26, 4096
	s_nop 0
	global_load_lds_dwordx4 v225, s[0:1]
	s_add_u32 m0, s26, 8192
	s_nop 0
	global_load_lds_dwordx4 v226, s[0:1]
	s_add_u32 m0, s26, 12288
	s_nop 0
	global_load_lds_dwordx4 v227, s[0:1]
	s_add_u32 m0, s26, 16384
	s_nop 0
	global_load_lds_dwordx4 v228, s[2:3]
	s_add_u32 m0, s26, 20480
	s_nop 0
	global_load_lds_dwordx4 v229, s[2:3]
	s_add_u32 s0, s0, 64
	s_addc_u32 s1, s1, 0
	s_add_u32 s2, s2, 64
	s_addc_u32 s3, s3, 0
	s_add_u32 s99, s99, 1
	s_add_u32 s30, s30, 24576
	s_cmp_eq_u32 s30, 73728
	s_cselect_b32 s30, 0, s30
	v_mov_b32_e32 v0, 0
	v_mov_b32_e32 v1, 0
	v_mov_b32_e32 v2, 0
	v_mov_b32_e32 v3, 0
	v_mov_b32_e32 v4, 0
	v_mov_b32_e32 v5, 0
	v_mov_b32_e32 v6, 0
	v_mov_b32_e32 v7, 0
	v_mov_b32_e32 v8, 0
	v_mov_b32_e32 v9, 0
	v_mov_b32_e32 v10, 0
	v_mov_b32_e32 v11, 0
	v_mov_b32_e32 v12, 0
	v_mov_b32_e32 v13, 0
	v_mov_b32_e32 v14, 0
	v_mov_b32_e32 v15, 0
	v_mov_b32_e32 v16, 0
	v_mov_b32_e32 v17, 0
	v_mov_b32_e32 v18, 0
	v_mov_b32_e32 v19, 0
	v_mov_b32_e32 v20, 0
	v_mov_b32_e32 v21, 0
	v_mov_b32_e32 v22, 0
	v_mov_b32_e32 v23, 0
	v_mov_b32_e32 v24, 0
	v_mov_b32_e32 v25, 0
	v_mov_b32_e32 v26, 0
	v_mov_b32_e32 v27, 0
	v_mov_b32_e32 v28, 0
	v_mov_b32_e32 v29, 0
	v_mov_b32_e32 v30, 0
	v_mov_b32_e32 v31, 0
	v_mov_b32_e32 v32, 0
	v_mov_b32_e32 v33, 0
	v_mov_b32_e32 v34, 0
	v_mov_b32_e32 v35, 0
	v_mov_b32_e32 v36, 0
	v_mov_b32_e32 v37, 0
	v_mov_b32_e32 v38, 0
	v_mov_b32_e32 v39, 0
	v_mov_b32_e32 v40, 0
	v_mov_b32_e32 v41, 0
	v_mov_b32_e32 v42, 0
	v_mov_b32_e32 v43, 0
	v_mov_b32_e32 v44, 0
	v_mov_b32_e32 v45, 0
	v_mov_b32_e32 v46, 0
	v_mov_b32_e32 v47, 0
	v_mov_b32_e32 v48, 0
	v_mov_b32_e32 v49, 0
; #define LWRITE(S, buf) do { bf16_t* sA_ = sbase + (buf) * BUF; bf16_t* sB_ = sA_ + 256 * PITCH; \
;     _Pragma("unroll") for (int i_ = 0; i_ < 4; ++i_) *(u32x4*)(sA_ + (sr + i_ * 64) * PITCH + scv * 8) = ra[S][i_]; \
;     _Pragma("unroll") for (int i_ = 0; i_ < 2; ++i_) *(u32x4*)(sB_ + (sr + i_ * 64) * PITCH + scv * 8) = rb[S][i_]; } while (0)
; template <class Epi>
; DI void gemm_tile(char* smem, const bf16_t* __restrict__ A0, int lda0, int ksplit, const bf16_t* __restrict__ A1, int lda1,
;                   const bf16_t* __restrict__ Bt, int K, int row0, int col0, const Epi& epi, int tid) {
;     ...
;   for (int m = 0; m < 8; ++m)
; #pragma unroll
;     for (int n = 0; n < 4; ++n) acc[m][n] = (f32x4){0.f, 0.f, 0.f, 0.f};
;     ...
;   __syncthreads();
;   {
;     const int last = nk - 1;
;     GLOAD(0, 0);
;     __builtin_amdgcn_sched_barrier(0);
;     GLOAD(1, 1);
;     __builtin_amdgcn_sched_barrier(0);
;     LWRITE(0, 0);
;     __builtin_amdgcn_sched_barrier(0);
;     GLOAD(0, (2 < last ? 2 : last));
;     __builtin_amdgcn_sched_barrier(0);
;     __syncthreads();
	v_mov_b32_e32 v50, 0
	v_mov_b32_e32 v51, 0
	v_mov_b32_e32 v52, 0
	v_mov_b32_e32 v53, 0
	v_mov_b32_e32 v54, 0
	v_mov_b32_e32 v55, 0
	v_mov_b32_e32 v56, 0
	v_mov_b32_e32 v57, 0
	v_mov_b32_e32 v58, 0
	v_mov_b32_e32 v59, 0
	v_mov_b32_e32 v60, 0
	v_mov_b32_e32 v61, 0
	v_mov_b32_e32 v62, 0
	v_mov_b32_e32 v63, 0
	v_mov_b32_e32 v64, 0
	v_mov_b32_e32 v65, 0
	v_mov_b32_e32 v66, 0
	v_mov_b32_e32 v67, 0
	v_mov_b32_e32 v68, 0
	v_mov_b32_e32 v69, 0
	v_mov_b32_e32 v70, 0
	v_mov_b32_e32 v71, 0
	v_mov_b32_e32 v72, 0
	v_mov_b32_e32 v73, 0
	v_mov_b32_e32 v74, 0
	v_mov_b32_e32 v75, 0
	v_mov_b32_e32 v76, 0
	v_mov_b32_e32 v77, 0
	v_mov_b32_e32 v78, 0
	v_mov_b32_e32 v79, 0
	v_mov_b32_e32 v80, 0
	v_mov_b32_e32 v81, 0
	v_mov_b32_e32 v82, 0
	v_mov_b32_e32 v83, 0
	v_mov_b32_e32 v84, 0
	v_mov_b32_e32 v85, 0
	v_mov_b32_e32 v86, 0
	v_mov_b32_e32 v87, 0
	v_mov_b32_e32 v88, 0
	v_mov_b32_e32 v89, 0
	v_mov_b32_e32 v90, 0
	v_mov_b32_e32 v91, 0
	v_mov_b32_e32 v92, 0
	v_mov_b32_e32 v93, 0
	v_mov_b32_e32 v94, 0
	v_mov_b32_e32 v95, 0
	v_mov_b32_e32 v96, 0
	v_mov_b32_e32 v97, 0
	v_mov_b32_e32 v98, 0
	v_mov_b32_e32 v99, 0
	v_mov_b32_e32 v100, 0
	v_mov_b32_e32 v101, 0
	v_mov_b32_e32 v102, 0
	v_mov_b32_e32 v103, 0
	v_mov_b32_e32 v104, 0
	v_mov_b32_e32 v105, 0
	v_mov_b32_e32 v106, 0
	v_mov_b32_e32 v107, 0
	v_mov_b32_e32 v108, 0
	v_mov_b32_e32 v109, 0
	v_mov_b32_e32 v110, 0
	v_mov_b32_e32 v111, 0
	v_mov_b32_e32 v112, 0
	v_mov_b32_e32 v113, 0
	v_mov_b32_e32 v114, 0
	v_mov_b32_e32 v115, 0
	v_mov_b32_e32 v116, 0
	v_mov_b32_e32 v117, 0
	v_mov_b32_e32 v118, 0
	v_mov_b32_e32 v119, 0
	v_mov_b32_e32 v120, 0
	v_mov_b32_e32 v121, 0
	v_mov_b32_e32 v122, 0
	v_mov_b32_e32 v123, 0
	v_mov_b32_e32 v124, 0
	v_mov_b32_e32 v125, 0
	v_mov_b32_e32 v126, 0
	v_mov_b32_e32 v127, 0
	s_mov_b32 s98, 0
	s_mov_b32 s31, 24576
	s_waitcnt vmcnt(6)
	s_barrier
	ds_read_b128 v[128:131], v231 offset:0
	ds_read_b128 v[132:135], v231 offset:1024
	ds_read_b128 v[136:139], v231 offset:2048
	ds_read_b128 v[140:143], v231 offset:3072
	ds_read_b128 v[144:147], v230 offset:0
	ds_read_b128 v[148:151], v230 offset:1024
	ds_read_b128 v[152:155], v230 offset:2048
	ds_read_b128 v[156:159], v230 offset:3072
	ds_read_b128 v[160:163], v230 offset:4096
	ds_read_b128 v[164:167], v230 offset:5120
	ds_read_b128 v[168:171], v230 offset:6144
	ds_read_b128 v[172:175], v230 offset:7168
	s_waitcnt vmcnt(0)
	s_waitcnt lgkmcnt(0)
	s_barrier
	v_add_u32_e32 v232, s31, v230
	v_add_u32_e32 v233, s31, v231
	s_setprio 1
	v_mfma_f32_16x16x32_bf16 v[0:3], v[128:131], v[144:147], v[0:3]
	v_mfma_f32_16x16x32_bf16 v[4:7], v[132:135], v[144:147], v[4:7]
	v_mfma_f32_16x16x32_bf16 v[8:11], v[136:139], v[144:147], v[8:11]
	v_mfma_f32_16x16x32_bf16 v[12:15], v[140:143], v[144:147], v[12:15]
	ds_read_b128 v[176:179], v233 offset:0
	ds_read_b128 v[180:183], v233 offset:1024
	v_mfma_f32_16x16x32_bf16 v[16:19], v[128:131], v[148:151], v[16:19]
	v_mfma_f32_16x16x32_bf16 v[20:23], v[132:135], v[148:151], v[20:23]
	v_mfma_f32_16x16x32_bf16 v[24:27], v[136:139], v[148:151], v[24:27]
	v_mfma_f32_16x16x32_bf16 v[28:31], v[140:143], v[148:151], v[28:31]
	ds_read_b128 v[184:187], v233 offset:2048
	ds_read_b128 v[188:191], v233 offset:3072
	v_mfma_f32_16x16x32_bf16 v[32:35], v[128:131], v[152:155], v[32:35]
	v_mfma_f32_16x16x32_bf16 v[36:39], v[132:135], v[152:155], v[36:39]
	v_mfma_f32_16x16x32_bf16 v[40:43], v[136:139], v[152:155], v[40:43]
	v_mfma_f32_16x16x32_bf16 v[44:47], v[140:143], v[152:155], v[44:47]
	ds_read_b128 v[192:195], v232 offset:0
	ds_read_b128 v[196:199], v232 offset:1024
	v_mfma_f32_16x16x32_bf16 v[48:51], v[128:131], v[156:159], v[48:51]
	v_mfma_f32_16x16x32_bf16 v[52:55], v[132:135], v[156:159], v[52:55]
	v_mfma_f32_16x16x32_bf16 v[56:59], v[136:139], v[156:159], v[56:59]
	v_mfma_f32_16x16x32_bf16 v[60:63], v[140:143], v[156:159], v[60:63]
	ds_read_b128 v[200:203], v232 offset:2048
	ds_read_b128 v[204:207], v232 offset:3072
	v_mfma_f32_16x16x32_bf16 v[64:67], v[128:131], v[160:163], v[64:67]
	v_mfma_f32_16x16x32_bf16 v[68:71], v[132:135], v[160:163], v[68:71]
	v_mfma_f32_16x16x32_bf16 v[72:75], v[136:139], v[160:163], v[72:75]
	v_mfma_f32_16x16x32_bf16 v[76:79], v[140:143], v[160:163], v[76:79]
	ds_read_b128 v[208:211], v232 offset:4096
	v_mfma_f32_16x16x32_bf16 v[80:83], v[128:131], v[164:167], v[80:83]
	v_mfma_f32_16x16x32_bf16 v[84:87], v[132:135], v[164:167], v[84:87]
	v_mfma_f32_16x16x32_bf16 v[88:91], v[136:139], v[164:167], v[88:91]
	v_mfma_f32_16x16x32_bf16 v[92:95], v[140:143], v[164:167], v[92:95]
	ds_read_b128 v[212:215], v232 offset:5120
	v_mfma_f32_16x16x32_bf16 v[96:99], v[128:131], v[168:171], v[96:99]
	v_mfma_f32_16x16x32_bf16 v[100:103], v[132:135], v[168:171], v[100:103]
	v_mfma_f32_16x16x32_bf16 v[104:107], v[136:139], v[168:171], v[104:107]
	v_mfma_f32_16x16x32_bf16 v[108:111], v[140:143], v[168:171], v[108:111]
	ds_read_b128 v[216:219], v232 offset:6144
	s_add_u32 s31, s31, 24576
	s_cmp_eq_u32 s31, 73728
	s_cselect_b32 s31, 0, s31
	v_mfma_f32_16x16x32_bf16 v[112:115], v[128:131], v[172:175], v[112:115]
	v_mfma_f32_16x16x32_bf16 v[116:119], v[132:135], v[172:175], v[116:119]
	v_mfma_f32_16x16x32_bf16 v[120:123], v[136:139], v[172:175], v[120:123]
	v_mfma_f32_16x16x32_bf16 v[124:127], v[140:143], v[172:175], v[124:127]
	ds_read_b128 v[220:223], v232 offset:7168
	s_setprio 0
	s_waitcnt lgkmcnt(0)
	s_barrier
	s_setprio 1
	v_mfma_f32_16x16x32_bf16 v[0:3], v[176:179], v[192:195], v[0:3]
	v_mfma_f32_16x16x32_bf16 v[4:7], v[180:183], v[192:195], v[4:7]
	v_mfma_f32_16x16x32_bf16 v[8:11], v[184:187], v[192:195], v[8:11]
	v_mfma_f32_16x16x32_bf16 v[12:15], v[188:191], v[192:195], v[12:15]
	v_mfma_f32_16x16x32_bf16 v[16:19], v[176:179], v[196:199], v[16:19]
	v_mfma_f32_16x16x32_bf16 v[20:23], v[180:183], v[196:199], v[20:23]
	v_mfma_f32_16x16x32_bf16 v[24:27], v[184:187], v[196:199], v[24:27]
	v_mfma_f32_16x16x32_bf16 v[28:31], v[188:191], v[196:199], v[28:31]
	v_mfma_f32_16x16x32_bf16 v[32:35], v[176:179], v[200:203], v[32:35]
	v_mfma_f32_16x16x32_bf16 v[36:39], v[180:183], v[200:203], v[36:39]
	v_mfma_f32_16x16x32_bf16 v[40:43], v[184:187], v[200:203], v[40:43]
	v_mfma_f32_16x16x32_bf16 v[44:47], v[188:191], v[200:203], v[44:47]
	v_mfma_f32_16x16x32_bf16 v[48:51], v[176:179], v[204:207], v[48:51]
	v_mfma_f32_16x16x32_bf16 v[52:55], v[180:183], v[204:207], v[52:55]
	v_mfma_f32_16x16x32_bf16 v[56:59], v[184:187], v[204:207], v[56:59]
	v_mfma_f32_16x16x32_bf16 v[60:63], v[188:191], v[204:207], v[60:63]
	v_mfma_f32_16x16x32_bf16 v[64:67], v[176:179], v[208:211], v[64:67]
	v_mfma_f32_16x16x32_bf16 v[68:71], v[180:183], v[208:211], v[68:71]
	v_mfma_f32_16x16x32_bf16 v[72:75], v[184:187], v[208:211], v[72:75]
	v_mfma_f32_16x16x32_bf16 v[76:79], v[188:191], v[208:211], v[76:79]
	v_mfma_f32_16x16x32_bf16 v[80:83], v[176:179], v[212:215], v[80:83]
	v_mfma_f32_16x16x32_bf16 v[84:87], v[180:183], v[212:215], v[84:87]
	v_mfma_f32_16x16x32_bf16 v[88:91], v[184:187], v[212:215], v[88:91]
	v_mfma_f32_16x16x32_bf16 v[92:95], v[188:191], v[212:215], v[92:95]
	v_mfma_f32_16x16x32_bf16 v[96:99], v[176:179], v[216:219], v[96:99]
	v_mfma_f32_16x16x32_bf16 v[100:103], v[180:183], v[216:219], v[100:103]
	v_mfma_f32_16x16x32_bf16 v[104:107], v[184:187], v[216:219], v[104:107]
	v_mfma_f32_16x16x32_bf16 v[108:111], v[188:191], v[216:219], v[108:111]
	v_mfma_f32_16x16x32_bf16 v[112:115], v[176:179], v[220:223], v[112:115]
	v_mfma_f32_16x16x32_bf16 v[116:119], v[180:183], v[220:223], v[116:119]
	v_mfma_f32_16x16x32_bf16 v[120:123], v[184:187], v[220:223], v[120:123]
	v_mfma_f32_16x16x32_bf16 v[124:127], v[188:191], v[220:223], v[124:127]
	s_setprio 0
	s_branch .Lg3a_epi

; template <class Epi>
; DI void gemm_phase(char* smem, const bf16_t* A0, int lda0, int ksplit, const bf16_t* A1, int lda1, const bf16_t* Bt, int K, int nN, const Epi& epi, int tid) {
;   const int G = gridDim.x;
;   if ((G & 7) == 0) {
;     const int x = blockIdx.x & 7, l = blockIdx.x >> 3, L = G >> 3, per = 8 * nN, tot = 2 * per;
;     for (int q = l; q < tot; q += L) { const int rgl = q / per, rem = q % per, ct = rem >> 3, rt = (x * 2 + rgl) * 8 + (rem & 7);
;       gemm_tile(smem, A0, lda0, ksplit, A1, lda1, Bt, K, rt * 256, ct * 128, epi, tid); }
; DI void phase_rw_small_gemms(const Ctx& c, char* smem) {
;     ...
;   gemm_phase(smem, sm, 256, 1 << 30, sm, 256, W2, 64, 4, EpiSmall{0, p.rw_w0, E0}, tid);
;   gemm_phase(smem, sm, 256, 1 << 30, sm, 256, W2 + 512 * 64, 64, 4, EpiSmall{0, p.rw_w0 + 512, E1}, tid);
.Lg3a_done:
	s_setprio 0
	v_mbcnt_lo_u32_b32 v194, -1, 0
	v_mbcnt_hi_u32_b32 v136, -1, v194
	v_mbcnt_lo_u32_b32 v240, -1, 0
	v_mbcnt_hi_u32_b32 v240, -1, v240
	s_lshr_b32 s27, s72, 6
	s_lshl_b32 s100, s27, 10
	v_and_b32_e32 v241, 15, v240
	v_lshrrev_b32_e32 v242, 4, v240
	v_bfe_u32 v243, v240, 3, 1
	v_mul_u32_u24_e32 v243, 3, v243
	v_xor_b32_e32 v243, v242, v243
	v_lshlrev_b32_e32 v243, 4, v243
	v_lshl_add_u32 v243, v241, 6, v243
	s_lshr_b32 s26, s27, 1
	s_lshl_b32 s26, s26, 13
	v_add_u32_e32 v230, s26, v243
	s_and_b32 s26, s27, 1
	s_lshl_b32 s26, s26, 12
	s_add_u32 s26, s26, 16384
	v_add_u32_e32 v231, s26, v243
	s_lshr_b32 s26, s27, 1
	s_lshl_b32 s26, s26, 7
	v_add_u32_e32 v244, s26, v241
	s_and_b32 s26, s27, 1
	s_lshl_b32 s26, s26, 6
	v_lshl_add_u32 v245, v242, 2, s26
	v_lshlrev_b32_e32 v235, 2, v245
	s_mul_i32 s26, s27, 18432
	v_mul_u32_u24_e32 v246, 144, v241
	v_lshl_add_u32 v246, v242, 3, v246
	v_add_u32_e32 v236, s26, v246
	v_lshrrev_b32_e32 v246, 3, v240
	v_mul_u32_u24_e32 v246, 144, v246
	v_and_b32_e32 v247, 7, v240
	v_lshl_add_u32 v246, v247, 4, v246
	v_add_u32_e32 v237, s26, v246
	s_lshr_b32 s26, s27, 1
	s_lshl_b32 s26, s26, 7
	v_lshrrev_b32_e32 v246, 3, v240
	v_add_u32_e32 v246, s26, v246
	s_and_b32 s26, s27, 1
	s_lshl_b32 s26, s26, 6
	v_lshl_add_u32 v248, v247, 3, s26
	s_movk_i32 s26, 1024
	v_mul_lo_u32 v247, v246, s26
	v_lshl_add_u32 v238, v248, 1, v247
	v_lshrrev_b32_e32 v241, 2, v240
	s_lshl_b32 s26, s27, 4
	v_add_u32_e32 v241, s26, v241
	v_bfe_u32 v242, v240, 5, 1
	v_mul_u32_u24_e32 v242, 3, v242
	v_and_b32_e32 v243, 3, v240
	v_xor_b32_e32 v243, v243, v242
	v_lshlrev_b32_e32 v243, 4, v243
	s_mov_b32 s26, 512
	v_mad_u32_u24 v224, v241, s26, v243
	v_add_u32_e32 v225, 0x8000, v224
	v_add_u32_e32 v226, 0x10000, v224
	v_add_u32_e32 v227, 0x18000, v224
	s_mov_b32 s26, 128
	v_mad_u32_u24 v228, v241, s26, v243
	v_add_u32_e32 v229, 0x2000, v228
	s_load_dwordx2 s[6:7], s[74:75], 0x48
	s_cmpk_gt_u32 s96, 0xff
	s_cbranch_scc0 .Lg3b_prio
	s_setprio 1

; #define LWRITE(S, buf) do { bf16_t* sA_ = sbase + (buf) * BUF; bf16_t* sB_ = sA_ + 256 * PITCH; \
;     _Pragma("unroll") for (int i_ = 0; i_ < 4; ++i_) *(u32x4*)(sA_ + (sr + i_ * 64) * PITCH + scv * 8) = ra[S][i_]; \
;     _Pragma("unroll") for (int i_ = 0; i_ < 2; ++i_) *(u32x4*)(sB_ + (sr + i_ * 64) * PITCH + scv * 8) = rb[S][i_]; } while (0)
; template <class Epi>
; DI void gemm_tile(char* smem, const bf16_t* __restrict__ A0, int lda0, int ksplit, const bf16_t* __restrict__ A1, int lda1,
;                   const bf16_t* __restrict__ Bt, int K, int row0, int col0, const Epi& epi, int tid) {
;     ...
;   __syncthreads();
;   {
;     const int last = nk - 1;
;     GLOAD(0, 0);
;     __builtin_amdgcn_sched_barrier(0);
;     GLOAD(1, 1);
;     __builtin_amdgcn_sched_barrier(0);
;     LWRITE(0, 0);
;     __builtin_amdgcn_sched_barrier(0);
;     GLOAD(0, (2 < last ? 2 : last));
;     __builtin_amdgcn_sched_barrier(0);
;     __syncthreads();
; template <class Epi>
; DI void gemm_phase(char* smem, const bf16_t* A0, int lda0, int ksplit, const bf16_t* A1, int lda1, const bf16_t* Bt, int K, int nN, const Epi& epi, int tid) {
;     ...
;     for (int q = l; q < tot; q += L) { const int rgl = q / per, rem = q % per, ct = rem >> 3, rt = (x * 2 + rgl) * 8 + (rem & 7);
;       gemm_tile(smem, A0, lda0, ksplit, A1, lda1, Bt, K, rt * 256, ct * 128, epi, tid); }
.Lg3b_tile:
	s_cmpk_ge_u32 s15, 64
	s_cbranch_scc1 .Lg3b_done
	s_cmpk_ge_u32 s15, 32
	s_cselect_b32 s27, 1, 0
	s_cselect_b32 s26, 32, 0
	s_sub_u32 s26, s15, s26
	s_add_u32 s27, s27, s101
	s_lshl_b32 s27, s27, 3
	s_and_b32 s29, s26, 7
	s_add_u32 s29, s29, s27
	s_lshl_b32 s29, s29, 8
	s_lshr_b32 s28, s26, 3
	s_lshl_b32 s28, s28, 7
	s_mul_i32 s27, s29, 512
	s_add_u32 s27, s27, 0x1ea00000
	s_add_u32 s0, s92, s27
	s_addc_u32 s1, s93, 0
	s_mul_i32 s27, s28, 128
	s_add_u32 s27, s27, 0x34b0000
	s_add_u32 s2, s92, s27
	s_addc_u32 s3, s93, 0
	s_waitcnt lgkmcnt(0)
	s_barrier
	s_mov_b32 s99, 0
	s_mov_b32 s30, 0
	s_add_u32 s26, s30, s100
	s_add_u32 m0, s26, 0
	s_nop 0
	global_load_lds_dwordx4 v224, s[0:1]
	s_add_u32 m0, s26, 4096
	s_nop 0
	global_load_lds_dwordx4 v225, s[0:1]
	s_add_u32 m0, s26, 8192
	s_nop 0
	global_load_lds_dwordx4 v226, s[0:1]
	s_add_u32 m0, s26, 12288
	s_nop 0
	global_load_lds_dwordx4 v227, s[0:1]
	s_add_u32 m0, s26, 16384
	s_nop 0
	global_load_lds_dwordx4 v228, s[2:3]
	s_add_u32 m0, s26, 20480
	s_nop 0
	global_load_lds_dwordx4 v229, s[2:3]
	s_add_u32 s0, s0, 64
	s_addc_u32 s1, s1, 0
	s_add_u32 s2, s2, 64
	s_addc_u32 s3, s3, 0
	s_add_u32 s99, s99, 1
	s_add_u32 s30, s30, 24576
	s_cmp_eq_u32 s30, 73728
	s_cselect_b32 s30, 0, s30
	s_add_u32 s26, s30, s100
	s_add_u32 m0, s26, 0
	s_nop 0
	global_load_lds_dwordx4 v224, s[0:1]
	s_add_u32 m0, s26, 4096
	s_nop 0
	global_load_lds_dwordx4 v225, s[0:1]
	s_add_u32 m0, s26, 8192
	s_nop 0
	global_load_lds_dwordx4 v226, s[0:1]
	s_add_u32 m0, s26, 12288
	s_nop 0
	global_load_lds_dwordx4 v227, s[0:1]
	s_add_u32 m0, s26, 16384
	s_nop 0
	global_load_lds_dwordx4 v228, s[2:3]
	s_add_u32 m0, s26, 20480
	s_nop 0
	global_load_lds_dwordx4 v229, s[2:3]
	s_add_u32 s0, s0, 64
	s_addc_u32 s1, s1, 0
	s_add_u32 s2, s2, 64
	s_addc_u32 s3, s3, 0
	s_add_u32 s99, s99, 1
	s_add_u32 s30, s30, 24576
	s_cmp_eq_u32 s30, 73728
	s_cselect_b32 s30, 0, s30
	v_mov_b32_e32 v0, 0
	v_mov_b32_e32 v1, 0
	v_mov_b32_e32 v2, 0
	v_mov_b32_e32 v3, 0
	v_mov_b32_e32 v4, 0
	v_mov_b32_e32 v5, 0
	v_mov_b32_e32 v6, 0
	v_mov_b32_e32 v7, 0
	v_mov_b32_e32 v8, 0
	v_mov_b32_e32 v9, 0
	v_mov_b32_e32 v10, 0
	v_mov_b32_e32 v11, 0
	v_mov_b32_e32 v12, 0
	v_mov_b32_e32 v13, 0
	v_mov_b32_e32 v14, 0
	v_mov_b32_e32 v15, 0
	v_mov_b32_e32 v16, 0
	v_mov_b32_e32 v17, 0
	v_mov_b32_e32 v18, 0
	v_mov_b32_e32 v19, 0
	v_mov_b32_e32 v20, 0
	v_mov_b32_e32 v21, 0
	v_mov_b32_e32 v22, 0
	v_mov_b32_e32 v23, 0
	v_mov_b32_e32 v24, 0
	v_mov_b32_e32 v25, 0
	v_mov_b32_e32 v26, 0
	v_mov_b32_e32 v27, 0
	v_mov_b32_e32 v28, 0
	v_mov_b32_e32 v29, 0
	v_mov_b32_e32 v30, 0
	v_mov_b32_e32 v31, 0
	v_mov_b32_e32 v32, 0
	v_mov_b32_e32 v33, 0
	v_mov_b32_e32 v34, 0
	v_mov_b32_e32 v35, 0
	v_mov_b32_e32 v36, 0
	v_mov_b32_e32 v37, 0
	v_mov_b32_e32 v38, 0
	v_mov_b32_e32 v39, 0
	v_mov_b32_e32 v40, 0
	v_mov_b32_e32 v41, 0
	v_mov_b32_e32 v42, 0
	v_mov_b32_e32 v43, 0
	v_mov_b32_e32 v44, 0
	v_mov_b32_e32 v45, 0
	v_mov_b32_e32 v46, 0
	v_mov_b32_e32 v47, 0
	v_mov_b32_e32 v48, 0
	v_mov_b32_e32 v49, 0
	v_mov_b32_e32 v50, 0
	v_mov_b32_e32 v51, 0
	v_mov_b32_e32 v52, 0
	v_mov_b32_e32 v53, 0
	v_mov_b32_e32 v54, 0
	v_mov_b32_e32 v55, 0
	v_mov_b32_e32 v56, 0
	v_mov_b32_e32 v57, 0
	v_mov_b32_e32 v58, 0
	v_mov_b32_e32 v59, 0
	v_mov_b32_e32 v60, 0
	v_mov_b32_e32 v61, 0
	v_mov_b32_e32 v62, 0
	v_mov_b32_e32 v63, 0
	v_mov_b32_e32 v64, 0
	v_mov_b32_e32 v65, 0
	v_mov_b32_e32 v66, 0
	v_mov_b32_e32 v67, 0
	v_mov_b32_e32 v68, 0
	v_mov_b32_e32 v69, 0
	v_mov_b32_e32 v70, 0
	v_mov_b32_e32 v71, 0
	v_mov_b32_e32 v72, 0
	v_mov_b32_e32 v73, 0
	v_mov_b32_e32 v74, 0
	v_mov_b32_e32 v75, 0
	v_mov_b32_e32 v76, 0
	v_mov_b32_e32 v77, 0
	v_mov_b32_e32 v78, 0
	v_mov_b32_e32 v79, 0
	v_mov_b32_e32 v80, 0
	v_mov_b32_e32 v81, 0
	v_mov_b32_e32 v82, 0
	v_mov_b32_e32 v83, 0
	v_mov_b32_e32 v84, 0
	v_mov_b32_e32 v85, 0
	v_mov_b32_e32 v86, 0
	v_mov_b32_e32 v87, 0
	v_mov_b32_e32 v88, 0
	v_mov_b32_e32 v89, 0
	v_mov_b32_e32 v90, 0
	v_mov_b32_e32 v91, 0
	v_mov_b32_e32 v92, 0
	v_mov_b32_e32 v93, 0
	v_mov_b32_e32 v94, 0
	v_mov_b32_e32 v95, 0
	v_mov_b32_e32 v96, 0
	v_mov_b32_e32 v97, 0
	v_mov_b32_e32 v98, 0
	v_mov_b32_e32 v99, 0
	v_mov_b32_e32 v100, 0
	v_mov_b32_e32 v101, 0
	v_mov_b32_e32 v102, 0
	v_mov_b32_e32 v103, 0
	v_mov_b32_e32 v104, 0
	v_mov_b32_e32 v105, 0
	v_mov_b32_e32 v106, 0
	v_mov_b32_e32 v107, 0
	v_mov_b32_e32 v108, 0
	v_mov_b32_e32 v109, 0
	v_mov_b32_e32 v110, 0
	v_mov_b32_e32 v111, 0
	v_mov_b32_e32 v112, 0
	v_mov_b32_e32 v113, 0
	v_mov_b32_e32 v114, 0
	v_mov_b32_e32 v115, 0
	v_mov_b32_e32 v116, 0
	v_mov_b32_e32 v117, 0
	v_mov_b32_e32 v118, 0
	v_mov_b32_e32 v119, 0
	v_mov_b32_e32 v120, 0
	v_mov_b32_e32 v121, 0
	v_mov_b32_e32 v122, 0
	v_mov_b32_e32 v123, 0
	v_mov_b32_e32 v124, 0
	v_mov_b32_e32 v125, 0
	v_mov_b32_e32 v126, 0
	v_mov_b32_e32 v127, 0
	s_mov_b32 s98, 0
	s_mov_b32 s31, 24576
	s_waitcnt vmcnt(6)
	s_barrier
	ds_read_b128 v[128:131], v231 offset:0
	ds_read_b128 v[132:135], v231 offset:1024
	ds_read_b128 v[136:139], v231 offset:2048
	ds_read_b128 v[140:143], v231 offset:3072
	ds_read_b128 v[144:147], v230 offset:0
	ds_read_b128 v[148:151], v230 offset:1024
	ds_read_b128 v[152:155], v230 offset:2048
	ds_read_b128 v[156:159], v230 offset:3072
	ds_read_b128 v[160:163], v230 offset:4096
	ds_read_b128 v[164:167], v230 offset:5120
	ds_read_b128 v[168:171], v230 offset:6144
	ds_read_b128 v[172:175], v230 offset:7168
	s_waitcnt vmcnt(0)
	s_waitcnt lgkmcnt(0)
	s_barrier
	v_add_u32_e32 v232, s31, v230
	v_add_u32_e32 v233, s31, v231
	s_setprio 1
	v_mfma_f32_16x16x32_bf16 v[0:3], v[128:131], v[144:147], v[0:3]
	v_mfma_f32_16x16x32_bf16 v[4:7], v[132:135], v[144:147], v[4:7]
	v_mfma_f32_16x16x32_bf16 v[8:11], v[136:139], v[144:147], v[8:11]
	v_mfma_f32_16x16x32_bf16 v[12:15], v[140:143], v[144:147], v[12:15]
	ds_read_b128 v[176:179], v233 offset:0
	ds_read_b128 v[180:183], v233 offset:1024
	v_mfma_f32_16x16x32_bf16 v[16:19], v[128:131], v[148:151], v[16:19]
	v_mfma_f32_16x16x32_bf16 v[20:23], v[132:135], v[148:151], v[20:23]
	v_mfma_f32_16x16x32_bf16 v[24:27], v[136:139], v[148:151], v[24:27]
	v_mfma_f32_16x16x32_bf16 v[28:31], v[140:143], v[148:151], v[28:31]
	ds_read_b128 v[184:187], v233 offset:2048
	ds_read_b128 v[188:191], v233 offset:3072
	v_mfma_f32_16x16x32_bf16 v[32:35], v[128:131], v[152:155], v[32:35]
	v_mfma_f32_16x16x32_bf16 v[36:39], v[132:135], v[152:155], v[36:39]
	v_mfma_f32_16x16x32_bf16 v[40:43], v[136:139], v[152:155], v[40:43]
	v_mfma_f32_16x16x32_bf16 v[44:47], v[140:143], v[152:155], v[44:47]
	ds_read_b128 v[192:195], v232 offset:0
	ds_read_b128 v[196:199], v232 offset:1024
	v_mfma_f32_16x16x32_bf16 v[48:51], v[128:131], v[156:159], v[48:51]
	v_mfma_f32_16x16x32_bf16 v[52:55], v[132:135], v[156:159], v[52:55]
	v_mfma_f32_16x16x32_bf16 v[56:59], v[136:139], v[156:159], v[56:59]
	v_mfma_f32_16x16x32_bf16 v[60:63], v[140:143], v[156:159], v[60:63]
	ds_read_b128 v[200:203], v232 offset:2048
	ds_read_b128 v[204:207], v232 offset:3072
	v_mfma_f32_16x16x32_bf16 v[64:67], v[128:131], v[160:163], v[64:67]
	v_mfma_f32_16x16x32_bf16 v[68:71], v[132:135], v[160:163], v[68:71]
	v_mfma_f32_16x16x32_bf16 v[72:75], v[136:139], v[160:163], v[72:75]
	v_mfma_f32_16x16x32_bf16 v[76:79], v[140:143], v[160:163], v[76:79]
	ds_read_b128 v[208:211], v232 offset:4096
	v_mfma_f32_16x16x32_bf16 v[80:83], v[128:131], v[164:167], v[80:83]
	v_mfma_f32_16x16x32_bf16 v[84:87], v[132:135], v[164:167], v[84:87]
	v_mfma_f32_16x16x32_bf16 v[88:91], v[136:139], v[164:167], v[88:91]
	v_mfma_f32_16x16x32_bf16 v[92:95], v[140:143], v[164:167], v[92:95]
	ds_read_b128 v[212:215], v232 offset:5120
	v_mfma_f32_16x16x32_bf16 v[96:99], v[128:131], v[168:171], v[96:99]
	v_mfma_f32_16x16x32_bf16 v[100:103], v[132:135], v[168:171], v[100:103]
	v_mfma_f32_16x16x32_bf16 v[104:107], v[136:139], v[168:171], v[104:107]
	v_mfma_f32_16x16x32_bf16 v[108:111], v[140:143], v[168:171], v[108:111]
	ds_read_b128 v[216:219], v232 offset:6144
	s_add_u32 s31, s31, 24576
	s_cmp_eq_u32 s31, 73728
	s_cselect_b32 s31, 0, s31
	v_mfma_f32_16x16x32_bf16 v[112:115], v[128:131], v[172:175], v[112:115]
	v_mfma_f32_16x16x32_bf16 v[116:119], v[132:135], v[172:175], v[116:119]
	v_mfma_f32_16x16x32_bf16 v[120:123], v[136:139], v[172:175], v[120:123]
	v_mfma_f32_16x16x32_bf16 v[124:127], v[140:143], v[172:175], v[124:127]
	ds_read_b128 v[220:223], v232 offset:7168
	s_setprio 0
	s_waitcnt lgkmcnt(0)
	s_barrier
	s_setprio 1
	v_mfma_f32_16x16x32_bf16 v[0:3], v[176:179], v[192:195], v[0:3]
	v_mfma_f32_16x16x32_bf16 v[4:7], v[180:183], v[192:195], v[4:7]
	v_mfma_f32_16x16x32_bf16 v[8:11], v[184:187], v[192:195], v[8:11]
	v_mfma_f32_16x16x32_bf16 v[12:15], v[188:191], v[192:195], v[12:15]
	v_mfma_f32_16x16x32_bf16 v[16:19], v[176:179], v[196:199], v[16:19]
	v_mfma_f32_16x16x32_bf16 v[20:23], v[180:183], v[196:199], v[20:23]
	v_mfma_f32_16x16x32_bf16 v[24:27], v[184:187], v[196:199], v[24:27]
	v_mfma_f32_16x16x32_bf16 v[28:31], v[188:191], v[196:199], v[28:31]
	v_mfma_f32_16x16x32_bf16 v[32:35], v[176:179], v[200:203], v[32:35]
	v_mfma_f32_16x16x32_bf16 v[36:39], v[180:183], v[200:203], v[36:39]
	v_mfma_f32_16x16x32_bf16 v[40:43], v[184:187], v[200:203], v[40:43]
	v_mfma_f32_16x16x32_bf16 v[44:47], v[188:191], v[200:203], v[44:47]
	v_mfma_f32_16x16x32_bf16 v[48:51], v[176:179], v[204:207], v[48:51]
	v_mfma_f32_16x16x32_bf16 v[52:55], v[180:183], v[204:207], v[52:55]
	v_mfma_f32_16x16x32_bf16 v[56:59], v[184:187], v[204:207], v[56:59]
	v_mfma_f32_16x16x32_bf16 v[60:63], v[188:191], v[204:207], v[60:63]
	v_mfma_f32_16x16x32_bf16 v[64:67], v[176:179], v[208:211], v[64:67]
	v_mfma_f32_16x16x32_bf16 v[68:71], v[180:183], v[208:211], v[68:71]
	v_mfma_f32_16x16x32_bf16 v[72:75], v[184:187], v[208:211], v[72:75]
	v_mfma_f32_16x16x32_bf16 v[76:79], v[188:191], v[208:211], v[76:79]
	v_mfma_f32_16x16x32_bf16 v[80:83], v[176:179], v[212:215], v[80:83]
	v_mfma_f32_16x16x32_bf16 v[84:87], v[180:183], v[212:215], v[84:87]
	v_mfma_f32_16x16x32_bf16 v[88:91], v[184:187], v[212:215], v[88:91]
	v_mfma_f32_16x16x32_bf16 v[92:95], v[188:191], v[212:215], v[92:95]
	v_mfma_f32_16x16x32_bf16 v[96:99], v[176:179], v[216:219], v[96:99]
	v_mfma_f32_16x16x32_bf16 v[100:103], v[180:183], v[216:219], v[100:103]
	v_mfma_f32_16x16x32_bf16 v[104:107], v[184:187], v[216:219], v[104:107]
	v_mfma_f32_16x16x32_bf16 v[108:111], v[188:191], v[216:219], v[108:111]
	v_mfma_f32_16x16x32_bf16 v[112:115], v[176:179], v[220:223], v[112:115]
	v_mfma_f32_16x16x32_bf16 v[116:119], v[180:183], v[220:223], v[116:119]
	v_mfma_f32_16x16x32_bf16 v[120:123], v[184:187], v[220:223], v[120:123]
	v_mfma_f32_16x16x32_bf16 v[124:127], v[188:191], v[220:223], v[124:127]
	s_setprio 0
	s_branch .Lg3b_epi

; template <class Epi>
; DI void gemm_phase(char* smem, const bf16_t* A0, int lda0, int ksplit, const bf16_t* A1, int lda1, const bf16_t* Bt, int K, int nN, const Epi& epi, int tid) {
;   const int G = gridDim.x;
;   if ((G & 7) == 0) {
;     const int x = blockIdx.x & 7, l = blockIdx.x >> 3, L = G >> 3, per = 8 * nN, tot = 2 * per;
;     for (int q = l; q < tot; q += L) { const int rgl = q / per, rem = q % per, ct = rem >> 3, rt = (x * 2 + rgl) * 8 + (rem & 7);
;       gemm_tile(smem, A0, lda0, ksplit, A1, lda1, Bt, K, rt * 256, ct * 128, epi, tid); }
; DI void phase_rw_small_gemms(const Ctx& c, char* smem) {
;     ...
;   gemm_phase(smem, sm + 64, 256, 1 << 30, sm, 256, A2, 64, 4, EpiSmall{1, p.rw_a0, Ab}, tid);
.Lg3b_done:
	s_setprio 0
	v_mbcnt_lo_u32_b32 v194, -1, 0
	v_mbcnt_hi_u32_b32 v136, -1, v194
	v_mbcnt_lo_u32_b32 v240, -1, 0
	v_mbcnt_hi_u32_b32 v240, -1, v240
	s_lshr_b32 s27, s72, 6
	s_lshl_b32 s100, s27, 10
	v_and_b32_e32 v241, 15, v240
	v_lshrrev_b32_e32 v242, 4, v240
	v_bfe_u32 v243, v240, 3, 1
	v_mul_u32_u24_e32 v243, 3, v243
	v_xor_b32_e32 v243, v242, v243
	v_lshlrev_b32_e32 v243, 4, v243
	v_lshl_add_u32 v243, v241, 6, v243
	s_lshr_b32 s26, s27, 1
	s_lshl_b32 s26, s26, 13
	v_add_u32_e32 v230, s26, v243
	s_and_b32 s26, s27, 1
	s_lshl_b32 s26, s26, 12
	s_add_u32 s26, s26, 16384
	v_add_u32_e32 v231, s26, v243
	s_lshr_b32 s26, s27, 1
	s_lshl_b32 s26, s26, 7
	v_add_u32_e32 v244, s26, v241
	s_and_b32 s26, s27, 1
	s_lshl_b32 s26, s26, 6
	v_lshl_add_u32 v245, v242, 2, s26
	v_lshlrev_b32_e32 v235, 2, v245
	s_mul_i32 s26, s27, 18432
	v_mul_u32_u24_e32 v246, 144, v241
	v_lshl_add_u32 v246, v242, 3, v246
	v_add_u32_e32 v236, s26, v246
	v_lshrrev_b32_e32 v246, 3, v240
	v_mul_u32_u24_e32 v246, 144, v246
	v_and_b32_e32 v247, 7, v240
	v_lshl_add_u32 v246, v247, 4, v246
	v_add_u32_e32 v237, s26, v246
	s_lshr_b32 s26, s27, 1
	s_lshl_b32 s26, s26, 7
	v_lshrrev_b32_e32 v246, 3, v240
	v_add_u32_e32 v246, s26, v246
	s_and_b32 s26, s27, 1
	s_lshl_b32 s26, s26, 6
	v_lshl_add_u32 v248, v247, 3, s26
	s_movk_i32 s26, 1024
	v_mul_lo_u32 v247, v246, s26
	v_lshl_add_u32 v238, v248, 1, v247
	v_lshrrev_b32_e32 v241, 2, v240
	s_lshl_b32 s26, s27, 4
	v_add_u32_e32 v241, s26, v241
	v_bfe_u32 v242, v240, 5, 1
	v_mul_u32_u24_e32 v242, 3, v242
	v_and_b32_e32 v243, 3, v240
	v_xor_b32_e32 v243, v243, v242
	v_lshlrev_b32_e32 v243, 4, v243
	s_mov_b32 s26, 512
	v_mad_u32_u24 v224, v241, s26, v243
	v_add_u32_e32 v225, 0x8000, v224
	v_add_u32_e32 v226, 0x10000, v224
	v_add_u32_e32 v227, 0x18000, v224
	s_mov_b32 s26, 128
	v_mad_u32_u24 v228, v241, s26, v243
	v_add_u32_e32 v229, 0x2000, v228
	s_load_dwordx2 s[6:7], s[74:75], 0x58
	s_cmpk_gt_u32 s96, 0xff
	s_cbranch_scc0 .Lg3c_prio
	s_setprio 1

; #define LWRITE(S, buf) do { bf16_t* sA_ = sbase + (buf) * BUF; bf16_t* sB_ = sA_ + 256 * PITCH; \
;     _Pragma("unroll") for (int i_ = 0; i_ < 4; ++i_) *(u32x4*)(sA_ + (sr + i_ * 64) * PITCH + scv * 8) = ra[S][i_]; \
;     _Pragma("unroll") for (int i_ = 0; i_ < 2; ++i_) *(u32x4*)(sB_ + (sr + i_ * 64) * PITCH + scv * 8) = rb[S][i_]; } while (0)
; template <class Epi>
; DI void gemm_tile(char* smem, const bf16_t* __restrict__ A0, int lda0, int ksplit, const bf16_t* __restrict__ A1, int lda1,
;                   const bf16_t* __restrict__ Bt, int K, int row0, int col0, const Epi& epi, int tid) {
;     ...
;   __syncthreads();
;   {
;     const int last = nk - 1;
;     GLOAD(0, 0);
;     __builtin_amdgcn_sched_barrier(0);
;     GLOAD(1, 1);
;     __builtin_amdgcn_sched_barrier(0);
;     LWRITE(0, 0);
;     __builtin_amdgcn_sched_barrier(0);
;     GLOAD(0, (2 < last ? 2 : last));
;     __builtin_amdgcn_sched_barrier(0);
;     __syncthreads();
; template <class Epi>
; DI void gemm_phase(char* smem, const bf16_t* A0, int lda0, int ksplit, const bf16_t* A1, int lda1, const bf16_t* Bt, int K, int nN, const Epi& epi, int tid) {
;     ...
;     for (int q = l; q < tot; q += L) { const int rgl = q / per, rem = q % per, ct = rem >> 3, rt = (x * 2 + rgl) * 8 + (rem & 7);
;       gemm_tile(smem, A0, lda0, ksplit, A1, lda1, Bt, K, rt * 256, ct * 128, epi, tid); }
.Lg3c_tile:
	s_cmpk_ge_u32 s15, 64
	s_cbranch_scc1 .Lg3c_done
	s_cmpk_ge_u32 s15, 32
	s_cselect_b32 s27, 1, 0
	s_cselect_b32 s26, 32, 0
	s_sub_u32 s26, s15, s26
	s_add_u32 s27, s27, s101
	s_lshl_b32 s27, s27, 3
	s_and_b32 s29, s26, 7
	s_add_u32 s29, s29, s27
	s_lshl_b32 s29, s29, 8
	s_lshr_b32 s28, s26, 3
	s_lshl_b32 s28, s28, 7
	s_mul_i32 s27, s29, 512
	s_add_u32 s27, s27, 0x1ea00080
	s_add_u32 s0, s92, s27
	s_addc_u32 s1, s93, 0
	s_mul_i32 s27, s28, 128
	s_add_u32 s27, s27, 0x34c0000
	s_add_u32 s2, s92, s27
	s_addc_u32 s3, s93, 0
	s_waitcnt lgkmcnt(0)
	s_barrier
	s_mov_b32 s99, 0
	s_mov_b32 s30, 0
	s_add_u32 s26, s30, s100
	s_add_u32 m0, s26, 0
	s_nop 0
	global_load_lds_dwordx4 v224, s[0:1]
	s_add_u32 m0, s26, 4096
	s_nop 0
	global_load_lds_dwordx4 v225, s[0:1]
	s_add_u32 m0, s26, 8192
	s_nop 0
	global_load_lds_dwordx4 v226, s[0:1]
	s_add_u32 m0, s26, 12288
	s_nop 0
	global_load_lds_dwordx4 v227, s[0:1]
	s_add_u32 m0, s26, 16384
	s_nop 0
	global_load_lds_dwordx4 v228, s[2:3]
	s_add_u32 m0, s26, 20480
	s_nop 0
	global_load_lds_dwordx4 v229, s[2:3]
	s_add_u32 s0, s0, 64
	s_addc_u32 s1, s1, 0
	s_add_u32 s2, s2, 64
	s_addc_u32 s3, s3, 0
	s_add_u32 s99, s99, 1
	s_add_u32 s30, s30, 24576
	s_cmp_eq_u32 s30, 73728
	s_cselect_b32 s30, 0, s30
	s_add_u32 s26, s30, s100
	s_add_u32 m0, s26, 0
	s_nop 0
	global_load_lds_dwordx4 v224, s[0:1]
	s_add_u32 m0, s26, 4096
	s_nop 0
	global_load_lds_dwordx4 v225, s[0:1]
	s_add_u32 m0, s26, 8192
	s_nop 0
	global_load_lds_dwordx4 v226, s[0:1]
	s_add_u32 m0, s26, 12288
	s_nop 0
	global_load_lds_dwordx4 v227, s[0:1]
	s_add_u32 m0, s26, 16384
	s_nop 0
	global_load_lds_dwordx4 v228, s[2:3]
	s_add_u32 m0, s26, 20480
	s_nop 0
	global_load_lds_dwordx4 v229, s[2:3]
	s_add_u32 s0, s0, 64
	s_addc_u32 s1, s1, 0
	s_add_u32 s2, s2, 64
	s_addc_u32 s3, s3, 0
	s_add_u32 s99, s99, 1
	s_add_u32 s30, s30, 24576
	s_cmp_eq_u32 s30, 73728
	s_cselect_b32 s30, 0, s30
	v_mov_b32_e32 v0, 0
	v_mov_b32_e32 v1, 0
	v_mov_b32_e32 v2, 0
	v_mov_b32_e32 v3, 0
	v_mov_b32_e32 v4, 0
	v_mov_b32_e32 v5, 0
	v_mov_b32_e32 v6, 0
	v_mov_b32_e32 v7, 0
	v_mov_b32_e32 v8, 0
	v_mov_b32_e32 v9, 0
	v_mov_b32_e32 v10, 0
	v_mov_b32_e32 v11, 0
	v_mov_b32_e32 v12, 0
	v_mov_b32_e32 v13, 0
	v_mov_b32_e32 v14, 0
	v_mov_b32_e32 v15, 0
	v_mov_b32_e32 v16, 0
	v_mov_b32_e32 v17, 0
	v_mov_b32_e32 v18, 0
	v_mov_b32_e32 v19, 0
	v_mov_b32_e32 v20, 0
	v_mov_b32_e32 v21, 0
	v_mov_b32_e32 v22, 0
	v_mov_b32_e32 v23, 0
	v_mov_b32_e32 v24, 0
	v_mov_b32_e32 v25, 0
	v_mov_b32_e32 v26, 0
	v_mov_b32_e32 v27, 0
	v_mov_b32_e32 v28, 0
	v_mov_b32_e32 v29, 0
	v_mov_b32_e32 v30, 0
	v_mov_b32_e32 v31, 0
	v_mov_b32_e32 v32, 0
	v_mov_b32_e32 v33, 0
	v_mov_b32_e32 v34, 0
	v_mov_b32_e32 v35, 0
	v_mov_b32_e32 v36, 0
	v_mov_b32_e32 v37, 0
	v_mov_b32_e32 v38, 0
	v_mov_b32_e32 v39, 0
	v_mov_b32_e32 v40, 0
	v_mov_b32_e32 v41, 0
	v_mov_b32_e32 v42, 0
	v_mov_b32_e32 v43, 0
	v_mov_b32_e32 v44, 0
	v_mov_b32_e32 v45, 0
	v_mov_b32_e32 v46, 0
	v_mov_b32_e32 v47, 0
	v_mov_b32_e32 v48, 0
	v_mov_b32_e32 v49, 0
	v_mov_b32_e32 v50, 0
	v_mov_b32_e32 v51, 0
	v_mov_b32_e32 v52, 0
	v_mov_b32_e32 v53, 0
	v_mov_b32_e32 v54, 0
	v_mov_b32_e32 v55, 0
	v_mov_b32_e32 v56, 0
	v_mov_b32_e32 v57, 0
	v_mov_b32_e32 v58, 0
	v_mov_b32_e32 v59, 0
	v_mov_b32_e32 v60, 0
	v_mov_b32_e32 v61, 0
	v_mov_b32_e32 v62, 0
	v_mov_b32_e32 v63, 0
	v_mov_b32_e32 v64, 0
	v_mov_b32_e32 v65, 0
	v_mov_b32_e32 v66, 0
	v_mov_b32_e32 v67, 0
	v_mov_b32_e32 v68, 0
	v_mov_b32_e32 v69, 0
	v_mov_b32_e32 v70, 0
	v_mov_b32_e32 v71, 0
	v_mov_b32_e32 v72, 0
	v_mov_b32_e32 v73, 0
	v_mov_b32_e32 v74, 0
	v_mov_b32_e32 v75, 0
	v_mov_b32_e32 v76, 0
	v_mov_b32_e32 v77, 0
	v_mov_b32_e32 v78, 0
	v_mov_b32_e32 v79, 0
	v_mov_b32_e32 v80, 0
	v_mov_b32_e32 v81, 0
	v_mov_b32_e32 v82, 0
	v_mov_b32_e32 v83, 0
	v_mov_b32_e32 v84, 0
	v_mov_b32_e32 v85, 0
	v_mov_b32_e32 v86, 0
	v_mov_b32_e32 v87, 0
	v_mov_b32_e32 v88, 0
	v_mov_b32_e32 v89, 0
	v_mov_b32_e32 v90, 0
	v_mov_b32_e32 v91, 0
	v_mov_b32_e32 v92, 0
	v_mov_b32_e32 v93, 0
	v_mov_b32_e32 v94, 0
	v_mov_b32_e32 v95, 0
	v_mov_b32_e32 v96, 0
	v_mov_b32_e32 v97, 0
	v_mov_b32_e32 v98, 0
	v_mov_b32_e32 v99, 0
	v_mov_b32_e32 v100, 0
	v_mov_b32_e32 v101, 0
	v_mov_b32_e32 v102, 0
	v_mov_b32_e32 v103, 0
	v_mov_b32_e32 v104, 0
	v_mov_b32_e32 v105, 0
	v_mov_b32_e32 v106, 0
	v_mov_b32_e32 v107, 0
	v_mov_b32_e32 v108, 0
	v_mov_b32_e32 v109, 0
	v_mov_b32_e32 v110, 0
	v_mov_b32_e32 v111, 0
	v_mov_b32_e32 v112, 0
	v_mov_b32_e32 v113, 0
	v_mov_b32_e32 v114, 0
	v_mov_b32_e32 v115, 0
	v_mov_b32_e32 v116, 0
	v_mov_b32_e32 v117, 0
	v_mov_b32_e32 v118, 0
	v_mov_b32_e32 v119, 0
	v_mov_b32_e32 v120, 0
	v_mov_b32_e32 v121, 0
	v_mov_b32_e32 v122, 0
	v_mov_b32_e32 v123, 0
	v_mov_b32_e32 v124, 0
	v_mov_b32_e32 v125, 0
	v_mov_b32_e32 v126, 0
	v_mov_b32_e32 v127, 0
	s_mov_b32 s98, 0
	s_mov_b32 s31, 24576
	s_waitcnt vmcnt(6)
	s_barrier
	ds_read_b128 v[128:131], v231 offset:0
	ds_read_b128 v[132:135], v231 offset:1024
	ds_read_b128 v[136:139], v231 offset:2048
	ds_read_b128 v[140:143], v231 offset:3072
	ds_read_b128 v[144:147], v230 offset:0
	ds_read_b128 v[148:151], v230 offset:1024
	ds_read_b128 v[152:155], v230 offset:2048
	ds_read_b128 v[156:159], v230 offset:3072
	ds_read_b128 v[160:163], v230 offset:4096
	ds_read_b128 v[164:167], v230 offset:5120
	ds_read_b128 v[168:171], v230 offset:6144
	ds_read_b128 v[172:175], v230 offset:7168
	s_waitcnt vmcnt(0)
	s_waitcnt lgkmcnt(0)
	s_barrier
	v_add_u32_e32 v232, s31, v230
	v_add_u32_e32 v233, s31, v231
	s_setprio 1
	v_mfma_f32_16x16x32_bf16 v[0:3], v[128:131], v[144:147], v[0:3]
	v_mfma_f32_16x16x32_bf16 v[4:7], v[132:135], v[144:147], v[4:7]
	v_mfma_f32_16x16x32_bf16 v[8:11], v[136:139], v[144:147], v[8:11]
	v_mfma_f32_16x16x32_bf16 v[12:15], v[140:143], v[144:147], v[12:15]
	ds_read_b128 v[176:179], v233 offset:0
	ds_read_b128 v[180:183], v233 offset:1024
	v_mfma_f32_16x16x32_bf16 v[16:19], v[128:131], v[148:151], v[16:19]
	v_mfma_f32_16x16x32_bf16 v[20:23], v[132:135], v[148:151], v[20:23]
	v_mfma_f32_16x16x32_bf16 v[24:27], v[136:139], v[148:151], v[24:27]
	v_mfma_f32_16x16x32_bf16 v[28:31], v[140:143], v[148:151], v[28:31]
	ds_read_b128 v[184:187], v233 offset:2048
	ds_read_b128 v[188:191], v233 offset:3072
	v_mfma_f32_16x16x32_bf16 v[32:35], v[128:131], v[152:155], v[32:35]
	v_mfma_f32_16x16x32_bf16 v[36:39], v[132:135], v[152:155], v[36:39]
	v_mfma_f32_16x16x32_bf16 v[40:43], v[136:139], v[152:155], v[40:43]
	v_mfma_f32_16x16x32_bf16 v[44:47], v[140:143], v[152:155], v[44:47]
	ds_read_b128 v[192:195], v232 offset:0
	ds_read_b128 v[196:199], v232 offset:1024
	v_mfma_f32_16x16x32_bf16 v[48:51], v[128:131], v[156:159], v[48:51]
	v_mfma_f32_16x16x32_bf16 v[52:55], v[132:135], v[156:159], v[52:55]
	v_mfma_f32_16x16x32_bf16 v[56:59], v[136:139], v[156:159], v[56:59]
	v_mfma_f32_16x16x32_bf16 v[60:63], v[140:143], v[156:159], v[60:63]
	ds_read_b128 v[200:203], v232 offset:2048
	ds_read_b128 v[204:207], v232 offset:3072
	v_mfma_f32_16x16x32_bf16 v[64:67], v[128:131], v[160:163], v[64:67]
	v_mfma_f32_16x16x32_bf16 v[68:71], v[132:135], v[160:163], v[68:71]
	v_mfma_f32_16x16x32_bf16 v[72:75], v[136:139], v[160:163], v[72:75]
	v_mfma_f32_16x16x32_bf16 v[76:79], v[140:143], v[160:163], v[76:79]
	ds_read_b128 v[208:211], v232 offset:4096
	v_mfma_f32_16x16x32_bf16 v[80:83], v[128:131], v[164:167], v[80:83]
	v_mfma_f32_16x16x32_bf16 v[84:87], v[132:135], v[164:167], v[84:87]
	v_mfma_f32_16x16x32_bf16 v[88:91], v[136:139], v[164:167], v[88:91]
	v_mfma_f32_16x16x32_bf16 v[92:95], v[140:143], v[164:167], v[92:95]
	ds_read_b128 v[212:215], v232 offset:5120
	v_mfma_f32_16x16x32_bf16 v[96:99], v[128:131], v[168:171], v[96:99]
	v_mfma_f32_16x16x32_bf16 v[100:103], v[132:135], v[168:171], v[100:103]
	v_mfma_f32_16x16x32_bf16 v[104:107], v[136:139], v[168:171], v[104:107]
	v_mfma_f32_16x16x32_bf16 v[108:111], v[140:143], v[168:171], v[108:111]
	ds_read_b128 v[216:219], v232 offset:6144
	s_add_u32 s31, s31, 24576
	s_cmp_eq_u32 s31, 73728
	s_cselect_b32 s31, 0, s31
	v_mfma_f32_16x16x32_bf16 v[112:115], v[128:131], v[172:175], v[112:115]
	v_mfma_f32_16x16x32_bf16 v[116:119], v[132:135], v[172:175], v[116:119]
	v_mfma_f32_16x16x32_bf16 v[120:123], v[136:139], v[172:175], v[120:123]
	v_mfma_f32_16x16x32_bf16 v[124:127], v[140:143], v[172:175], v[124:127]
	ds_read_b128 v[220:223], v232 offset:7168
	s_setprio 0
	s_waitcnt lgkmcnt(0)
	s_barrier
	s_setprio 1
	v_mfma_f32_16x16x32_bf16 v[0:3], v[176:179], v[192:195], v[0:3]
	v_mfma_f32_16x16x32_bf16 v[4:7], v[180:183], v[192:195], v[4:7]
	v_mfma_f32_16x16x32_bf16 v[8:11], v[184:187], v[192:195], v[8:11]
	v_mfma_f32_16x16x32_bf16 v[12:15], v[188:191], v[192:195], v[12:15]
	v_mfma_f32_16x16x32_bf16 v[16:19], v[176:179], v[196:199], v[16:19]
	v_mfma_f32_16x16x32_bf16 v[20:23], v[180:183], v[196:199], v[20:23]
	v_mfma_f32_16x16x32_bf16 v[24:27], v[184:187], v[196:199], v[24:27]
	v_mfma_f32_16x16x32_bf16 v[28:31], v[188:191], v[196:199], v[28:31]
	v_mfma_f32_16x16x32_bf16 v[32:35], v[176:179], v[200:203], v[32:35]
	v_mfma_f32_16x16x32_bf16 v[36:39], v[180:183], v[200:203], v[36:39]
	v_mfma_f32_16x16x32_bf16 v[40:43], v[184:187], v[200:203], v[40:43]
	v_mfma_f32_16x16x32_bf16 v[44:47], v[188:191], v[200:203], v[44:47]
	v_mfma_f32_16x16x32_bf16 v[48:51], v[176:179], v[204:207], v[48:51]
	v_mfma_f32_16x16x32_bf16 v[52:55], v[180:183], v[204:207], v[52:55]
	v_mfma_f32_16x16x32_bf16 v[56:59], v[184:187], v[204:207], v[56:59]
	v_mfma_f32_16x16x32_bf16 v[60:63], v[188:191], v[204:207], v[60:63]
	v_mfma_f32_16x16x32_bf16 v[64:67], v[176:179], v[208:211], v[64:67]
	v_mfma_f32_16x16x32_bf16 v[68:71], v[180:183], v[208:211], v[68:71]
	v_mfma_f32_16x16x32_bf16 v[72:75], v[184:187], v[208:211], v[72:75]
	v_mfma_f32_16x16x32_bf16 v[76:79], v[188:191], v[208:211], v[76:79]
	v_mfma_f32_16x16x32_bf16 v[80:83], v[176:179], v[212:215], v[80:83]
	v_mfma_f32_16x16x32_bf16 v[84:87], v[180:183], v[212:215], v[84:87]
	v_mfma_f32_16x16x32_bf16 v[88:91], v[184:187], v[212:215], v[88:91]
	v_mfma_f32_16x16x32_bf16 v[92:95], v[188:191], v[212:215], v[92:95]
	v_mfma_f32_16x16x32_bf16 v[96:99], v[176:179], v[216:219], v[96:99]
	v_mfma_f32_16x16x32_bf16 v[100:103], v[180:183], v[216:219], v[100:103]
	v_mfma_f32_16x16x32_bf16 v[104:107], v[184:187], v[216:219], v[104:107]
	v_mfma_f32_16x16x32_bf16 v[108:111], v[188:191], v[216:219], v[108:111]
	v_mfma_f32_16x16x32_bf16 v[112:115], v[176:179], v[220:223], v[112:115]
	v_mfma_f32_16x16x32_bf16 v[116:119], v[180:183], v[220:223], v[116:119]
	v_mfma_f32_16x16x32_bf16 v[120:123], v[184:187], v[220:223], v[120:123]
	v_mfma_f32_16x16x32_bf16 v[124:127], v[188:191], v[220:223], v[124:127]
	s_setprio 0
	s_branch .Lg3c_epi

; template <class Epi>
; DI void gemm_phase(char* smem, const bf16_t* A0, int lda0, int ksplit, const bf16_t* A1, int lda1, const bf16_t* Bt, int K, int nN, const Epi& epi, int tid) {
;   const int G = gridDim.x;
;   if ((G & 7) == 0) {
;     const int x = blockIdx.x & 7, l = blockIdx.x >> 3, L = G >> 3, per = 8 * nN, tot = 2 * per;
;     for (int q = l; q < tot; q += L) { const int rgl = q / per, rem = q % per, ct = rem >> 3, rt = (x * 2 + rgl) * 8 + (rem & 7);
;       gemm_tile(smem, A0, lda0, ksplit, A1, lda1, Bt, K, rt * 256, ct * 128, epi, tid); }
; DI void phase_rw_small_gemms(const Ctx& c, char* smem) {
;     ...
;   gemm_phase(smem, sm + 128, 256, 1 << 30, sm, 256, G2, 128, 4, EpiSmall{2, p.rw_a0, G}, tid);
.Lg3c_done:
	s_setprio 0
	v_mbcnt_lo_u32_b32 v194, -1, 0
	v_mbcnt_hi_u32_b32 v136, -1, v194
	v_mbcnt_lo_u32_b32 v240, -1, 0
	v_mbcnt_hi_u32_b32 v240, -1, v240
	s_lshr_b32 s27, s72, 6
	s_lshl_b32 s100, s27, 10
	v_and_b32_e32 v241, 15, v240
	v_lshrrev_b32_e32 v242, 4, v240
	v_bfe_u32 v243, v240, 3, 1
	v_mul_u32_u24_e32 v243, 3, v243
	v_xor_b32_e32 v243, v242, v243
	v_lshlrev_b32_e32 v243, 4, v243
	v_lshl_add_u32 v243, v241, 6, v243
	s_lshr_b32 s26, s27, 1
	s_lshl_b32 s26, s26, 13
	v_add_u32_e32 v230, s26, v243
	s_and_b32 s26, s27, 1
	s_lshl_b32 s26, s26, 12
	s_add_u32 s26, s26, 16384
	v_add_u32_e32 v231, s26, v243
	s_lshr_b32 s26, s27, 1
	s_lshl_b32 s26, s26, 7
	v_add_u32_e32 v244, s26, v241
	s_and_b32 s26, s27, 1
	s_lshl_b32 s26, s26, 6
	v_lshl_add_u32 v245, v242, 2, s26
	v_lshlrev_b32_e32 v235, 2, v245
	s_mul_i32 s26, s27, 18432
	v_mul_u32_u24_e32 v246, 144, v241
	v_lshl_add_u32 v246, v242, 3, v246
	v_add_u32_e32 v236, s26, v246
	v_lshrrev_b32_e32 v246, 3, v240
	v_mul_u32_u24_e32 v246, 144, v246
	v_and_b32_e32 v247, 7, v240
	v_lshl_add_u32 v246, v247, 4, v246
	v_add_u32_e32 v237, s26, v246
	s_lshr_b32 s26, s27, 1
	s_lshl_b32 s26, s26, 7
	v_lshrrev_b32_e32 v246, 3, v240
	v_add_u32_e32 v246, s26, v246
	s_and_b32 s26, s27, 1
	s_lshl_b32 s26, s26, 6
	v_lshl_add_u32 v248, v247, 3, s26
	s_movk_i32 s26, 1024
	v_mul_lo_u32 v247, v246, s26
	v_lshl_add_u32 v238, v248, 1, v247
	v_lshrrev_b32_e32 v241, 2, v240
	s_lshl_b32 s26, s27, 4
	v_add_u32_e32 v241, s26, v241
	v_bfe_u32 v242, v240, 5, 1
	v_mul_u32_u24_e32 v242, 3, v242
	v_and_b32_e32 v243, 3, v240
	v_xor_b32_e32 v243, v243, v242
	v_lshlrev_b32_e32 v243, 4, v243
	s_mov_b32 s26, 512
	v_mad_u32_u24 v224, v241, s26, v243
	v_add_u32_e32 v225, 0x8000, v224
	v_add_u32_e32 v226, 0x10000, v224
	v_add_u32_e32 v227, 0x18000, v224
	s_mov_b32 s26, 256
	v_mad_u32_u24 v228, v241, s26, v243
	v_add_u32_e32 v229, 0x4000, v228
	s_cmpk_gt_u32 s96, 0xff
	s_cbranch_scc0 .Lg3d_prio
	s_setprio 1

; #define LWRITE(S, buf) do { bf16_t* sA_ = sbase + (buf) * BUF; bf16_t* sB_ = sA_ + 256 * PITCH; \
;     _Pragma("unroll") for (int i_ = 0; i_ < 4; ++i_) *(u32x4*)(sA_ + (sr + i_ * 64) * PITCH + scv * 8) = ra[S][i_]; \
;     _Pragma("unroll") for (int i_ = 0; i_ < 2; ++i_) *(u32x4*)(sB_ + (sr + i_ * 64) * PITCH + scv * 8) = rb[S][i_]; } while (0)
; template <class Epi>
; DI void gemm_tile(char* smem, const bf16_t* __restrict__ A0, int lda0, int ksplit, const bf16_t* __restrict__ A1, int lda1,
;                   const bf16_t* __restrict__ Bt, int K, int row0, int col0, const Epi& epi, int tid) {
;     ...
;   __syncthreads();
;   {
;     const int last = nk - 1;
;     GLOAD(0, 0);
;     __builtin_amdgcn_sched_barrier(0);
;     GLOAD(1, 1);
;     __builtin_amdgcn_sched_barrier(0);
;     LWRITE(0, 0);
;     __builtin_amdgcn_sched_barrier(0);
;     GLOAD(0, (2 < last ? 2 : last));
;     __builtin_amdgcn_sched_barrier(0);
;     __syncthreads();
; template <class Epi>
; DI void gemm_phase(char* smem, const bf16_t* A0, int lda0, int ksplit, const bf16_t* A1, int lda1, const bf16_t* Bt, int K, int nN, const Epi& epi, int tid) {
;     ...
;     for (int q = l; q < tot; q += L) { const int rgl = q / per, rem = q % per, ct = rem >> 3, rt = (x * 2 + rgl) * 8 + (rem & 7);
;       gemm_tile(smem, A0, lda0, ksplit, A1, lda1, Bt, K, rt * 256, ct * 128, epi, tid); }
.Lg3d_tile:
	s_cmpk_ge_u32 s15, 64
	s_cbranch_scc1 .Lg3d_done
	s_cmpk_ge_u32 s15, 32
	s_cselect_b32 s27, 1, 0
	s_cselect_b32 s26, 32, 0
	s_sub_u32 s26, s15, s26
	s_add_u32 s27, s27, s101
	s_lshl_b32 s27, s27, 3
	s_and_b32 s29, s26, 7
	s_add_u32 s29, s29, s27
	s_lshl_b32 s29, s29, 8
	s_lshr_b32 s28, s26, 3
	s_lshl_b32 s28, s28, 7
	s_mul_i32 s27, s29, 512
	s_add_u32 s27, s27, 0x1ea00100
	s_add_u32 s0, s92, s27
	s_addc_u32 s1, s93, 0
	s_mul_i32 s27, s28, 256
	s_add_u32 s27, s27, 0x3480000
	s_add_u32 s2, s92, s27
	s_addc_u32 s3, s93, 0
	s_waitcnt lgkmcnt(0)
	s_barrier
	s_mov_b32 s99, 0
	s_mov_b32 s30, 0
	s_add_u32 s26, s30, s100
	s_add_u32 m0, s26, 0
	s_nop 0
	global_load_lds_dwordx4 v224, s[0:1]
	s_add_u32 m0, s26, 4096
	s_nop 0
	global_load_lds_dwordx4 v225, s[0:1]
	s_add_u32 m0, s26, 8192
	s_nop 0
	global_load_lds_dwordx4 v226, s[0:1]
	s_add_u32 m0, s26, 12288
	s_nop 0
	global_load_lds_dwordx4 v227, s[0:1]
	s_add_u32 m0, s26, 16384
	s_nop 0
	global_load_lds_dwordx4 v228, s[2:3]
	s_add_u32 m0, s26, 20480
	s_nop 0
	global_load_lds_dwordx4 v229, s[2:3]
	s_add_u32 s0, s0, 64
	s_addc_u32 s1, s1, 0
	s_add_u32 s2, s2, 64
	s_addc_u32 s3, s3, 0
	s_add_u32 s99, s99, 1
	s_add_u32 s30, s30, 24576
	s_cmp_eq_u32 s30, 73728
	s_cselect_b32 s30, 0, s30
	s_add_u32 s26, s30, s100
	s_add_u32 m0, s26, 0
	s_nop 0
	global_load_lds_dwordx4 v224, s[0:1]
	s_add_u32 m0, s26, 4096
	s_nop 0
	global_load_lds_dwordx4 v225, s[0:1]
	s_add_u32 m0, s26, 8192
	s_nop 0
	global_load_lds_dwordx4 v226, s[0:1]
	s_add_u32 m0, s26, 12288
	s_nop 0
	global_load_lds_dwordx4 v227, s[0:1]
	s_add_u32 m0, s26, 16384
	s_nop 0
	global_load_lds_dwordx4 v228, s[2:3]
	s_add_u32 m0, s26, 20480
	s_nop 0
	global_load_lds_dwordx4 v229, s[2:3]
	s_add_u32 s0, s0, 64
	s_addc_u32 s1, s1, 0
	s_add_u32 s2, s2, 64
	s_addc_u32 s3, s3, 0
	s_add_u32 s99, s99, 1
	s_add_u32 s30, s30, 24576
	s_cmp_eq_u32 s30, 73728
	s_cselect_b32 s30, 0, s30
	s_add_u32 s26, s30, s100
	s_add_u32 m0, s26, 0
	s_nop 0
	global_load_lds_dwordx4 v224, s[0:1]
	s_add_u32 m0, s26, 4096
	s_nop 0
	global_load_lds_dwordx4 v225, s[0:1]
	s_add_u32 m0, s26, 8192
	s_nop 0
	global_load_lds_dwordx4 v226, s[0:1]
	s_add_u32 m0, s26, 12288
	s_nop 0
	global_load_lds_dwordx4 v227, s[0:1]
	s_add_u32 m0, s26, 16384
	s_nop 0
	global_load_lds_dwordx4 v228, s[2:3]
	s_add_u32 m0, s26, 20480
	s_nop 0
	global_load_lds_dwordx4 v229, s[2:3]
	s_add_u32 s0, s0, 64
	s_addc_u32 s1, s1, 0
	s_add_u32 s2, s2, 64
	s_addc_u32 s3, s3, 0
	s_add_u32 s99, s99, 1
	s_add_u32 s30, s30, 24576
	s_cmp_eq_u32 s30, 73728
	s_cselect_b32 s30, 0, s30
	v_mov_b32_e32 v0, 0
	v_mov_b32_e32 v1, 0
	v_mov_b32_e32 v2, 0
	v_mov_b32_e32 v3, 0
	v_mov_b32_e32 v4, 0
	v_mov_b32_e32 v5, 0
	v_mov_b32_e32 v6, 0
	v_mov_b32_e32 v7, 0
	v_mov_b32_e32 v8, 0
	v_mov_b32_e32 v9, 0
	v_mov_b32_e32 v10, 0
	v_mov_b32_e32 v11, 0
	v_mov_b32_e32 v12, 0
	v_mov_b32_e32 v13, 0
	v_mov_b32_e32 v14, 0
	v_mov_b32_e32 v15, 0
	v_mov_b32_e32 v16, 0
	v_mov_b32_e32 v17, 0
	v_mov_b32_e32 v18, 0
	v_mov_b32_e32 v19, 0
	v_mov_b32_e32 v20, 0
	v_mov_b32_e32 v21, 0
	v_mov_b32_e32 v22, 0
	v_mov_b32_e32 v23, 0
	v_mov_b32_e32 v24, 0
	v_mov_b32_e32 v25, 0
	v_mov_b32_e32 v26, 0
	v_mov_b32_e32 v27, 0
	v_mov_b32_e32 v28, 0
	v_mov_b32_e32 v29, 0
	v_mov_b32_e32 v30, 0
	v_mov_b32_e32 v31, 0
	v_mov_b32_e32 v32, 0
	v_mov_b32_e32 v33, 0
	v_mov_b32_e32 v34, 0
	v_mov_b32_e32 v35, 0
	v_mov_b32_e32 v36, 0
	v_mov_b32_e32 v37, 0
	v_mov_b32_e32 v38, 0
	v_mov_b32_e32 v39, 0
	v_mov_b32_e32 v40, 0
	v_mov_b32_e32 v41, 0
	v_mov_b32_e32 v42, 0
	v_mov_b32_e32 v43, 0
	v_mov_b32_e32 v44, 0
	v_mov_b32_e32 v45, 0
	v_mov_b32_e32 v46, 0
	v_mov_b32_e32 v47, 0
	v_mov_b32_e32 v48, 0
	v_mov_b32_e32 v49, 0
	v_mov_b32_e32 v50, 0
	v_mov_b32_e32 v51, 0
	v_mov_b32_e32 v52, 0
	v_mov_b32_e32 v53, 0
	v_mov_b32_e32 v54, 0
	v_mov_b32_e32 v55, 0
	v_mov_b32_e32 v56, 0
	v_mov_b32_e32 v57, 0
	v_mov_b32_e32 v58, 0
	v_mov_b32_e32 v59, 0
	v_mov_b32_e32 v60, 0
	v_mov_b32_e32 v61, 0
	v_mov_b32_e32 v62, 0
	v_mov_b32_e32 v63, 0
	v_mov_b32_e32 v64, 0
	v_mov_b32_e32 v65, 0
	v_mov_b32_e32 v66, 0
	v_mov_b32_e32 v67, 0
	v_mov_b32_e32 v68, 0
	v_mov_b32_e32 v69, 0
	v_mov_b32_e32 v70, 0
	v_mov_b32_e32 v71, 0
	v_mov_b32_e32 v72, 0
	v_mov_b32_e32 v73, 0
	v_mov_b32_e32 v74, 0
	v_mov_b32_e32 v75, 0
	v_mov_b32_e32 v76, 0
	v_mov_b32_e32 v77, 0
	v_mov_b32_e32 v78, 0
	v_mov_b32_e32 v79, 0
	v_mov_b32_e32 v80, 0
	v_mov_b32_e32 v81, 0
	v_mov_b32_e32 v82, 0
	v_mov_b32_e32 v83, 0
	v_mov_b32_e32 v84, 0
	v_mov_b32_e32 v85, 0
	v_mov_b32_e32 v86, 0
	v_mov_b32_e32 v87, 0
	v_mov_b32_e32 v88, 0
	v_mov_b32_e32 v89, 0
	v_mov_b32_e32 v90, 0
	v_mov_b32_e32 v91, 0
	v_mov_b32_e32 v92, 0
	v_mov_b32_e32 v93, 0
	v_mov_b32_e32 v94, 0
	v_mov_b32_e32 v95, 0
	v_mov_b32_e32 v96, 0
	v_mov_b32_e32 v97, 0
	v_mov_b32_e32 v98, 0
	v_mov_b32_e32 v99, 0
	v_mov_b32_e32 v100, 0
	v_mov_b32_e32 v101, 0
	v_mov_b32_e32 v102, 0
	v_mov_b32_e32 v103, 0
	v_mov_b32_e32 v104, 0
	v_mov_b32_e32 v105, 0
	v_mov_b32_e32 v106, 0
	v_mov_b32_e32 v107, 0
	v_mov_b32_e32 v108, 0
	v_mov_b32_e32 v109, 0
	v_mov_b32_e32 v110, 0
	v_mov_b32_e32 v111, 0
	v_mov_b32_e32 v112, 0
	v_mov_b32_e32 v113, 0
	v_mov_b32_e32 v114, 0
	v_mov_b32_e32 v115, 0
	v_mov_b32_e32 v116, 0
	v_mov_b32_e32 v117, 0
	v_mov_b32_e32 v118, 0
	v_mov_b32_e32 v119, 0
	v_mov_b32_e32 v120, 0
	v_mov_b32_e32 v121, 0
	v_mov_b32_e32 v122, 0
	v_mov_b32_e32 v123, 0
	v_mov_b32_e32 v124, 0
	v_mov_b32_e32 v125, 0
	v_mov_b32_e32 v126, 0
	v_mov_b32_e32 v127, 0
	s_mov_b32 s98, 0
	s_mov_b32 s31, 24576
	s_waitcnt vmcnt(12)
	s_barrier
; #define LWRITE(S, buf) do { bf16_t* sA_ = sbase + (buf) * BUF; bf16_t* sB_ = sA_ + 256 * PITCH; \
;     _Pragma("unroll") for (int i_ = 0; i_ < 4; ++i_) *(u32x4*)(sA_ + (sr + i_ * 64) * PITCH + scv * 8) = ra[S][i_]; \
;     _Pragma("unroll") for (int i_ = 0; i_ < 2; ++i_) *(u32x4*)(sB_ + (sr + i_ * 64) * PITCH + scv * 8) = rb[S][i_]; } while (0)
; template <class Epi>
; DI void gemm_tile(char* smem, const bf16_t* __restrict__ A0, int lda0, int ksplit, const bf16_t* __restrict__ A1, int lda1,
;                   const bf16_t* __restrict__ Bt, int K, int row0, int col0, const Epi& epi, int tid) {
;     ...
;   __syncthreads();
;   {
;     const int last = nk - 1;
;     GLOAD(0, 0);
;     __builtin_amdgcn_sched_barrier(0);
;     GLOAD(1, 1);
;     __builtin_amdgcn_sched_barrier(0);
;     LWRITE(0, 0);
;     __builtin_amdgcn_sched_barrier(0);
;     GLOAD(0, (2 < last ? 2 : last));
;     __builtin_amdgcn_sched_barrier(0);
;     __syncthreads();
;     for (int kt = 0; kt < nk; kt += 2) {
;       LWRITE(1, 1);
;       __builtin_amdgcn_sched_barrier(0);
;       GLOAD(1, (kt + 3 < last ? kt + 3 : last));
;       __builtin_amdgcn_sched_barrier(0);
;       COMPUTE(0);
;       __syncthreads();
;       LWRITE(0, 0);
;       __builtin_amdgcn_sched_barrier(0);
;       GLOAD(0, (kt + 4 < last ? kt + 4 : last));
;       __builtin_amdgcn_sched_barrier(0);
;       COMPUTE(1);
;       __syncthreads();
	ds_read_b128 v[128:131], v231 offset:0
	ds_read_b128 v[132:135], v231 offset:1024
	ds_read_b128 v[136:139], v231 offset:2048
	ds_read_b128 v[140:143], v231 offset:3072
	ds_read_b128 v[144:147], v230 offset:0
	ds_read_b128 v[148:151], v230 offset:1024
	ds_read_b128 v[152:155], v230 offset:2048
	ds_read_b128 v[156:159], v230 offset:3072
	ds_read_b128 v[160:163], v230 offset:4096
	ds_read_b128 v[164:167], v230 offset:5120
	ds_read_b128 v[168:171], v230 offset:6144
	ds_read_b128 v[172:175], v230 offset:7168
	s_waitcnt vmcnt(6)
	s_waitcnt lgkmcnt(0)
	s_barrier
	v_add_u32_e32 v232, s31, v230
	v_add_u32_e32 v233, s31, v231
	s_add_u32 s26, s30, s100
	s_setprio 1
	v_mfma_f32_16x16x32_bf16 v[0:3], v[128:131], v[144:147], v[0:3]
	v_mfma_f32_16x16x32_bf16 v[4:7], v[132:135], v[144:147], v[4:7]
	v_mfma_f32_16x16x32_bf16 v[8:11], v[136:139], v[144:147], v[8:11]
	v_mfma_f32_16x16x32_bf16 v[12:15], v[140:143], v[144:147], v[12:15]
	ds_read_b128 v[176:179], v233 offset:0
	ds_read_b128 v[180:183], v233 offset:1024
	s_add_u32 m0, s26, 0
	s_nop 0
	global_load_lds_dwordx4 v224, s[0:1]
	v_mfma_f32_16x16x32_bf16 v[16:19], v[128:131], v[148:151], v[16:19]
	v_mfma_f32_16x16x32_bf16 v[20:23], v[132:135], v[148:151], v[20:23]
	v_mfma_f32_16x16x32_bf16 v[24:27], v[136:139], v[148:151], v[24:27]
	v_mfma_f32_16x16x32_bf16 v[28:31], v[140:143], v[148:151], v[28:31]
	ds_read_b128 v[184:187], v233 offset:2048
	ds_read_b128 v[188:191], v233 offset:3072
	s_add_u32 m0, s26, 4096
	s_nop 0
	global_load_lds_dwordx4 v225, s[0:1]
	v_mfma_f32_16x16x32_bf16 v[32:35], v[128:131], v[152:155], v[32:35]
	v_mfma_f32_16x16x32_bf16 v[36:39], v[132:135], v[152:155], v[36:39]
	v_mfma_f32_16x16x32_bf16 v[40:43], v[136:139], v[152:155], v[40:43]
	v_mfma_f32_16x16x32_bf16 v[44:47], v[140:143], v[152:155], v[44:47]
	ds_read_b128 v[192:195], v232 offset:0
	ds_read_b128 v[196:199], v232 offset:1024
	s_add_u32 m0, s26, 8192
	s_nop 0
	global_load_lds_dwordx4 v226, s[0:1]
	v_mfma_f32_16x16x32_bf16 v[48:51], v[128:131], v[156:159], v[48:51]
	v_mfma_f32_16x16x32_bf16 v[52:55], v[132:135], v[156:159], v[52:55]
	v_mfma_f32_16x16x32_bf16 v[56:59], v[136:139], v[156:159], v[56:59]
	v_mfma_f32_16x16x32_bf16 v[60:63], v[140:143], v[156:159], v[60:63]
	ds_read_b128 v[200:203], v232 offset:2048
	ds_read_b128 v[204:207], v232 offset:3072
	s_add_u32 m0, s26, 12288
	s_nop 0
	global_load_lds_dwordx4 v227, s[0:1]
	v_mfma_f32_16x16x32_bf16 v[64:67], v[128:131], v[160:163], v[64:67]
	v_mfma_f32_16x16x32_bf16 v[68:71], v[132:135], v[160:163], v[68:71]
	v_mfma_f32_16x16x32_bf16 v[72:75], v[136:139], v[160:163], v[72:75]
	v_mfma_f32_16x16x32_bf16 v[76:79], v[140:143], v[160:163], v[76:79]
	ds_read_b128 v[208:211], v232 offset:4096
	s_add_u32 m0, s26, 16384
	s_nop 0
	global_load_lds_dwordx4 v228, s[2:3]
	v_mfma_f32_16x16x32_bf16 v[80:83], v[128:131], v[164:167], v[80:83]
	v_mfma_f32_16x16x32_bf16 v[84:87], v[132:135], v[164:167], v[84:87]
	v_mfma_f32_16x16x32_bf16 v[88:91], v[136:139], v[164:167], v[88:91]
	v_mfma_f32_16x16x32_bf16 v[92:95], v[140:143], v[164:167], v[92:95]
	ds_read_b128 v[212:215], v232 offset:5120
	s_add_u32 m0, s26, 20480
	s_nop 0
	global_load_lds_dwordx4 v229, s[2:3]
	v_mfma_f32_16x16x32_bf16 v[96:99], v[128:131], v[168:171], v[96:99]
	v_mfma_f32_16x16x32_bf16 v[100:103], v[132:135], v[168:171], v[100:103]
	v_mfma_f32_16x16x32_bf16 v[104:107], v[136:139], v[168:171], v[104:107]
	v_mfma_f32_16x16x32_bf16 v[108:111], v[140:143], v[168:171], v[108:111]
	ds_read_b128 v[216:219], v232 offset:6144
	s_add_u32 s0, s0, 64
	s_addc_u32 s1, s1, 0
	s_add_u32 s2, s2, 64
	s_addc_u32 s3, s3, 0
	s_add_u32 s99, s99, 1
	s_add_u32 s30, s30, 24576
	s_cmp_eq_u32 s30, 73728
	s_cselect_b32 s30, 0, s30
	s_add_u32 s31, s31, 24576
	s_cmp_eq_u32 s31, 73728
	s_cselect_b32 s31, 0, s31
	v_mfma_f32_16x16x32_bf16 v[112:115], v[128:131], v[172:175], v[112:115]
	v_mfma_f32_16x16x32_bf16 v[116:119], v[132:135], v[172:175], v[116:119]
	v_mfma_f32_16x16x32_bf16 v[120:123], v[136:139], v[172:175], v[120:123]
	v_mfma_f32_16x16x32_bf16 v[124:127], v[140:143], v[172:175], v[124:127]
	ds_read_b128 v[220:223], v232 offset:7168
	s_setprio 0
	s_waitcnt vmcnt(6)
	s_waitcnt lgkmcnt(0)
	s_barrier
	v_add_u32_e32 v232, s31, v230
	v_add_u32_e32 v233, s31, v231
	s_setprio 1
	v_mfma_f32_16x16x32_bf16 v[0:3], v[176:179], v[192:195], v[0:3]
	v_mfma_f32_16x16x32_bf16 v[4:7], v[180:183], v[192:195], v[4:7]
	v_mfma_f32_16x16x32_bf16 v[8:11], v[184:187], v[192:195], v[8:11]
	v_mfma_f32_16x16x32_bf16 v[12:15], v[188:191], v[192:195], v[12:15]
	ds_read_b128 v[128:131], v233 offset:0
	ds_read_b128 v[132:135], v233 offset:1024
	v_mfma_f32_16x16x32_bf16 v[16:19], v[176:179], v[196:199], v[16:19]
	v_mfma_f32_16x16x32_bf16 v[20:23], v[180:183], v[196:199], v[20:23]
	v_mfma_f32_16x16x32_bf16 v[24:27], v[184:187], v[196:199], v[24:27]
	v_mfma_f32_16x16x32_bf16 v[28:31], v[188:191], v[196:199], v[28:31]
	ds_read_b128 v[136:139], v233 offset:2048
	ds_read_b128 v[140:143], v233 offset:3072
	v_mfma_f32_16x16x32_bf16 v[32:35], v[176:179], v[200:203], v[32:35]
	v_mfma_f32_16x16x32_bf16 v[36:39], v[180:183], v[200:203], v[36:39]
	v_mfma_f32_16x16x32_bf16 v[40:43], v[184:187], v[200:203], v[40:43]
	v_mfma_f32_16x16x32_bf16 v[44:47], v[188:191], v[200:203], v[44:47]
	ds_read_b128 v[144:147], v232 offset:0
	ds_read_b128 v[148:151], v232 offset:1024
	v_mfma_f32_16x16x32_bf16 v[48:51], v[176:179], v[204:207], v[48:51]
	v_mfma_f32_16x16x32_bf16 v[52:55], v[180:183], v[204:207], v[52:55]
	v_mfma_f32_16x16x32_bf16 v[56:59], v[184:187], v[204:207], v[56:59]
	v_mfma_f32_16x16x32_bf16 v[60:63], v[188:191], v[204:207], v[60:63]
	ds_read_b128 v[152:155], v232 offset:2048
; #define LWRITE(S, buf) do { bf16_t* sA_ = sbase + (buf) * BUF; bf16_t* sB_ = sA_ + 256 * PITCH; \
;     _Pragma("unroll") for (int i_ = 0; i_ < 4; ++i_) *(u32x4*)(sA_ + (sr + i_ * 64) * PITCH + scv * 8) = ra[S][i_]; \
;     _Pragma("unroll") for (int i_ = 0; i_ < 2; ++i_) *(u32x4*)(sB_ + (sr + i_ * 64) * PITCH + scv * 8) = rb[S][i_]; } while (0)
; template <class Epi>
; DI void gemm_tile(char* smem, const bf16_t* __restrict__ A0, int lda0, int ksplit, const bf16_t* __restrict__ A1, int lda1,
;                   const bf16_t* __restrict__ Bt, int K, int row0, int col0, const Epi& epi, int tid) {
;     ...
;     for (int kt = 0; kt < nk; kt += 2) {
;       LWRITE(1, 1);
;       __builtin_amdgcn_sched_barrier(0);
;       GLOAD(1, (kt + 3 < last ? kt + 3 : last));
;       __builtin_amdgcn_sched_barrier(0);
;       COMPUTE(0);
;       __syncthreads();
;       LWRITE(0, 0);
;       __builtin_amdgcn_sched_barrier(0);
;       GLOAD(0, (kt + 4 < last ? kt + 4 : last));
;       __builtin_amdgcn_sched_barrier(0);
;       COMPUTE(1);
;       __syncthreads();
	ds_read_b128 v[156:159], v232 offset:3072
	v_mfma_f32_16x16x32_bf16 v[64:67], v[176:179], v[208:211], v[64:67]
	v_mfma_f32_16x16x32_bf16 v[68:71], v[180:183], v[208:211], v[68:71]
	v_mfma_f32_16x16x32_bf16 v[72:75], v[184:187], v[208:211], v[72:75]
	v_mfma_f32_16x16x32_bf16 v[76:79], v[188:191], v[208:211], v[76:79]
	ds_read_b128 v[160:163], v232 offset:4096
	v_mfma_f32_16x16x32_bf16 v[80:83], v[176:179], v[212:215], v[80:83]
	v_mfma_f32_16x16x32_bf16 v[84:87], v[180:183], v[212:215], v[84:87]
	v_mfma_f32_16x16x32_bf16 v[88:91], v[184:187], v[212:215], v[88:91]
	v_mfma_f32_16x16x32_bf16 v[92:95], v[188:191], v[212:215], v[92:95]
	ds_read_b128 v[164:167], v232 offset:5120
	v_mfma_f32_16x16x32_bf16 v[96:99], v[176:179], v[216:219], v[96:99]
	v_mfma_f32_16x16x32_bf16 v[100:103], v[180:183], v[216:219], v[100:103]
	v_mfma_f32_16x16x32_bf16 v[104:107], v[184:187], v[216:219], v[104:107]
	v_mfma_f32_16x16x32_bf16 v[108:111], v[188:191], v[216:219], v[108:111]
	ds_read_b128 v[168:171], v232 offset:6144
	s_add_u32 s31, s31, 24576
	s_cmp_eq_u32 s31, 73728
	s_cselect_b32 s31, 0, s31
	v_mfma_f32_16x16x32_bf16 v[112:115], v[176:179], v[220:223], v[112:115]
	v_mfma_f32_16x16x32_bf16 v[116:119], v[180:183], v[220:223], v[116:119]
	v_mfma_f32_16x16x32_bf16 v[120:123], v[184:187], v[220:223], v[120:123]
	v_mfma_f32_16x16x32_bf16 v[124:127], v[188:191], v[220:223], v[124:127]
	ds_read_b128 v[172:175], v232 offset:7168
	s_setprio 0
	s_waitcnt vmcnt(0)
	s_waitcnt lgkmcnt(0)
	s_barrier
	v_add_u32_e32 v232, s31, v230
	v_add_u32_e32 v233, s31, v231
	s_setprio 1
	v_mfma_f32_16x16x32_bf16 v[0:3], v[128:131], v[144:147], v[0:3]
	v_mfma_f32_16x16x32_bf16 v[4:7], v[132:135], v[144:147], v[4:7]
	v_mfma_f32_16x16x32_bf16 v[8:11], v[136:139], v[144:147], v[8:11]
	v_mfma_f32_16x16x32_bf16 v[12:15], v[140:143], v[144:147], v[12:15]
	ds_read_b128 v[176:179], v233 offset:0
	ds_read_b128 v[180:183], v233 offset:1024
	v_mfma_f32_16x16x32_bf16 v[16:19], v[128:131], v[148:151], v[16:19]
	v_mfma_f32_16x16x32_bf16 v[20:23], v[132:135], v[148:151], v[20:23]
	v_mfma_f32_16x16x32_bf16 v[24:27], v[136:139], v[148:151], v[24:27]
	v_mfma_f32_16x16x32_bf16 v[28:31], v[140:143], v[148:151], v[28:31]
	ds_read_b128 v[184:187], v233 offset:2048
	ds_read_b128 v[188:191], v233 offset:3072
	v_mfma_f32_16x16x32_bf16 v[32:35], v[128:131], v[152:155], v[32:35]
	v_mfma_f32_16x16x32_bf16 v[36:39], v[132:135], v[152:155], v[36:39]
	v_mfma_f32_16x16x32_bf16 v[40:43], v[136:139], v[152:155], v[40:43]
	v_mfma_f32_16x16x32_bf16 v[44:47], v[140:143], v[152:155], v[44:47]
	ds_read_b128 v[192:195], v232 offset:0
	ds_read_b128 v[196:199], v232 offset:1024
	v_mfma_f32_16x16x32_bf16 v[48:51], v[128:131], v[156:159], v[48:51]
	v_mfma_f32_16x16x32_bf16 v[52:55], v[132:135], v[156:159], v[52:55]
	v_mfma_f32_16x16x32_bf16 v[56:59], v[136:139], v[156:159], v[56:59]
	v_mfma_f32_16x16x32_bf16 v[60:63], v[140:143], v[156:159], v[60:63]
	ds_read_b128 v[200:203], v232 offset:2048
	ds_read_b128 v[204:207], v232 offset:3072
	v_mfma_f32_16x16x32_bf16 v[64:67], v[128:131], v[160:163], v[64:67]
	v_mfma_f32_16x16x32_bf16 v[68:71], v[132:135], v[160:163], v[68:71]
	v_mfma_f32_16x16x32_bf16 v[72:75], v[136:139], v[160:163], v[72:75]
	v_mfma_f32_16x16x32_bf16 v[76:79], v[140:143], v[160:163], v[76:79]
	ds_read_b128 v[208:211], v232 offset:4096
	v_mfma_f32_16x16x32_bf16 v[80:83], v[128:131], v[164:167], v[80:83]
	v_mfma_f32_16x16x32_bf16 v[84:87], v[132:135], v[164:167], v[84:87]
	v_mfma_f32_16x16x32_bf16 v[88:91], v[136:139], v[164:167], v[88:91]
	v_mfma_f32_16x16x32_bf16 v[92:95], v[140:143], v[164:167], v[92:95]
	ds_read_b128 v[212:215], v232 offset:5120
	v_mfma_f32_16x16x32_bf16 v[96:99], v[128:131], v[168:171], v[96:99]
	v_mfma_f32_16x16x32_bf16 v[100:103], v[132:135], v[168:171], v[100:103]
	v_mfma_f32_16x16x32_bf16 v[104:107], v[136:139], v[168:171], v[104:107]
	v_mfma_f32_16x16x32_bf16 v[108:111], v[140:143], v[168:171], v[108:111]
	ds_read_b128 v[216:219], v232 offset:6144
	s_add_u32 s31, s31, 24576
	s_cmp_eq_u32 s31, 73728
	s_cselect_b32 s31, 0, s31
	v_mfma_f32_16x16x32_bf16 v[112:115], v[128:131], v[172:175], v[112:115]
	v_mfma_f32_16x16x32_bf16 v[116:119], v[132:135], v[172:175], v[116:119]
	v_mfma_f32_16x16x32_bf16 v[120:123], v[136:139], v[172:175], v[120:123]
	v_mfma_f32_16x16x32_bf16 v[124:127], v[140:143], v[172:175], v[124:127]
	ds_read_b128 v[220:223], v232 offset:7168
	s_setprio 0
	s_waitcnt lgkmcnt(0)
	s_barrier
	s_setprio 1
	v_mfma_f32_16x16x32_bf16 v[0:3], v[176:179], v[192:195], v[0:3]
	v_mfma_f32_16x16x32_bf16 v[4:7], v[180:183], v[192:195], v[4:7]
	v_mfma_f32_16x16x32_bf16 v[8:11], v[184:187], v[192:195], v[8:11]
	v_mfma_f32_16x16x32_bf16 v[12:15], v[188:191], v[192:195], v[12:15]
	v_mfma_f32_16x16x32_bf16 v[16:19], v[176:179], v[196:199], v[16:19]
	v_mfma_f32_16x16x32_bf16 v[20:23], v[180:183], v[196:199], v[20:23]
	v_mfma_f32_16x16x32_bf16 v[24:27], v[184:187], v[196:199], v[24:27]
	v_mfma_f32_16x16x32_bf16 v[28:31], v[188:191], v[196:199], v[28:31]
	v_mfma_f32_16x16x32_bf16 v[32:35], v[176:179], v[200:203], v[32:35]
	v_mfma_f32_16x16x32_bf16 v[36:39], v[180:183], v[200:203], v[36:39]
	v_mfma_f32_16x16x32_bf16 v[40:43], v[184:187], v[200:203], v[40:43]
	v_mfma_f32_16x16x32_bf16 v[44:47], v[188:191], v[200:203], v[44:47]
	v_mfma_f32_16x16x32_bf16 v[48:51], v[176:179], v[204:207], v[48:51]
	v_mfma_f32_16x16x32_bf16 v[52:55], v[180:183], v[204:207], v[52:55]
	v_mfma_f32_16x16x32_bf16 v[56:59], v[184:187], v[204:207], v[56:59]
	v_mfma_f32_16x16x32_bf16 v[60:63], v[188:191], v[204:207], v[60:63]
	v_mfma_f32_16x16x32_bf16 v[64:67], v[176:179], v[208:211], v[64:67]
	v_mfma_f32_16x16x32_bf16 v[68:71], v[180:183], v[208:211], v[68:71]
	v_mfma_f32_16x16x32_bf16 v[72:75], v[184:187], v[208:211], v[72:75]
	v_mfma_f32_16x16x32_bf16 v[76:79], v[188:191], v[208:211], v[76:79]
	v_mfma_f32_16x16x32_bf16 v[80:83], v[176:179], v[212:215], v[80:83]
	v_mfma_f32_16x16x32_bf16 v[84:87], v[180:183], v[212:215], v[84:87]
	v_mfma_f32_16x16x32_bf16 v[88:91], v[184:187], v[212:215], v[88:91]
	v_mfma_f32_16x16x32_bf16 v[92:95], v[188:191], v[212:215], v[92:95]
	v_mfma_f32_16x16x32_bf16 v[96:99], v[176:179], v[216:219], v[96:99]
	v_mfma_f32_16x16x32_bf16 v[100:103], v[180:183], v[216:219], v[100:103]
	v_mfma_f32_16x16x32_bf16 v[104:107], v[184:187], v[216:219], v[104:107]
	v_mfma_f32_16x16x32_bf16 v[108:111], v[188:191], v[216:219], v[108:111]
	v_mfma_f32_16x16x32_bf16 v[112:115], v[176:179], v[220:223], v[112:115]
	v_mfma_f32_16x16x32_bf16 v[116:119], v[180:183], v[220:223], v[116:119]
	v_mfma_f32_16x16x32_bf16 v[120:123], v[184:187], v[220:223], v[120:123]
	v_mfma_f32_16x16x32_bf16 v[124:127], v[188:191], v[220:223], v[124:127]
	s_setprio 0
	s_branch .Lg3d_epi

; template <class Epi>
; DI void gemm_phase(char* smem, const bf16_t* A0, int lda0, int ksplit, const bf16_t* A1, int lda1, const bf16_t* Bt, int K, int nN, const Epi& epi, int tid) {
;   const int G = gridDim.x;
;   if ((G & 7) == 0) {
;     const int x = blockIdx.x & 7, l = blockIdx.x >> 3, L = G >> 3, per = 8 * nN, tot = 2 * per;
;     for (int q = l; q < tot; q += L) { const int rgl = q / per, rem = q % per, ct = rem >> 3, rt = (x * 2 + rgl) * 8 + (rem & 7);
;       gemm_tile(smem, A0, lda0, ksplit, A1, lda1, Bt, K, rt * 256, ct * 128, epi, tid); }
;   } else {
;     const int ntiles = (NTOK / 256) * nN;
;     for (int u = blockIdx.x; u < ntiles; u += G) { const int rt = u / nN, ct = u % nN; gemm_tile(smem, A0, lda0, ksplit, A1, lda1, Bt, K, rt * 256, ct * 128, epi, tid); }
;   }
; }
.Lg3d_done:
	s_setprio 0
	v_mbcnt_lo_u32_b32 v194, -1, 0
	v_mbcnt_hi_u32_b32 v136, -1, v194

; #define PH(k) case k: if (ONLY_PHASE >= 0 && ONLY_PHASE != k) break;
; template <class Epi>
; DI void gemm_phase(char* smem, const bf16_t* A0, int lda0, int ksplit, const bf16_t* A1, int lda1, const bf16_t* Bt, int K, int nN, const Epi& epi, int tid) {
;   const int G = gridDim.x;
;   if ((G & 7) == 0) {
;     const int x = blockIdx.x & 7, l = blockIdx.x >> 3, L = G >> 3, per = 8 * nN, tot = 2 * per;
;     for (int q = l; q < tot; q += L) { const int rgl = q / per, rem = q % per, ct = rem >> 3, rt = (x * 2 + rgl) * 8 + (rem & 7);
;       gemm_tile(smem, A0, lda0, ksplit, A1, lda1, Bt, K, rt * 256, ct * 128, epi, tid); }
; template <int ph> DI void run_phase(const Ctx& c, char* smem) {
;     ...
;     PH(6) gemm_phase(smem, (const bf16_t*)(ws + OFF_R1), 512, 512, (const bf16_t*)(ws + OFF_R2), 2592, (const bf16_t*)(ws + OFF_WABOUT), 1536, 8, EpiResid{p.x, p.out}, TIDX); break;
.LBB0_855:
	s_cmp_gt_i32 s94, 6
	s_cselect_b64 s[0:1], -1, 0
	s_cmp_lt_i32 s95, 7
	s_cselect_b64 s[2:3], -1, 0
	s_or_b64 s[0:1], s[0:1], s[2:3]
	s_and_b64 vcc, exec, s[0:1]
	s_cbranch_vccnz .LBB0_883
	s_add_u32 s0, s92, 0x7800000
	s_load_dword s12, s[74:75], 0x180
	s_addc_u32 s1, s93, 0
	s_add_u32 s6, s92, 0xe800000
	s_addc_u32 s7, s93, 0
	s_add_u32 s2, s92, 0x8c0000
	s_addc_u32 s3, s93, 0
	s_and_b32 s8, s72, 0xffffffc0
	v_mbcnt_hi_u32_b32 v195, -1, v194
	s_waitcnt lgkmcnt(0)
	s_and_b32 s10, s12, 7
	s_cmp_lg_u32 s10, 0
	s_waitcnt vmcnt(16)
	v_add_u32_e32 v196, s8, v195
	v_mbcnt_lo_u32_b32 v240, -1, 0
	v_mbcnt_hi_u32_b32 v240, -1, v240
	s_lshr_b32 s20, s72, 6
	s_lshl_b32 s13, s20, 10
	v_and_b32_e32 v241, 15, v240
	v_lshrrev_b32_e32 v242, 4, v240
	v_bfe_u32 v243, v240, 3, 1
	v_mul_u32_u24_e32 v243, 3, v243
	v_xor_b32_e32 v243, v242, v243
	v_lshlrev_b32_e32 v243, 4, v243
	v_lshl_add_u32 v243, v241, 6, v243
	s_lshr_b32 s19, s20, 1
	s_lshl_b32 s19, s19, 13
	v_add_u32_e32 v230, s19, v243
	s_and_b32 s19, s20, 1
	s_lshl_b32 s19, s19, 12
	s_add_u32 s19, s19, 16384
	v_add_u32_e32 v231, s19, v243
	s_lshr_b32 s19, s20, 1
	s_lshl_b32 s19, s19, 7
	v_add_u32_e32 v244, s19, v241
	s_and_b32 s19, s20, 1
	s_lshl_b32 s19, s19, 6
	v_lshl_add_u32 v245, v242, 2, s19
	s_movk_i32 s19, 0x1000
	v_mul_lo_u32 v246, v244, s19
	v_lshl_add_u32 v234, v245, 2, v246
	v_lshrrev_b32_e32 v241, 2, v240
	s_lshl_b32 s19, s20, 4
	v_add_u32_e32 v241, s19, v241
	v_bfe_u32 v242, v240, 5, 1
	v_mul_u32_u24_e32 v242, 3, v242
	v_and_b32_e32 v243, 3, v240
	v_xor_b32_e32 v243, v243, v242
	v_lshlrev_b32_e32 v243, 4, v243
	s_mov_b32 s19, 1024
	v_mad_u32_u24 v224, v241, s19, v243
	v_add_u32_e32 v225, 0x10000, v224
	v_add_u32_e32 v226, 0x20000, v224
	v_add_u32_e32 v227, 0x30000, v224
	s_mov_b32 s19, 5184
	v_mad_u32_u24 v236, v241, s19, v243
	v_add_u32_e32 v237, 0x51000, v236
	v_add_u32_e32 v238, 0xa2000, v236
	v_add_u32_e32 v239, 0xf3000, v236
	v_mov_b32_e32 v248, v224
	v_mov_b32_e32 v249, v225
	v_mov_b32_e32 v250, v226
	v_mov_b32_e32 v251, v227
	s_mov_b32 s19, 3072
	v_mad_u32_u24 v228, v241, s19, v243
	v_add_u32_e32 v229, 0x30000, v228
	s_load_dwordx2 s[6:7], s[74:75], 0x168
	s_load_dwordx2 s[14:15], s[74:75], 0x0
	v_mbcnt_lo_u32_b32 v240, -1, 0
	v_mbcnt_hi_u32_b32 v240, -1, v240
	s_lshr_b32 s20, s72, 6
	s_mul_i32 s19, s20, 17408
	v_and_b32_e32 v241, 15, v240
	v_lshrrev_b32_e32 v242, 4, v240
	v_mul_u32_u24_e32 v243, 0x110, v241
	v_lshl_add_u32 v243, v242, 4, v243
	v_add_u32_e32 v245, s19, v243
	v_mul_u32_u24_e32 v243, 0x110, v242
	v_lshl_add_u32 v243, v241, 4, v243
	v_add_u32_e32 v246, s19, v243
	s_lshr_b32 s19, s20, 1
	s_lshl_b32 s19, s19, 7
	v_add_u32_e32 v243, s19, v242
	v_lshlrev_b32_e32 v243, 12, v243
	s_and_b32 s19, s20, 1
	s_lshl_b32 s19, s19, 8
	v_lshl_add_u32 v244, v241, 4, s19
	v_add_u32_e32 v247, v243, v244
	s_cmpk_gt_u32 s96, 0xff
	s_cbranch_scc0 .Lg6_prio
	s_setprio 1
.Lg6_prio:
	s_lshr_b32 s9, s96, 3
	s_and_b32 s11, s96, 7
	s_lshl_b32 s11, s11, 1
	s_waitcnt lgkmcnt(0)

; #define LWRITE(S, buf) do { bf16_t* sA_ = sbase + (buf) * BUF; bf16_t* sB_ = sA_ + 256 * PITCH; \
;     _Pragma("unroll") for (int i_ = 0; i_ < 4; ++i_) *(u32x4*)(sA_ + (sr + i_ * 64) * PITCH + scv * 8) = ra[S][i_]; \
;     _Pragma("unroll") for (int i_ = 0; i_ < 2; ++i_) *(u32x4*)(sB_ + (sr + i_ * 64) * PITCH + scv * 8) = rb[S][i_]; } while (0)
; template <class Epi>
; DI void gemm_tile(char* smem, const bf16_t* __restrict__ A0, int lda0, int ksplit, const bf16_t* __restrict__ A1, int lda1,
;                   const bf16_t* __restrict__ Bt, int K, int row0, int col0, const Epi& epi, int tid) {
;     ...
;   __syncthreads();
;   {
;     const int last = nk - 1;
;     GLOAD(0, 0);
;     __builtin_amdgcn_sched_barrier(0);
;     GLOAD(1, 1);
;     __builtin_amdgcn_sched_barrier(0);
;     LWRITE(0, 0);
;     __builtin_amdgcn_sched_barrier(0);
;     GLOAD(0, (2 < last ? 2 : last));
;     __builtin_amdgcn_sched_barrier(0);
;     __syncthreads();
;     for (int kt = 0; kt < nk; kt += 2) {
;       LWRITE(1, 1);
;       __builtin_amdgcn_sched_barrier(0);
;       GLOAD(1, (kt + 3 < last ? kt + 3 : last));
;       __builtin_amdgcn_sched_barrier(0);
;       COMPUTE(0);
;       __syncthreads();
;       LWRITE(0, 0);
;       __builtin_amdgcn_sched_barrier(0);
;       GLOAD(0, (kt + 4 < last ? kt + 4 : last));
;       __builtin_amdgcn_sched_barrier(0);
;       COMPUTE(1);
;       __syncthreads();
.Lg6_swb0:
	s_waitcnt vmcnt(6)
	s_waitcnt lgkmcnt(0)
	s_barrier
	v_add_u32_e32 v232, s100, v230
	v_add_u32_e32 v233, s100, v231
	s_add_u32 s19, s99, s13
	s_setprio 1
	v_mfma_f32_16x16x32_bf16 v[0:3], v[128:131], v[144:147], v[0:3]
	v_mfma_f32_16x16x32_bf16 v[4:7], v[132:135], v[144:147], v[4:7]
	v_mfma_f32_16x16x32_bf16 v[8:11], v[136:139], v[144:147], v[8:11]
	v_mfma_f32_16x16x32_bf16 v[12:15], v[140:143], v[144:147], v[12:15]
	ds_read_b128 v[176:179], v233 offset:0
	ds_read_b128 v[180:183], v233 offset:1024
	s_add_u32 m0, s19, 0
	s_nop 0
	global_load_lds_dwordx4 v224, s[0:1]
	v_mfma_f32_16x16x32_bf16 v[16:19], v[128:131], v[148:151], v[16:19]
	v_mfma_f32_16x16x32_bf16 v[20:23], v[132:135], v[148:151], v[20:23]
	v_mfma_f32_16x16x32_bf16 v[24:27], v[136:139], v[148:151], v[24:27]
	v_mfma_f32_16x16x32_bf16 v[28:31], v[140:143], v[148:151], v[28:31]
	ds_read_b128 v[184:187], v233 offset:2048
	ds_read_b128 v[188:191], v233 offset:3072
	s_add_u32 m0, s19, 4096
	s_nop 0
	global_load_lds_dwordx4 v225, s[0:1]
	v_mfma_f32_16x16x32_bf16 v[32:35], v[128:131], v[152:155], v[32:35]
	v_mfma_f32_16x16x32_bf16 v[36:39], v[132:135], v[152:155], v[36:39]
	v_mfma_f32_16x16x32_bf16 v[40:43], v[136:139], v[152:155], v[40:43]
	v_mfma_f32_16x16x32_bf16 v[44:47], v[140:143], v[152:155], v[44:47]
	ds_read_b128 v[192:195], v232 offset:0
	ds_read_b128 v[196:199], v232 offset:1024
	s_add_u32 m0, s19, 8192
	s_nop 0
	global_load_lds_dwordx4 v226, s[0:1]
	v_mfma_f32_16x16x32_bf16 v[48:51], v[128:131], v[156:159], v[48:51]
	v_mfma_f32_16x16x32_bf16 v[52:55], v[132:135], v[156:159], v[52:55]
	v_mfma_f32_16x16x32_bf16 v[56:59], v[136:139], v[156:159], v[56:59]
	v_mfma_f32_16x16x32_bf16 v[60:63], v[140:143], v[156:159], v[60:63]
	ds_read_b128 v[200:203], v232 offset:2048
	ds_read_b128 v[204:207], v232 offset:3072
	s_add_u32 m0, s19, 12288
	s_nop 0
	global_load_lds_dwordx4 v227, s[0:1]
	v_mfma_f32_16x16x32_bf16 v[64:67], v[128:131], v[160:163], v[64:67]
	v_mfma_f32_16x16x32_bf16 v[68:71], v[132:135], v[160:163], v[68:71]
	v_mfma_f32_16x16x32_bf16 v[72:75], v[136:139], v[160:163], v[72:75]
	v_mfma_f32_16x16x32_bf16 v[76:79], v[140:143], v[160:163], v[76:79]
	ds_read_b128 v[208:211], v232 offset:4096
	s_add_u32 m0, s19, 16384
	s_nop 0
	global_load_lds_dwordx4 v228, s[2:3]
	v_mfma_f32_16x16x32_bf16 v[80:83], v[128:131], v[164:167], v[80:83]
	v_mfma_f32_16x16x32_bf16 v[84:87], v[132:135], v[164:167], v[84:87]
	v_mfma_f32_16x16x32_bf16 v[88:91], v[136:139], v[164:167], v[88:91]
	v_mfma_f32_16x16x32_bf16 v[92:95], v[140:143], v[164:167], v[92:95]
	ds_read_b128 v[212:215], v232 offset:5120
	s_add_u32 m0, s19, 20480
	s_nop 0
	global_load_lds_dwordx4 v229, s[2:3]
	v_mfma_f32_16x16x32_bf16 v[96:99], v[128:131], v[168:171], v[96:99]
	v_mfma_f32_16x16x32_bf16 v[100:103], v[132:135], v[168:171], v[100:103]
	v_mfma_f32_16x16x32_bf16 v[104:107], v[136:139], v[168:171], v[104:107]
	v_mfma_f32_16x16x32_bf16 v[108:111], v[140:143], v[168:171], v[108:111]
	ds_read_b128 v[216:219], v232 offset:6144
	s_add_u32 s0, s0, 64
	s_addc_u32 s1, s1, 0
	s_add_u32 s2, s2, 64
	s_addc_u32 s3, s3, 0
	s_add_u32 s22, s22, 1
	s_add_u32 s99, s99, 24576
	s_cmp_eq_u32 s99, 73728
	s_cselect_b32 s99, 0, s99
	s_add_u32 s100, s100, 24576
	s_cmp_eq_u32 s100, 73728
	s_cselect_b32 s100, 0, s100
	v_mfma_f32_16x16x32_bf16 v[112:115], v[128:131], v[172:175], v[112:115]
	v_mfma_f32_16x16x32_bf16 v[116:119], v[132:135], v[172:175], v[116:119]
	v_mfma_f32_16x16x32_bf16 v[120:123], v[136:139], v[172:175], v[120:123]
	v_mfma_f32_16x16x32_bf16 v[124:127], v[140:143], v[172:175], v[124:127]
	ds_read_b128 v[220:223], v232 offset:7168
	s_setprio 0
	s_cmp_eq_u32 s22, 16
	s_cbranch_scc1 .Lg6_sw1
.Lg6_swb1:
	s_waitcnt vmcnt(6)
	s_waitcnt lgkmcnt(0)
	s_barrier
	v_add_u32_e32 v232, s100, v230
	v_add_u32_e32 v233, s100, v231
	s_add_u32 s19, s99, s13
	s_setprio 1
	v_mfma_f32_16x16x32_bf16 v[0:3], v[176:179], v[192:195], v[0:3]
	v_mfma_f32_16x16x32_bf16 v[4:7], v[180:183], v[192:195], v[4:7]
	v_mfma_f32_16x16x32_bf16 v[8:11], v[184:187], v[192:195], v[8:11]
	v_mfma_f32_16x16x32_bf16 v[12:15], v[188:191], v[192:195], v[12:15]
	ds_read_b128 v[128:131], v233 offset:0
	ds_read_b128 v[132:135], v233 offset:1024
	s_add_u32 m0, s19, 0
	s_nop 0
	global_load_lds_dwordx4 v224, s[0:1]
	v_mfma_f32_16x16x32_bf16 v[16:19], v[176:179], v[196:199], v[16:19]
	v_mfma_f32_16x16x32_bf16 v[20:23], v[180:183], v[196:199], v[20:23]
	v_mfma_f32_16x16x32_bf16 v[24:27], v[184:187], v[196:199], v[24:27]
	v_mfma_f32_16x16x32_bf16 v[28:31], v[188:191], v[196:199], v[28:31]
	ds_read_b128 v[136:139], v233 offset:2048
	ds_read_b128 v[140:143], v233 offset:3072
	s_add_u32 m0, s19, 4096
	s_nop 0
	global_load_lds_dwordx4 v225, s[0:1]
	v_mfma_f32_16x16x32_bf16 v[32:35], v[176:179], v[200:203], v[32:35]
	v_mfma_f32_16x16x32_bf16 v[36:39], v[180:183], v[200:203], v[36:39]
	v_mfma_f32_16x16x32_bf16 v[40:43], v[184:187], v[200:203], v[40:43]
	v_mfma_f32_16x16x32_bf16 v[44:47], v[188:191], v[200:203], v[44:47]
	ds_read_b128 v[144:147], v232 offset:0
	ds_read_b128 v[148:151], v232 offset:1024
	s_add_u32 m0, s19, 8192
	s_nop 0
	global_load_lds_dwordx4 v226, s[0:1]
	v_mfma_f32_16x16x32_bf16 v[48:51], v[176:179], v[204:207], v[48:51]
	v_mfma_f32_16x16x32_bf16 v[52:55], v[180:183], v[204:207], v[52:55]
	v_mfma_f32_16x16x32_bf16 v[56:59], v[184:187], v[204:207], v[56:59]
	v_mfma_f32_16x16x32_bf16 v[60:63], v[188:191], v[204:207], v[60:63]
	ds_read_b128 v[152:155], v232 offset:2048
	ds_read_b128 v[156:159], v232 offset:3072
	s_add_u32 m0, s19, 12288
	s_nop 0
	global_load_lds_dwordx4 v227, s[0:1]
	v_mfma_f32_16x16x32_bf16 v[64:67], v[176:179], v[208:211], v[64:67]
; #define LWRITE(S, buf) do { bf16_t* sA_ = sbase + (buf) * BUF; bf16_t* sB_ = sA_ + 256 * PITCH; \
;     _Pragma("unroll") for (int i_ = 0; i_ < 4; ++i_) *(u32x4*)(sA_ + (sr + i_ * 64) * PITCH + scv * 8) = ra[S][i_]; \
;     _Pragma("unroll") for (int i_ = 0; i_ < 2; ++i_) *(u32x4*)(sB_ + (sr + i_ * 64) * PITCH + scv * 8) = rb[S][i_]; } while (0)
; template <class Epi>
; DI void gemm_tile(char* smem, const bf16_t* __restrict__ A0, int lda0, int ksplit, const bf16_t* __restrict__ A1, int lda1,
;                   const bf16_t* __restrict__ Bt, int K, int row0, int col0, const Epi& epi, int tid) {
;     ...
;   __syncthreads();
;   {
;     const int last = nk - 1;
;     GLOAD(0, 0);
;     __builtin_amdgcn_sched_barrier(0);
;     GLOAD(1, 1);
;     __builtin_amdgcn_sched_barrier(0);
;     LWRITE(0, 0);
;     __builtin_amdgcn_sched_barrier(0);
;     GLOAD(0, (2 < last ? 2 : last));
;     __builtin_amdgcn_sched_barrier(0);
;     __syncthreads();
;     for (int kt = 0; kt < nk; kt += 2) {
;       LWRITE(1, 1);
;       __builtin_amdgcn_sched_barrier(0);
;       GLOAD(1, (kt + 3 < last ? kt + 3 : last));
;       __builtin_amdgcn_sched_barrier(0);
;       COMPUTE(0);
;       __syncthreads();
;       LWRITE(0, 0);
;       __builtin_amdgcn_sched_barrier(0);
;       GLOAD(0, (kt + 4 < last ? kt + 4 : last));
;       __builtin_amdgcn_sched_barrier(0);
;       COMPUTE(1);
;       __syncthreads();
	v_mfma_f32_16x16x32_bf16 v[68:71], v[180:183], v[208:211], v[68:71]
	v_mfma_f32_16x16x32_bf16 v[72:75], v[184:187], v[208:211], v[72:75]
	v_mfma_f32_16x16x32_bf16 v[76:79], v[188:191], v[208:211], v[76:79]
	ds_read_b128 v[160:163], v232 offset:4096
	s_add_u32 m0, s19, 16384
	s_nop 0
	global_load_lds_dwordx4 v228, s[2:3]
	v_mfma_f32_16x16x32_bf16 v[80:83], v[176:179], v[212:215], v[80:83]
	v_mfma_f32_16x16x32_bf16 v[84:87], v[180:183], v[212:215], v[84:87]
	v_mfma_f32_16x16x32_bf16 v[88:91], v[184:187], v[212:215], v[88:91]
	v_mfma_f32_16x16x32_bf16 v[92:95], v[188:191], v[212:215], v[92:95]
	ds_read_b128 v[164:167], v232 offset:5120
	s_add_u32 m0, s19, 20480
	s_nop 0
	global_load_lds_dwordx4 v229, s[2:3]
	v_mfma_f32_16x16x32_bf16 v[96:99], v[176:179], v[216:219], v[96:99]
	v_mfma_f32_16x16x32_bf16 v[100:103], v[180:183], v[216:219], v[100:103]
	v_mfma_f32_16x16x32_bf16 v[104:107], v[184:187], v[216:219], v[104:107]
	v_mfma_f32_16x16x32_bf16 v[108:111], v[188:191], v[216:219], v[108:111]
	ds_read_b128 v[168:171], v232 offset:6144
	s_add_u32 s0, s0, 64
	s_addc_u32 s1, s1, 0
	s_add_u32 s2, s2, 64
	s_addc_u32 s3, s3, 0
	s_add_u32 s22, s22, 1
	s_add_u32 s99, s99, 24576
	s_cmp_eq_u32 s99, 73728
	s_cselect_b32 s99, 0, s99
	s_add_u32 s100, s100, 24576
	s_cmp_eq_u32 s100, 73728
	s_cselect_b32 s100, 0, s100
	v_mfma_f32_16x16x32_bf16 v[112:115], v[176:179], v[220:223], v[112:115]
	v_mfma_f32_16x16x32_bf16 v[116:119], v[180:183], v[220:223], v[116:119]
	v_mfma_f32_16x16x32_bf16 v[120:123], v[184:187], v[220:223], v[120:123]
	v_mfma_f32_16x16x32_bf16 v[124:127], v[188:191], v[220:223], v[124:127]
	ds_read_b128 v[172:175], v232 offset:7168
	s_setprio 0
	s_add_u32 s101, s101, 2
	s_cmp_lt_u32 s101, 44
	s_cbranch_scc1 .Lg6_kloop
	s_cmp_eq_u32 s22, 16
	s_cbranch_scc1 .Lg6_sw2
.Lg6_swb2:
	s_waitcnt vmcnt(6)
	s_waitcnt lgkmcnt(0)
	s_barrier
	v_add_u32_e32 v232, s100, v230
	v_add_u32_e32 v233, s100, v231
	s_add_u32 s19, s99, s13
	s_setprio 1
	v_mfma_f32_16x16x32_bf16 v[0:3], v[128:131], v[144:147], v[0:3]
	v_mfma_f32_16x16x32_bf16 v[4:7], v[132:135], v[144:147], v[4:7]
	v_mfma_f32_16x16x32_bf16 v[8:11], v[136:139], v[144:147], v[8:11]
	v_mfma_f32_16x16x32_bf16 v[12:15], v[140:143], v[144:147], v[12:15]
	ds_read_b128 v[176:179], v233 offset:0
	ds_read_b128 v[180:183], v233 offset:1024
	s_add_u32 m0, s19, 0
	s_nop 0
	global_load_lds_dwordx4 v224, s[0:1]
	v_mfma_f32_16x16x32_bf16 v[16:19], v[128:131], v[148:151], v[16:19]
	v_mfma_f32_16x16x32_bf16 v[20:23], v[132:135], v[148:151], v[20:23]
	v_mfma_f32_16x16x32_bf16 v[24:27], v[136:139], v[148:151], v[24:27]
	v_mfma_f32_16x16x32_bf16 v[28:31], v[140:143], v[148:151], v[28:31]
	ds_read_b128 v[184:187], v233 offset:2048
	ds_read_b128 v[188:191], v233 offset:3072
	s_add_u32 m0, s19, 4096
	s_nop 0
	global_load_lds_dwordx4 v225, s[0:1]
	v_mfma_f32_16x16x32_bf16 v[32:35], v[128:131], v[152:155], v[32:35]
	v_mfma_f32_16x16x32_bf16 v[36:39], v[132:135], v[152:155], v[36:39]
	v_mfma_f32_16x16x32_bf16 v[40:43], v[136:139], v[152:155], v[40:43]
	v_mfma_f32_16x16x32_bf16 v[44:47], v[140:143], v[152:155], v[44:47]
	ds_read_b128 v[192:195], v232 offset:0
	ds_read_b128 v[196:199], v232 offset:1024
	s_add_u32 m0, s19, 8192
	s_nop 0
	global_load_lds_dwordx4 v226, s[0:1]
	v_mfma_f32_16x16x32_bf16 v[48:51], v[128:131], v[156:159], v[48:51]
	v_mfma_f32_16x16x32_bf16 v[52:55], v[132:135], v[156:159], v[52:55]
	v_mfma_f32_16x16x32_bf16 v[56:59], v[136:139], v[156:159], v[56:59]
	v_mfma_f32_16x16x32_bf16 v[60:63], v[140:143], v[156:159], v[60:63]
	ds_read_b128 v[200:203], v232 offset:2048
	ds_read_b128 v[204:207], v232 offset:3072
	s_add_u32 m0, s19, 12288
	s_nop 0
	global_load_lds_dwordx4 v227, s[0:1]
	v_mfma_f32_16x16x32_bf16 v[64:67], v[128:131], v[160:163], v[64:67]
	v_mfma_f32_16x16x32_bf16 v[68:71], v[132:135], v[160:163], v[68:71]
	v_mfma_f32_16x16x32_bf16 v[72:75], v[136:139], v[160:163], v[72:75]
	v_mfma_f32_16x16x32_bf16 v[76:79], v[140:143], v[160:163], v[76:79]
	ds_read_b128 v[208:211], v232 offset:4096
	s_add_u32 m0, s19, 16384
	s_nop 0
	global_load_lds_dwordx4 v228, s[2:3]
	v_mfma_f32_16x16x32_bf16 v[80:83], v[128:131], v[164:167], v[80:83]
	v_mfma_f32_16x16x32_bf16 v[84:87], v[132:135], v[164:167], v[84:87]
	v_mfma_f32_16x16x32_bf16 v[88:91], v[136:139], v[164:167], v[88:91]
	v_mfma_f32_16x16x32_bf16 v[92:95], v[140:143], v[164:167], v[92:95]
	ds_read_b128 v[212:215], v232 offset:5120
	s_add_u32 m0, s19, 20480
	s_nop 0
	global_load_lds_dwordx4 v229, s[2:3]
	v_mfma_f32_16x16x32_bf16 v[96:99], v[128:131], v[168:171], v[96:99]
	v_mfma_f32_16x16x32_bf16 v[100:103], v[132:135], v[168:171], v[100:103]
	v_mfma_f32_16x16x32_bf16 v[104:107], v[136:139], v[168:171], v[104:107]
	v_mfma_f32_16x16x32_bf16 v[108:111], v[140:143], v[168:171], v[108:111]
	ds_read_b128 v[216:219], v232 offset:6144
	s_add_u32 s0, s0, 64
	s_addc_u32 s1, s1, 0
	s_add_u32 s2, s2, 64
	s_addc_u32 s3, s3, 0
	s_add_u32 s22, s22, 1
	s_add_u32 s99, s99, 24576
	s_cmp_eq_u32 s99, 73728
	s_cselect_b32 s99, 0, s99
	s_add_u32 s100, s100, 24576
	s_cmp_eq_u32 s100, 73728
	s_cselect_b32 s100, 0, s100
	v_mfma_f32_16x16x32_bf16 v[112:115], v[128:131], v[172:175], v[112:115]
	v_mfma_f32_16x16x32_bf16 v[116:119], v[132:135], v[172:175], v[116:119]
	v_mfma_f32_16x16x32_bf16 v[120:123], v[136:139], v[172:175], v[120:123]
	v_mfma_f32_16x16x32_bf16 v[124:127], v[140:143], v[172:175], v[124:127]
	ds_read_b128 v[220:223], v232 offset:7168
	s_setprio 0
	s_waitcnt vmcnt(6)
	s_waitcnt lgkmcnt(0)
	s_barrier
; #define LWRITE(S, buf) do { bf16_t* sA_ = sbase + (buf) * BUF; bf16_t* sB_ = sA_ + 256 * PITCH; \
;     _Pragma("unroll") for (int i_ = 0; i_ < 4; ++i_) *(u32x4*)(sA_ + (sr + i_ * 64) * PITCH + scv * 8) = ra[S][i_]; \
;     _Pragma("unroll") for (int i_ = 0; i_ < 2; ++i_) *(u32x4*)(sB_ + (sr + i_ * 64) * PITCH + scv * 8) = rb[S][i_]; } while (0)
; template <class Epi>
; DI void gemm_tile(char* smem, const bf16_t* __restrict__ A0, int lda0, int ksplit, const bf16_t* __restrict__ A1, int lda1,
;                   const bf16_t* __restrict__ Bt, int K, int row0, int col0, const Epi& epi, int tid) {
;     ...
;   __syncthreads();
;   {
;     const int last = nk - 1;
;     GLOAD(0, 0);
;     __builtin_amdgcn_sched_barrier(0);
;     GLOAD(1, 1);
;     __builtin_amdgcn_sched_barrier(0);
;     LWRITE(0, 0);
;     __builtin_amdgcn_sched_barrier(0);
;     GLOAD(0, (2 < last ? 2 : last));
;     __builtin_amdgcn_sched_barrier(0);
;     __syncthreads();
;     for (int kt = 0; kt < nk; kt += 2) {
;       LWRITE(1, 1);
;       __builtin_amdgcn_sched_barrier(0);
;       GLOAD(1, (kt + 3 < last ? kt + 3 : last));
;       __builtin_amdgcn_sched_barrier(0);
;       COMPUTE(0);
;       __syncthreads();
;       LWRITE(0, 0);
;       __builtin_amdgcn_sched_barrier(0);
;       GLOAD(0, (kt + 4 < last ? kt + 4 : last));
;       __builtin_amdgcn_sched_barrier(0);
;       COMPUTE(1);
;       __syncthreads();
	v_add_u32_e32 v232, s100, v230
	v_add_u32_e32 v233, s100, v231
	s_setprio 1
	v_mfma_f32_16x16x32_bf16 v[0:3], v[176:179], v[192:195], v[0:3]
	v_mfma_f32_16x16x32_bf16 v[4:7], v[180:183], v[192:195], v[4:7]
	v_mfma_f32_16x16x32_bf16 v[8:11], v[184:187], v[192:195], v[8:11]
	v_mfma_f32_16x16x32_bf16 v[12:15], v[188:191], v[192:195], v[12:15]
	ds_read_b128 v[128:131], v233 offset:0
	ds_read_b128 v[132:135], v233 offset:1024
	v_mfma_f32_16x16x32_bf16 v[16:19], v[176:179], v[196:199], v[16:19]
	v_mfma_f32_16x16x32_bf16 v[20:23], v[180:183], v[196:199], v[20:23]
	v_mfma_f32_16x16x32_bf16 v[24:27], v[184:187], v[196:199], v[24:27]
	v_mfma_f32_16x16x32_bf16 v[28:31], v[188:191], v[196:199], v[28:31]
	ds_read_b128 v[136:139], v233 offset:2048
	ds_read_b128 v[140:143], v233 offset:3072
	v_mfma_f32_16x16x32_bf16 v[32:35], v[176:179], v[200:203], v[32:35]
	v_mfma_f32_16x16x32_bf16 v[36:39], v[180:183], v[200:203], v[36:39]
	v_mfma_f32_16x16x32_bf16 v[40:43], v[184:187], v[200:203], v[40:43]
	v_mfma_f32_16x16x32_bf16 v[44:47], v[188:191], v[200:203], v[44:47]
	ds_read_b128 v[144:147], v232 offset:0
	ds_read_b128 v[148:151], v232 offset:1024
	v_mfma_f32_16x16x32_bf16 v[48:51], v[176:179], v[204:207], v[48:51]
	v_mfma_f32_16x16x32_bf16 v[52:55], v[180:183], v[204:207], v[52:55]
	v_mfma_f32_16x16x32_bf16 v[56:59], v[184:187], v[204:207], v[56:59]
	v_mfma_f32_16x16x32_bf16 v[60:63], v[188:191], v[204:207], v[60:63]
	ds_read_b128 v[152:155], v232 offset:2048
	ds_read_b128 v[156:159], v232 offset:3072
	v_mfma_f32_16x16x32_bf16 v[64:67], v[176:179], v[208:211], v[64:67]
	v_mfma_f32_16x16x32_bf16 v[68:71], v[180:183], v[208:211], v[68:71]
	v_mfma_f32_16x16x32_bf16 v[72:75], v[184:187], v[208:211], v[72:75]
	v_mfma_f32_16x16x32_bf16 v[76:79], v[188:191], v[208:211], v[76:79]
	ds_read_b128 v[160:163], v232 offset:4096
	v_mfma_f32_16x16x32_bf16 v[80:83], v[176:179], v[212:215], v[80:83]
	v_mfma_f32_16x16x32_bf16 v[84:87], v[180:183], v[212:215], v[84:87]
	v_mfma_f32_16x16x32_bf16 v[88:91], v[184:187], v[212:215], v[88:91]
	v_mfma_f32_16x16x32_bf16 v[92:95], v[188:191], v[212:215], v[92:95]
	ds_read_b128 v[164:167], v232 offset:5120
	v_mfma_f32_16x16x32_bf16 v[96:99], v[176:179], v[216:219], v[96:99]
	v_mfma_f32_16x16x32_bf16 v[100:103], v[180:183], v[216:219], v[100:103]
	v_mfma_f32_16x16x32_bf16 v[104:107], v[184:187], v[216:219], v[104:107]
	v_mfma_f32_16x16x32_bf16 v[108:111], v[188:191], v[216:219], v[108:111]
	ds_read_b128 v[168:171], v232 offset:6144
	s_add_u32 s100, s100, 24576
	s_cmp_eq_u32 s100, 73728
	s_cselect_b32 s100, 0, s100
	v_mfma_f32_16x16x32_bf16 v[112:115], v[176:179], v[220:223], v[112:115]
	v_mfma_f32_16x16x32_bf16 v[116:119], v[180:183], v[220:223], v[116:119]
	v_mfma_f32_16x16x32_bf16 v[120:123], v[184:187], v[220:223], v[120:123]
	v_mfma_f32_16x16x32_bf16 v[124:127], v[188:191], v[220:223], v[124:127]
	ds_read_b128 v[172:175], v232 offset:7168
	s_setprio 0
	s_waitcnt vmcnt(0)
	s_waitcnt lgkmcnt(0)
	s_barrier
; #define LWRITE(S, buf) do { bf16_t* sA_ = sbase + (buf) * BUF; bf16_t* sB_ = sA_ + 256 * PITCH; \
;     _Pragma("unroll") for (int i_ = 0; i_ < 4; ++i_) *(u32x4*)(sA_ + (sr + i_ * 64) * PITCH + scv * 8) = ra[S][i_]; \
;     _Pragma("unroll") for (int i_ = 0; i_ < 2; ++i_) *(u32x4*)(sB_ + (sr + i_ * 64) * PITCH + scv * 8) = rb[S][i_]; } while (0)
; template <class Epi>
; DI void gemm_tile(char* smem, const bf16_t* __restrict__ A0, int lda0, int ksplit, const bf16_t* __restrict__ A1, int lda1,
;                   const bf16_t* __restrict__ Bt, int K, int row0, int col0, const Epi& epi, int tid) {
;     ...
;   __syncthreads();
;   {
;     const int last = nk - 1;
;     GLOAD(0, 0);
;     __builtin_amdgcn_sched_barrier(0);
;     GLOAD(1, 1);
;     __builtin_amdgcn_sched_barrier(0);
;     LWRITE(0, 0);
;     __builtin_amdgcn_sched_barrier(0);
;     GLOAD(0, (2 < last ? 2 : last));
;     __builtin_amdgcn_sched_barrier(0);
;     __syncthreads();
;     for (int kt = 0; kt < nk; kt += 2) {
;       LWRITE(1, 1);
;       __builtin_amdgcn_sched_barrier(0);
;       GLOAD(1, (kt + 3 < last ? kt + 3 : last));
;       __builtin_amdgcn_sched_barrier(0);
;       COMPUTE(0);
;       __syncthreads();
;       LWRITE(0, 0);
;       __builtin_amdgcn_sched_barrier(0);
;       GLOAD(0, (kt + 4 < last ? kt + 4 : last));
;       __builtin_amdgcn_sched_barrier(0);
;       COMPUTE(1);
;       __syncthreads();
	v_add_u32_e32 v232, s100, v230
	v_add_u32_e32 v233, s100, v231
	s_setprio 1
	v_mfma_f32_16x16x32_bf16 v[0:3], v[128:131], v[144:147], v[0:3]
	v_mfma_f32_16x16x32_bf16 v[4:7], v[132:135], v[144:147], v[4:7]
	v_mfma_f32_16x16x32_bf16 v[8:11], v[136:139], v[144:147], v[8:11]
	v_mfma_f32_16x16x32_bf16 v[12:15], v[140:143], v[144:147], v[12:15]
	ds_read_b128 v[176:179], v233 offset:0
	ds_read_b128 v[180:183], v233 offset:1024
	v_mfma_f32_16x16x32_bf16 v[16:19], v[128:131], v[148:151], v[16:19]
	v_mfma_f32_16x16x32_bf16 v[20:23], v[132:135], v[148:151], v[20:23]
	v_mfma_f32_16x16x32_bf16 v[24:27], v[136:139], v[148:151], v[24:27]
	v_mfma_f32_16x16x32_bf16 v[28:31], v[140:143], v[148:151], v[28:31]
	ds_read_b128 v[184:187], v233 offset:2048
	ds_read_b128 v[188:191], v233 offset:3072
	v_mfma_f32_16x16x32_bf16 v[32:35], v[128:131], v[152:155], v[32:35]
	v_mfma_f32_16x16x32_bf16 v[36:39], v[132:135], v[152:155], v[36:39]
	v_mfma_f32_16x16x32_bf16 v[40:43], v[136:139], v[152:155], v[40:43]
	v_mfma_f32_16x16x32_bf16 v[44:47], v[140:143], v[152:155], v[44:47]
	ds_read_b128 v[192:195], v232 offset:0
	ds_read_b128 v[196:199], v232 offset:1024
	v_mfma_f32_16x16x32_bf16 v[48:51], v[128:131], v[156:159], v[48:51]
	v_mfma_f32_16x16x32_bf16 v[52:55], v[132:135], v[156:159], v[52:55]
	v_mfma_f32_16x16x32_bf16 v[56:59], v[136:139], v[156:159], v[56:59]
	v_mfma_f32_16x16x32_bf16 v[60:63], v[140:143], v[156:159], v[60:63]
	ds_read_b128 v[200:203], v232 offset:2048
	ds_read_b128 v[204:207], v232 offset:3072
	v_mfma_f32_16x16x32_bf16 v[64:67], v[128:131], v[160:163], v[64:67]
	v_mfma_f32_16x16x32_bf16 v[68:71], v[132:135], v[160:163], v[68:71]
	v_mfma_f32_16x16x32_bf16 v[72:75], v[136:139], v[160:163], v[72:75]
	v_mfma_f32_16x16x32_bf16 v[76:79], v[140:143], v[160:163], v[76:79]
	ds_read_b128 v[208:211], v232 offset:4096
	v_mfma_f32_16x16x32_bf16 v[80:83], v[128:131], v[164:167], v[80:83]
	v_mfma_f32_16x16x32_bf16 v[84:87], v[132:135], v[164:167], v[84:87]
	v_mfma_f32_16x16x32_bf16 v[88:91], v[136:139], v[164:167], v[88:91]
	v_mfma_f32_16x16x32_bf16 v[92:95], v[140:143], v[164:167], v[92:95]
	ds_read_b128 v[212:215], v232 offset:5120
	v_mfma_f32_16x16x32_bf16 v[96:99], v[128:131], v[168:171], v[96:99]
	v_mfma_f32_16x16x32_bf16 v[100:103], v[132:135], v[168:171], v[100:103]
	v_mfma_f32_16x16x32_bf16 v[104:107], v[136:139], v[168:171], v[104:107]
	v_mfma_f32_16x16x32_bf16 v[108:111], v[140:143], v[168:171], v[108:111]
	ds_read_b128 v[216:219], v232 offset:6144
	s_add_u32 s100, s100, 24576
	s_cmp_eq_u32 s100, 73728
	s_cselect_b32 s100, 0, s100
	v_mfma_f32_16x16x32_bf16 v[112:115], v[128:131], v[172:175], v[112:115]
	v_mfma_f32_16x16x32_bf16 v[116:119], v[132:135], v[172:175], v[116:119]
	v_mfma_f32_16x16x32_bf16 v[120:123], v[136:139], v[172:175], v[120:123]
	v_mfma_f32_16x16x32_bf16 v[124:127], v[140:143], v[172:175], v[124:127]
	ds_read_b128 v[220:223], v232 offset:7168
	s_setprio 0
	s_waitcnt lgkmcnt(0)
	s_barrier
	s_setprio 1
	v_mfma_f32_16x16x32_bf16 v[0:3], v[176:179], v[192:195], v[0:3]
	v_mfma_f32_16x16x32_bf16 v[4:7], v[180:183], v[192:195], v[4:7]
	v_mfma_f32_16x16x32_bf16 v[8:11], v[184:187], v[192:195], v[8:11]
	v_mfma_f32_16x16x32_bf16 v[12:15], v[188:191], v[192:195], v[12:15]
	v_mfma_f32_16x16x32_bf16 v[16:19], v[176:179], v[196:199], v[16:19]
	v_mfma_f32_16x16x32_bf16 v[20:23], v[180:183], v[196:199], v[20:23]
	v_mfma_f32_16x16x32_bf16 v[24:27], v[184:187], v[196:199], v[24:27]
	v_mfma_f32_16x16x32_bf16 v[28:31], v[188:191], v[196:199], v[28:31]
	v_mfma_f32_16x16x32_bf16 v[32:35], v[176:179], v[200:203], v[32:35]
	v_mfma_f32_16x16x32_bf16 v[36:39], v[180:183], v[200:203], v[36:39]
	v_mfma_f32_16x16x32_bf16 v[40:43], v[184:187], v[200:203], v[40:43]
	v_mfma_f32_16x16x32_bf16 v[44:47], v[188:191], v[200:203], v[44:47]
	v_mfma_f32_16x16x32_bf16 v[48:51], v[176:179], v[204:207], v[48:51]
	v_mfma_f32_16x16x32_bf16 v[52:55], v[180:183], v[204:207], v[52:55]
	v_mfma_f32_16x16x32_bf16 v[56:59], v[184:187], v[204:207], v[56:59]
	v_mfma_f32_16x16x32_bf16 v[60:63], v[188:191], v[204:207], v[60:63]
	v_mfma_f32_16x16x32_bf16 v[64:67], v[176:179], v[208:211], v[64:67]
	v_mfma_f32_16x16x32_bf16 v[68:71], v[180:183], v[208:211], v[68:71]
	v_mfma_f32_16x16x32_bf16 v[72:75], v[184:187], v[208:211], v[72:75]
	v_mfma_f32_16x16x32_bf16 v[76:79], v[188:191], v[208:211], v[76:79]
	v_mfma_f32_16x16x32_bf16 v[80:83], v[176:179], v[212:215], v[80:83]
	v_mfma_f32_16x16x32_bf16 v[84:87], v[180:183], v[212:215], v[84:87]
	v_mfma_f32_16x16x32_bf16 v[88:91], v[184:187], v[212:215], v[88:91]
	v_mfma_f32_16x16x32_bf16 v[92:95], v[188:191], v[212:215], v[92:95]
	v_mfma_f32_16x16x32_bf16 v[96:99], v[176:179], v[216:219], v[96:99]
	v_mfma_f32_16x16x32_bf16 v[100:103], v[180:183], v[216:219], v[100:103]
	v_mfma_f32_16x16x32_bf16 v[104:107], v[184:187], v[216:219], v[104:107]
	v_mfma_f32_16x16x32_bf16 v[108:111], v[188:191], v[216:219], v[108:111]
	v_mfma_f32_16x16x32_bf16 v[112:115], v[176:179], v[220:223], v[112:115]
	v_mfma_f32_16x16x32_bf16 v[116:119], v[180:183], v[220:223], v[116:119]
	v_mfma_f32_16x16x32_bf16 v[120:123], v[184:187], v[220:223], v[120:123]
	v_mfma_f32_16x16x32_bf16 v[124:127], v[188:191], v[220:223], v[124:127]
	s_setprio 0
	s_branch .Lg6_epi

; #define PH(k) case k: if (ONLY_PHASE >= 0 && ONLY_PHASE != k) break;
; template <class Epi>
; DI void gemm_phase(char* smem, const bf16_t* A0, int lda0, int ksplit, const bf16_t* A1, int lda1, const bf16_t* Bt, int K, int nN, const Epi& epi, int tid) {
;   const int G = gridDim.x;
;   if ((G & 7) == 0) {
;     const int x = blockIdx.x & 7, l = blockIdx.x >> 3, L = G >> 3, per = 8 * nN, tot = 2 * per;
;     for (int q = l; q < tot; q += L) { const int rgl = q / per, rem = q % per, ct = rem >> 3, rt = (x * 2 + rgl) * 8 + (rem & 7);
;       gemm_tile(smem, A0, lda0, ksplit, A1, lda1, Bt, K, rt * 256, ct * 128, epi, tid); }
; template <int ph> DI void run_phase(const Ctx& c, char* smem) {
;     ...
;     PH(8) gemm_phase(smem, XN, 1024, 1 << 30, XN, 1024, (const bf16_t*)(ws + OFF_W1), 1024, 32, EpiRelu2{(bf16_t*)(ws + OFF_R1)}, TIDX); break;
.LBB0_901:
	s_cmp_gt_i32 s94, 8
	s_cselect_b64 s[0:1], -1, 0
	s_cmp_lt_i32 s95, 9
	s_cselect_b64 s[2:3], -1, 0
	s_or_b64 s[0:1], s[0:1], s[2:3]
	s_and_b64 vcc, exec, s[0:1]
	s_cbranch_vccnz .LBB0_929
	s_add_u32 s2, s92, 0x3800000
	s_waitcnt lgkmcnt(0)
	s_load_dword s14, s[74:75], 0x180
	s_addc_u32 s3, s93, 0
	s_add_u32 s4, s92, 0xbc0000
	s_addc_u32 s5, s93, 0
	s_add_u32 s0, s92, 0x7800000
	s_addc_u32 s1, s93, 0
	s_and_b32 s16, s72, 0xffffffc0
	v_mbcnt_hi_u32_b32 v195, -1, v194
	s_waitcnt lgkmcnt(0)
	s_and_b32 s15, s14, 7
	s_cmp_lg_u32 s15, 0
	s_waitcnt vmcnt(16)
	v_add_u32_e32 v196, s16, v195
	v_mbcnt_lo_u32_b32 v240, -1, 0
	v_mbcnt_hi_u32_b32 v240, -1, v240
	s_lshr_b32 s12, s72, 6
	s_lshl_b32 s101, s12, 10
	v_and_b32_e32 v241, 15, v240
	v_lshrrev_b32_e32 v242, 4, v240
	v_bfe_u32 v243, v240, 3, 1
	v_mul_u32_u24_e32 v243, 3, v243
	v_xor_b32_e32 v243, v242, v243
	v_lshlrev_b32_e32 v243, 4, v243
	v_lshl_add_u32 v243, v241, 6, v243
	s_lshr_b32 s11, s12, 1
	s_lshl_b32 s11, s11, 13
	v_add_u32_e32 v230, s11, v243
	s_and_b32 s11, s12, 1
	s_lshl_b32 s11, s11, 12
	s_add_u32 s11, s11, 16384
	v_add_u32_e32 v231, s11, v243
	s_lshr_b32 s11, s12, 1
	s_lshl_b32 s11, s11, 7
	v_add_u32_e32 v244, s11, v241
	s_and_b32 s11, s12, 1
	s_lshl_b32 s11, s11, 6
	v_lshl_add_u32 v245, v242, 2, s11
	s_movk_i32 s11, 0x2000
	v_mul_lo_u32 v246, v244, s11
	v_lshl_add_u32 v234, v245, 1, v246
	s_mul_i32 s11, s12, 18432
	v_mul_u32_u24_e32 v246, 144, v241
	v_lshl_add_u32 v246, v242, 3, v246
	v_add_u32_e32 v236, s11, v246
	v_lshrrev_b32_e32 v246, 3, v240
	v_mul_u32_u24_e32 v246, 144, v246
	v_and_b32_e32 v247, 7, v240
	v_lshl_add_u32 v246, v247, 4, v246
	v_add_u32_e32 v237, s11, v246
	s_lshr_b32 s11, s12, 1
	s_lshl_b32 s11, s11, 7
	v_lshrrev_b32_e32 v246, 3, v240
	v_add_u32_e32 v246, s11, v246
	s_and_b32 s11, s12, 1
	s_lshl_b32 s11, s11, 6
	v_lshl_add_u32 v248, v247, 3, s11
	s_movk_i32 s11, 8192
	v_mul_lo_u32 v247, v246, s11
	v_lshl_add_u32 v238, v248, 1, v247
	v_lshrrev_b32_e32 v241, 2, v240
	s_lshl_b32 s11, s12, 4
	v_add_u32_e32 v241, s11, v241
	v_bfe_u32 v242, v240, 5, 1
	v_mul_u32_u24_e32 v242, 3, v242
	v_and_b32_e32 v243, 3, v240
	v_xor_b32_e32 v243, v243, v242
	v_lshlrev_b32_e32 v243, 4, v243
	s_mov_b32 s11, 2048
	v_mad_u32_u24 v224, v241, s11, v243
	v_add_u32_e32 v225, 0x20000, v224
	v_add_u32_e32 v226, 0x40000, v224
	v_add_u32_e32 v227, 0x60000, v224
	s_mov_b32 s11, 2048
	v_mad_u32_u24 v228, v241, s11, v243
	v_add_u32_e32 v229, 0x20000, v228
	s_cmpk_gt_u32 s96, 0xff
	s_cbranch_scc0 .Lg8_prio
	s_setprio 1
.Lg8_prio:
	s_lshr_b32 s17, s96, 3
	s_and_b32 s20, s96, 7
	s_lshl_b32 s20, s20, 1
	s_waitcnt lgkmcnt(0)

; #define LWRITE(S, buf) do { bf16_t* sA_ = sbase + (buf) * BUF; bf16_t* sB_ = sA_ + 256 * PITCH; \
;     _Pragma("unroll") for (int i_ = 0; i_ < 4; ++i_) *(u32x4*)(sA_ + (sr + i_ * 64) * PITCH + scv * 8) = ra[S][i_]; \
;     _Pragma("unroll") for (int i_ = 0; i_ < 2; ++i_) *(u32x4*)(sB_ + (sr + i_ * 64) * PITCH + scv * 8) = rb[S][i_]; } while (0)
; template <class Epi>
; DI void gemm_tile(char* smem, const bf16_t* __restrict__ A0, int lda0, int ksplit, const bf16_t* __restrict__ A1, int lda1,
;                   const bf16_t* __restrict__ Bt, int K, int row0, int col0, const Epi& epi, int tid) {
;     ...
;   __syncthreads();
;   {
;     const int last = nk - 1;
;     GLOAD(0, 0);
;     __builtin_amdgcn_sched_barrier(0);
;     GLOAD(1, 1);
;     __builtin_amdgcn_sched_barrier(0);
;     LWRITE(0, 0);
;     __builtin_amdgcn_sched_barrier(0);
;     GLOAD(0, (2 < last ? 2 : last));
;     __builtin_amdgcn_sched_barrier(0);
;     __syncthreads();
;     for (int kt = 0; kt < nk; kt += 2) {
;       LWRITE(1, 1);
;       __builtin_amdgcn_sched_barrier(0);
;       GLOAD(1, (kt + 3 < last ? kt + 3 : last));
;       __builtin_amdgcn_sched_barrier(0);
;       COMPUTE(0);
;       __syncthreads();
;       LWRITE(0, 0);
;       __builtin_amdgcn_sched_barrier(0);
;       GLOAD(0, (kt + 4 < last ? kt + 4 : last));
;       __builtin_amdgcn_sched_barrier(0);
;       COMPUTE(1);
;       __syncthreads();
.Lg8_kloop:
	s_waitcnt vmcnt(6)
	s_waitcnt lgkmcnt(0)
	s_barrier
	v_add_u32_e32 v232, s98, v230
	v_add_u32_e32 v233, s98, v231
	s_add_u32 s11, s19, s101
	s_setprio 1
	v_mfma_f32_16x16x32_bf16 v[0:3], v[128:131], v[144:147], v[0:3]
	v_mfma_f32_16x16x32_bf16 v[4:7], v[132:135], v[144:147], v[4:7]
	v_mfma_f32_16x16x32_bf16 v[8:11], v[136:139], v[144:147], v[8:11]
	v_mfma_f32_16x16x32_bf16 v[12:15], v[140:143], v[144:147], v[12:15]
	ds_read_b128 v[176:179], v233 offset:0
	ds_read_b128 v[180:183], v233 offset:1024
	s_add_u32 m0, s11, 0
	s_nop 0
	global_load_lds_dwordx4 v224, s[0:1]
	v_mfma_f32_16x16x32_bf16 v[16:19], v[128:131], v[148:151], v[16:19]
	v_mfma_f32_16x16x32_bf16 v[20:23], v[132:135], v[148:151], v[20:23]
	v_mfma_f32_16x16x32_bf16 v[24:27], v[136:139], v[148:151], v[24:27]
	v_mfma_f32_16x16x32_bf16 v[28:31], v[140:143], v[148:151], v[28:31]
	ds_read_b128 v[184:187], v233 offset:2048
	ds_read_b128 v[188:191], v233 offset:3072
	s_add_u32 m0, s11, 4096
	s_nop 0
	global_load_lds_dwordx4 v225, s[0:1]
	v_mfma_f32_16x16x32_bf16 v[32:35], v[128:131], v[152:155], v[32:35]
	v_mfma_f32_16x16x32_bf16 v[36:39], v[132:135], v[152:155], v[36:39]
	v_mfma_f32_16x16x32_bf16 v[40:43], v[136:139], v[152:155], v[40:43]
	v_mfma_f32_16x16x32_bf16 v[44:47], v[140:143], v[152:155], v[44:47]
	ds_read_b128 v[192:195], v232 offset:0
	ds_read_b128 v[196:199], v232 offset:1024
	s_add_u32 m0, s11, 8192
	s_nop 0
	global_load_lds_dwordx4 v226, s[0:1]
	v_mfma_f32_16x16x32_bf16 v[48:51], v[128:131], v[156:159], v[48:51]
	v_mfma_f32_16x16x32_bf16 v[52:55], v[132:135], v[156:159], v[52:55]
	v_mfma_f32_16x16x32_bf16 v[56:59], v[136:139], v[156:159], v[56:59]
	v_mfma_f32_16x16x32_bf16 v[60:63], v[140:143], v[156:159], v[60:63]
	ds_read_b128 v[200:203], v232 offset:2048
	ds_read_b128 v[204:207], v232 offset:3072
	s_add_u32 m0, s11, 12288
	s_nop 0
	global_load_lds_dwordx4 v227, s[0:1]
	v_mfma_f32_16x16x32_bf16 v[64:67], v[128:131], v[160:163], v[64:67]
	v_mfma_f32_16x16x32_bf16 v[68:71], v[132:135], v[160:163], v[68:71]
	v_mfma_f32_16x16x32_bf16 v[72:75], v[136:139], v[160:163], v[72:75]
	v_mfma_f32_16x16x32_bf16 v[76:79], v[140:143], v[160:163], v[76:79]
	ds_read_b128 v[208:211], v232 offset:4096
	s_add_u32 m0, s11, 16384
	s_nop 0
	global_load_lds_dwordx4 v228, s[2:3]
	v_mfma_f32_16x16x32_bf16 v[80:83], v[128:131], v[164:167], v[80:83]
	v_mfma_f32_16x16x32_bf16 v[84:87], v[132:135], v[164:167], v[84:87]
	v_mfma_f32_16x16x32_bf16 v[88:91], v[136:139], v[164:167], v[88:91]
	v_mfma_f32_16x16x32_bf16 v[92:95], v[140:143], v[164:167], v[92:95]
	ds_read_b128 v[212:215], v232 offset:5120
	s_add_u32 m0, s11, 20480
	s_nop 0
	global_load_lds_dwordx4 v229, s[2:3]
	v_mfma_f32_16x16x32_bf16 v[96:99], v[128:131], v[168:171], v[96:99]
	v_mfma_f32_16x16x32_bf16 v[100:103], v[132:135], v[168:171], v[100:103]
	v_mfma_f32_16x16x32_bf16 v[104:107], v[136:139], v[168:171], v[104:107]
	v_mfma_f32_16x16x32_bf16 v[108:111], v[140:143], v[168:171], v[108:111]
	ds_read_b128 v[216:219], v232 offset:6144
	s_add_u32 s0, s0, 64
	s_addc_u32 s1, s1, 0
	s_add_u32 s2, s2, 64
	s_addc_u32 s3, s3, 0
	s_add_u32 s100, s100, 1
	s_add_u32 s19, s19, 24576
	s_cmp_eq_u32 s19, 73728
	s_cselect_b32 s19, 0, s19
	s_add_u32 s98, s98, 24576
	s_cmp_eq_u32 s98, 73728
	s_cselect_b32 s98, 0, s98
	v_mfma_f32_16x16x32_bf16 v[112:115], v[128:131], v[172:175], v[112:115]
	v_mfma_f32_16x16x32_bf16 v[116:119], v[132:135], v[172:175], v[116:119]
	v_mfma_f32_16x16x32_bf16 v[120:123], v[136:139], v[172:175], v[120:123]
	v_mfma_f32_16x16x32_bf16 v[124:127], v[140:143], v[172:175], v[124:127]
	ds_read_b128 v[220:223], v232 offset:7168
	s_setprio 0
	s_waitcnt vmcnt(6)
	s_waitcnt lgkmcnt(0)
	s_barrier
	v_add_u32_e32 v232, s98, v230
	v_add_u32_e32 v233, s98, v231
	s_add_u32 s11, s19, s101
	s_setprio 1
	v_mfma_f32_16x16x32_bf16 v[0:3], v[176:179], v[192:195], v[0:3]
	v_mfma_f32_16x16x32_bf16 v[4:7], v[180:183], v[192:195], v[4:7]
	v_mfma_f32_16x16x32_bf16 v[8:11], v[184:187], v[192:195], v[8:11]
	v_mfma_f32_16x16x32_bf16 v[12:15], v[188:191], v[192:195], v[12:15]
	ds_read_b128 v[128:131], v233 offset:0
	ds_read_b128 v[132:135], v233 offset:1024
	s_add_u32 m0, s11, 0
	s_nop 0
	global_load_lds_dwordx4 v224, s[0:1]
	v_mfma_f32_16x16x32_bf16 v[16:19], v[176:179], v[196:199], v[16:19]
	v_mfma_f32_16x16x32_bf16 v[20:23], v[180:183], v[196:199], v[20:23]
	v_mfma_f32_16x16x32_bf16 v[24:27], v[184:187], v[196:199], v[24:27]
	v_mfma_f32_16x16x32_bf16 v[28:31], v[188:191], v[196:199], v[28:31]
	ds_read_b128 v[136:139], v233 offset:2048
	ds_read_b128 v[140:143], v233 offset:3072
	s_add_u32 m0, s11, 4096
	s_nop 0
	global_load_lds_dwordx4 v225, s[0:1]
	v_mfma_f32_16x16x32_bf16 v[32:35], v[176:179], v[200:203], v[32:35]
	v_mfma_f32_16x16x32_bf16 v[36:39], v[180:183], v[200:203], v[36:39]
	v_mfma_f32_16x16x32_bf16 v[40:43], v[184:187], v[200:203], v[40:43]
	v_mfma_f32_16x16x32_bf16 v[44:47], v[188:191], v[200:203], v[44:47]
	ds_read_b128 v[144:147], v232 offset:0
	ds_read_b128 v[148:151], v232 offset:1024
	s_add_u32 m0, s11, 8192
	s_nop 0
	global_load_lds_dwordx4 v226, s[0:1]
	v_mfma_f32_16x16x32_bf16 v[48:51], v[176:179], v[204:207], v[48:51]
	v_mfma_f32_16x16x32_bf16 v[52:55], v[180:183], v[204:207], v[52:55]
	v_mfma_f32_16x16x32_bf16 v[56:59], v[184:187], v[204:207], v[56:59]
	v_mfma_f32_16x16x32_bf16 v[60:63], v[188:191], v[204:207], v[60:63]
	ds_read_b128 v[152:155], v232 offset:2048
	ds_read_b128 v[156:159], v232 offset:3072
	s_add_u32 m0, s11, 12288
	s_nop 0
	global_load_lds_dwordx4 v227, s[0:1]
	v_mfma_f32_16x16x32_bf16 v[64:67], v[176:179], v[208:211], v[64:67]
	v_mfma_f32_16x16x32_bf16 v[68:71], v[180:183], v[208:211], v[68:71]
; #define LWRITE(S, buf) do { bf16_t* sA_ = sbase + (buf) * BUF; bf16_t* sB_ = sA_ + 256 * PITCH; \
;     _Pragma("unroll") for (int i_ = 0; i_ < 4; ++i_) *(u32x4*)(sA_ + (sr + i_ * 64) * PITCH + scv * 8) = ra[S][i_]; \
;     _Pragma("unroll") for (int i_ = 0; i_ < 2; ++i_) *(u32x4*)(sB_ + (sr + i_ * 64) * PITCH + scv * 8) = rb[S][i_]; } while (0)
; template <class Epi>
; DI void gemm_tile(char* smem, const bf16_t* __restrict__ A0, int lda0, int ksplit, const bf16_t* __restrict__ A1, int lda1,
;                   const bf16_t* __restrict__ Bt, int K, int row0, int col0, const Epi& epi, int tid) {
;     ...
;   __syncthreads();
;   {
;     const int last = nk - 1;
;     GLOAD(0, 0);
;     __builtin_amdgcn_sched_barrier(0);
;     GLOAD(1, 1);
;     __builtin_amdgcn_sched_barrier(0);
;     LWRITE(0, 0);
;     __builtin_amdgcn_sched_barrier(0);
;     GLOAD(0, (2 < last ? 2 : last));
;     __builtin_amdgcn_sched_barrier(0);
;     __syncthreads();
;     for (int kt = 0; kt < nk; kt += 2) {
;       LWRITE(1, 1);
;       __builtin_amdgcn_sched_barrier(0);
;       GLOAD(1, (kt + 3 < last ? kt + 3 : last));
;       __builtin_amdgcn_sched_barrier(0);
;       COMPUTE(0);
;       __syncthreads();
;       LWRITE(0, 0);
;       __builtin_amdgcn_sched_barrier(0);
;       GLOAD(0, (kt + 4 < last ? kt + 4 : last));
;       __builtin_amdgcn_sched_barrier(0);
;       COMPUTE(1);
;       __syncthreads();
	v_mfma_f32_16x16x32_bf16 v[72:75], v[184:187], v[208:211], v[72:75]
	v_mfma_f32_16x16x32_bf16 v[76:79], v[188:191], v[208:211], v[76:79]
	ds_read_b128 v[160:163], v232 offset:4096
	s_add_u32 m0, s11, 16384
	s_nop 0
	global_load_lds_dwordx4 v228, s[2:3]
	v_mfma_f32_16x16x32_bf16 v[80:83], v[176:179], v[212:215], v[80:83]
	v_mfma_f32_16x16x32_bf16 v[84:87], v[180:183], v[212:215], v[84:87]
	v_mfma_f32_16x16x32_bf16 v[88:91], v[184:187], v[212:215], v[88:91]
	v_mfma_f32_16x16x32_bf16 v[92:95], v[188:191], v[212:215], v[92:95]
	ds_read_b128 v[164:167], v232 offset:5120
	s_add_u32 m0, s11, 20480
	s_nop 0
	global_load_lds_dwordx4 v229, s[2:3]
	v_mfma_f32_16x16x32_bf16 v[96:99], v[176:179], v[216:219], v[96:99]
	v_mfma_f32_16x16x32_bf16 v[100:103], v[180:183], v[216:219], v[100:103]
	v_mfma_f32_16x16x32_bf16 v[104:107], v[184:187], v[216:219], v[104:107]
	v_mfma_f32_16x16x32_bf16 v[108:111], v[188:191], v[216:219], v[108:111]
	ds_read_b128 v[168:171], v232 offset:6144
	s_add_u32 s0, s0, 64
	s_addc_u32 s1, s1, 0
	s_add_u32 s2, s2, 64
	s_addc_u32 s3, s3, 0
	s_add_u32 s100, s100, 1
	s_add_u32 s19, s19, 24576
	s_cmp_eq_u32 s19, 73728
	s_cselect_b32 s19, 0, s19
	s_add_u32 s98, s98, 24576
	s_cmp_eq_u32 s98, 73728
	s_cselect_b32 s98, 0, s98
	v_mfma_f32_16x16x32_bf16 v[112:115], v[176:179], v[220:223], v[112:115]
	v_mfma_f32_16x16x32_bf16 v[116:119], v[180:183], v[220:223], v[116:119]
	v_mfma_f32_16x16x32_bf16 v[120:123], v[184:187], v[220:223], v[120:123]
	v_mfma_f32_16x16x32_bf16 v[124:127], v[188:191], v[220:223], v[124:127]
	ds_read_b128 v[172:175], v232 offset:7168
	s_setprio 0
	s_add_u32 s99, s99, 2
	s_cmp_lt_u32 s99, 28
	s_cbranch_scc1 .Lg8_kloop
	s_waitcnt vmcnt(6)
	s_waitcnt lgkmcnt(0)
	s_barrier
	v_add_u32_e32 v232, s98, v230
	v_add_u32_e32 v233, s98, v231
	s_add_u32 s11, s19, s101
	s_setprio 1
	v_mfma_f32_16x16x32_bf16 v[0:3], v[128:131], v[144:147], v[0:3]
	v_mfma_f32_16x16x32_bf16 v[4:7], v[132:135], v[144:147], v[4:7]
	v_mfma_f32_16x16x32_bf16 v[8:11], v[136:139], v[144:147], v[8:11]
	v_mfma_f32_16x16x32_bf16 v[12:15], v[140:143], v[144:147], v[12:15]
	ds_read_b128 v[176:179], v233 offset:0
	ds_read_b128 v[180:183], v233 offset:1024
	s_add_u32 m0, s11, 0
	s_nop 0
	global_load_lds_dwordx4 v224, s[0:1]
	v_mfma_f32_16x16x32_bf16 v[16:19], v[128:131], v[148:151], v[16:19]
	v_mfma_f32_16x16x32_bf16 v[20:23], v[132:135], v[148:151], v[20:23]
	v_mfma_f32_16x16x32_bf16 v[24:27], v[136:139], v[148:151], v[24:27]
	v_mfma_f32_16x16x32_bf16 v[28:31], v[140:143], v[148:151], v[28:31]
	ds_read_b128 v[184:187], v233 offset:2048
	ds_read_b128 v[188:191], v233 offset:3072
	s_add_u32 m0, s11, 4096
	s_nop 0
	global_load_lds_dwordx4 v225, s[0:1]
	v_mfma_f32_16x16x32_bf16 v[32:35], v[128:131], v[152:155], v[32:35]
	v_mfma_f32_16x16x32_bf16 v[36:39], v[132:135], v[152:155], v[36:39]
	v_mfma_f32_16x16x32_bf16 v[40:43], v[136:139], v[152:155], v[40:43]
	v_mfma_f32_16x16x32_bf16 v[44:47], v[140:143], v[152:155], v[44:47]
	ds_read_b128 v[192:195], v232 offset:0
	ds_read_b128 v[196:199], v232 offset:1024
	s_add_u32 m0, s11, 8192
	s_nop 0
	global_load_lds_dwordx4 v226, s[0:1]
	v_mfma_f32_16x16x32_bf16 v[48:51], v[128:131], v[156:159], v[48:51]
	v_mfma_f32_16x16x32_bf16 v[52:55], v[132:135], v[156:159], v[52:55]
	v_mfma_f32_16x16x32_bf16 v[56:59], v[136:139], v[156:159], v[56:59]
	v_mfma_f32_16x16x32_bf16 v[60:63], v[140:143], v[156:159], v[60:63]
	ds_read_b128 v[200:203], v232 offset:2048
	ds_read_b128 v[204:207], v232 offset:3072
	s_add_u32 m0, s11, 12288
	s_nop 0
	global_load_lds_dwordx4 v227, s[0:1]
	v_mfma_f32_16x16x32_bf16 v[64:67], v[128:131], v[160:163], v[64:67]
	v_mfma_f32_16x16x32_bf16 v[68:71], v[132:135], v[160:163], v[68:71]
	v_mfma_f32_16x16x32_bf16 v[72:75], v[136:139], v[160:163], v[72:75]
	v_mfma_f32_16x16x32_bf16 v[76:79], v[140:143], v[160:163], v[76:79]
	ds_read_b128 v[208:211], v232 offset:4096
	s_add_u32 m0, s11, 16384
	s_nop 0
	global_load_lds_dwordx4 v228, s[2:3]
	v_mfma_f32_16x16x32_bf16 v[80:83], v[128:131], v[164:167], v[80:83]
	v_mfma_f32_16x16x32_bf16 v[84:87], v[132:135], v[164:167], v[84:87]
	v_mfma_f32_16x16x32_bf16 v[88:91], v[136:139], v[164:167], v[88:91]
	v_mfma_f32_16x16x32_bf16 v[92:95], v[140:143], v[164:167], v[92:95]
	ds_read_b128 v[212:215], v232 offset:5120
	s_add_u32 m0, s11, 20480
	s_nop 0
	global_load_lds_dwordx4 v229, s[2:3]
	v_mfma_f32_16x16x32_bf16 v[96:99], v[128:131], v[168:171], v[96:99]
	v_mfma_f32_16x16x32_bf16 v[100:103], v[132:135], v[168:171], v[100:103]
	v_mfma_f32_16x16x32_bf16 v[104:107], v[136:139], v[168:171], v[104:107]
	v_mfma_f32_16x16x32_bf16 v[108:111], v[140:143], v[168:171], v[108:111]
	ds_read_b128 v[216:219], v232 offset:6144
	s_add_u32 s0, s0, 64
	s_addc_u32 s1, s1, 0
	s_add_u32 s2, s2, 64
	s_addc_u32 s3, s3, 0
	s_add_u32 s100, s100, 1
	s_add_u32 s19, s19, 24576
	s_cmp_eq_u32 s19, 73728
	s_cselect_b32 s19, 0, s19
	s_add_u32 s98, s98, 24576
	s_cmp_eq_u32 s98, 73728
	s_cselect_b32 s98, 0, s98
	v_mfma_f32_16x16x32_bf16 v[112:115], v[128:131], v[172:175], v[112:115]
	v_mfma_f32_16x16x32_bf16 v[116:119], v[132:135], v[172:175], v[116:119]
	v_mfma_f32_16x16x32_bf16 v[120:123], v[136:139], v[172:175], v[120:123]
	v_mfma_f32_16x16x32_bf16 v[124:127], v[140:143], v[172:175], v[124:127]
	ds_read_b128 v[220:223], v232 offset:7168
	s_setprio 0
	s_waitcnt vmcnt(6)
	s_waitcnt lgkmcnt(0)
	s_barrier
; #define LWRITE(S, buf) do { bf16_t* sA_ = sbase + (buf) * BUF; bf16_t* sB_ = sA_ + 256 * PITCH; \
;     _Pragma("unroll") for (int i_ = 0; i_ < 4; ++i_) *(u32x4*)(sA_ + (sr + i_ * 64) * PITCH + scv * 8) = ra[S][i_]; \
;     _Pragma("unroll") for (int i_ = 0; i_ < 2; ++i_) *(u32x4*)(sB_ + (sr + i_ * 64) * PITCH + scv * 8) = rb[S][i_]; } while (0)
; template <class Epi>
; DI void gemm_tile(char* smem, const bf16_t* __restrict__ A0, int lda0, int ksplit, const bf16_t* __restrict__ A1, int lda1,
;                   const bf16_t* __restrict__ Bt, int K, int row0, int col0, const Epi& epi, int tid) {
;     ...
;   __syncthreads();
;   {
;     const int last = nk - 1;
;     GLOAD(0, 0);
;     __builtin_amdgcn_sched_barrier(0);
;     GLOAD(1, 1);
;     __builtin_amdgcn_sched_barrier(0);
;     LWRITE(0, 0);
;     __builtin_amdgcn_sched_barrier(0);
;     GLOAD(0, (2 < last ? 2 : last));
;     __builtin_amdgcn_sched_barrier(0);
;     __syncthreads();
;     for (int kt = 0; kt < nk; kt += 2) {
;       LWRITE(1, 1);
;       __builtin_amdgcn_sched_barrier(0);
;       GLOAD(1, (kt + 3 < last ? kt + 3 : last));
;       __builtin_amdgcn_sched_barrier(0);
;       COMPUTE(0);
;       __syncthreads();
;       LWRITE(0, 0);
;       __builtin_amdgcn_sched_barrier(0);
;       GLOAD(0, (kt + 4 < last ? kt + 4 : last));
;       __builtin_amdgcn_sched_barrier(0);
;       COMPUTE(1);
;       __syncthreads();
	v_add_u32_e32 v232, s98, v230
	v_add_u32_e32 v233, s98, v231
	s_setprio 1
	v_mfma_f32_16x16x32_bf16 v[0:3], v[176:179], v[192:195], v[0:3]
	v_mfma_f32_16x16x32_bf16 v[4:7], v[180:183], v[192:195], v[4:7]
	v_mfma_f32_16x16x32_bf16 v[8:11], v[184:187], v[192:195], v[8:11]
	v_mfma_f32_16x16x32_bf16 v[12:15], v[188:191], v[192:195], v[12:15]
	ds_read_b128 v[128:131], v233 offset:0
	ds_read_b128 v[132:135], v233 offset:1024
	v_mfma_f32_16x16x32_bf16 v[16:19], v[176:179], v[196:199], v[16:19]
	v_mfma_f32_16x16x32_bf16 v[20:23], v[180:183], v[196:199], v[20:23]
	v_mfma_f32_16x16x32_bf16 v[24:27], v[184:187], v[196:199], v[24:27]
	v_mfma_f32_16x16x32_bf16 v[28:31], v[188:191], v[196:199], v[28:31]
	ds_read_b128 v[136:139], v233 offset:2048
	ds_read_b128 v[140:143], v233 offset:3072
	v_mfma_f32_16x16x32_bf16 v[32:35], v[176:179], v[200:203], v[32:35]
	v_mfma_f32_16x16x32_bf16 v[36:39], v[180:183], v[200:203], v[36:39]
	v_mfma_f32_16x16x32_bf16 v[40:43], v[184:187], v[200:203], v[40:43]
	v_mfma_f32_16x16x32_bf16 v[44:47], v[188:191], v[200:203], v[44:47]
	ds_read_b128 v[144:147], v232 offset:0
	ds_read_b128 v[148:151], v232 offset:1024
	v_mfma_f32_16x16x32_bf16 v[48:51], v[176:179], v[204:207], v[48:51]
	v_mfma_f32_16x16x32_bf16 v[52:55], v[180:183], v[204:207], v[52:55]
	v_mfma_f32_16x16x32_bf16 v[56:59], v[184:187], v[204:207], v[56:59]
	v_mfma_f32_16x16x32_bf16 v[60:63], v[188:191], v[204:207], v[60:63]
	ds_read_b128 v[152:155], v232 offset:2048
	ds_read_b128 v[156:159], v232 offset:3072
	v_mfma_f32_16x16x32_bf16 v[64:67], v[176:179], v[208:211], v[64:67]
	v_mfma_f32_16x16x32_bf16 v[68:71], v[180:183], v[208:211], v[68:71]
	v_mfma_f32_16x16x32_bf16 v[72:75], v[184:187], v[208:211], v[72:75]
	v_mfma_f32_16x16x32_bf16 v[76:79], v[188:191], v[208:211], v[76:79]
	ds_read_b128 v[160:163], v232 offset:4096
	v_mfma_f32_16x16x32_bf16 v[80:83], v[176:179], v[212:215], v[80:83]
	v_mfma_f32_16x16x32_bf16 v[84:87], v[180:183], v[212:215], v[84:87]
	v_mfma_f32_16x16x32_bf16 v[88:91], v[184:187], v[212:215], v[88:91]
	v_mfma_f32_16x16x32_bf16 v[92:95], v[188:191], v[212:215], v[92:95]
	ds_read_b128 v[164:167], v232 offset:5120
	v_mfma_f32_16x16x32_bf16 v[96:99], v[176:179], v[216:219], v[96:99]
	v_mfma_f32_16x16x32_bf16 v[100:103], v[180:183], v[216:219], v[100:103]
	v_mfma_f32_16x16x32_bf16 v[104:107], v[184:187], v[216:219], v[104:107]
	v_mfma_f32_16x16x32_bf16 v[108:111], v[188:191], v[216:219], v[108:111]
	ds_read_b128 v[168:171], v232 offset:6144
	s_add_u32 s98, s98, 24576
	s_cmp_eq_u32 s98, 73728
	s_cselect_b32 s98, 0, s98
	v_mfma_f32_16x16x32_bf16 v[112:115], v[176:179], v[220:223], v[112:115]
	v_mfma_f32_16x16x32_bf16 v[116:119], v[180:183], v[220:223], v[116:119]
	v_mfma_f32_16x16x32_bf16 v[120:123], v[184:187], v[220:223], v[120:123]
	v_mfma_f32_16x16x32_bf16 v[124:127], v[188:191], v[220:223], v[124:127]
	ds_read_b128 v[172:175], v232 offset:7168
	s_setprio 0
	s_waitcnt vmcnt(0)
	s_waitcnt lgkmcnt(0)
	s_barrier
; #define LWRITE(S, buf) do { bf16_t* sA_ = sbase + (buf) * BUF; bf16_t* sB_ = sA_ + 256 * PITCH; \
;     _Pragma("unroll") for (int i_ = 0; i_ < 4; ++i_) *(u32x4*)(sA_ + (sr + i_ * 64) * PITCH + scv * 8) = ra[S][i_]; \
;     _Pragma("unroll") for (int i_ = 0; i_ < 2; ++i_) *(u32x4*)(sB_ + (sr + i_ * 64) * PITCH + scv * 8) = rb[S][i_]; } while (0)
; template <class Epi>
; DI void gemm_tile(char* smem, const bf16_t* __restrict__ A0, int lda0, int ksplit, const bf16_t* __restrict__ A1, int lda1,
;                   const bf16_t* __restrict__ Bt, int K, int row0, int col0, const Epi& epi, int tid) {
;     ...
;   __syncthreads();
;   {
;     const int last = nk - 1;
;     GLOAD(0, 0);
;     __builtin_amdgcn_sched_barrier(0);
;     GLOAD(1, 1);
;     __builtin_amdgcn_sched_barrier(0);
;     LWRITE(0, 0);
;     __builtin_amdgcn_sched_barrier(0);
;     GLOAD(0, (2 < last ? 2 : last));
;     __builtin_amdgcn_sched_barrier(0);
;     __syncthreads();
;     for (int kt = 0; kt < nk; kt += 2) {
;       LWRITE(1, 1);
;       __builtin_amdgcn_sched_barrier(0);
;       GLOAD(1, (kt + 3 < last ? kt + 3 : last));
;       __builtin_amdgcn_sched_barrier(0);
;       COMPUTE(0);
;       __syncthreads();
;       LWRITE(0, 0);
;       __builtin_amdgcn_sched_barrier(0);
;       GLOAD(0, (kt + 4 < last ? kt + 4 : last));
;       __builtin_amdgcn_sched_barrier(0);
;       COMPUTE(1);
;       __syncthreads();
	v_add_u32_e32 v232, s98, v230
	v_add_u32_e32 v233, s98, v231
	s_setprio 1
	v_mfma_f32_16x16x32_bf16 v[0:3], v[128:131], v[144:147], v[0:3]
	v_mfma_f32_16x16x32_bf16 v[4:7], v[132:135], v[144:147], v[4:7]
	v_mfma_f32_16x16x32_bf16 v[8:11], v[136:139], v[144:147], v[8:11]
	v_mfma_f32_16x16x32_bf16 v[12:15], v[140:143], v[144:147], v[12:15]
	ds_read_b128 v[176:179], v233 offset:0
	ds_read_b128 v[180:183], v233 offset:1024
	v_mfma_f32_16x16x32_bf16 v[16:19], v[128:131], v[148:151], v[16:19]
	v_mfma_f32_16x16x32_bf16 v[20:23], v[132:135], v[148:151], v[20:23]
	v_mfma_f32_16x16x32_bf16 v[24:27], v[136:139], v[148:151], v[24:27]
	v_mfma_f32_16x16x32_bf16 v[28:31], v[140:143], v[148:151], v[28:31]
	ds_read_b128 v[184:187], v233 offset:2048
	ds_read_b128 v[188:191], v233 offset:3072
	v_mfma_f32_16x16x32_bf16 v[32:35], v[128:131], v[152:155], v[32:35]
	v_mfma_f32_16x16x32_bf16 v[36:39], v[132:135], v[152:155], v[36:39]
	v_mfma_f32_16x16x32_bf16 v[40:43], v[136:139], v[152:155], v[40:43]
	v_mfma_f32_16x16x32_bf16 v[44:47], v[140:143], v[152:155], v[44:47]
	ds_read_b128 v[192:195], v232 offset:0
	ds_read_b128 v[196:199], v232 offset:1024
	v_mfma_f32_16x16x32_bf16 v[48:51], v[128:131], v[156:159], v[48:51]
	v_mfma_f32_16x16x32_bf16 v[52:55], v[132:135], v[156:159], v[52:55]
	v_mfma_f32_16x16x32_bf16 v[56:59], v[136:139], v[156:159], v[56:59]
	v_mfma_f32_16x16x32_bf16 v[60:63], v[140:143], v[156:159], v[60:63]
	ds_read_b128 v[200:203], v232 offset:2048
	ds_read_b128 v[204:207], v232 offset:3072
	v_mfma_f32_16x16x32_bf16 v[64:67], v[128:131], v[160:163], v[64:67]
	v_mfma_f32_16x16x32_bf16 v[68:71], v[132:135], v[160:163], v[68:71]
	v_mfma_f32_16x16x32_bf16 v[72:75], v[136:139], v[160:163], v[72:75]
	v_mfma_f32_16x16x32_bf16 v[76:79], v[140:143], v[160:163], v[76:79]
	ds_read_b128 v[208:211], v232 offset:4096
	v_mfma_f32_16x16x32_bf16 v[80:83], v[128:131], v[164:167], v[80:83]
	v_mfma_f32_16x16x32_bf16 v[84:87], v[132:135], v[164:167], v[84:87]
	v_mfma_f32_16x16x32_bf16 v[88:91], v[136:139], v[164:167], v[88:91]
	v_mfma_f32_16x16x32_bf16 v[92:95], v[140:143], v[164:167], v[92:95]
	ds_read_b128 v[212:215], v232 offset:5120
	v_mfma_f32_16x16x32_bf16 v[96:99], v[128:131], v[168:171], v[96:99]
	v_mfma_f32_16x16x32_bf16 v[100:103], v[132:135], v[168:171], v[100:103]
	v_mfma_f32_16x16x32_bf16 v[104:107], v[136:139], v[168:171], v[104:107]
	v_mfma_f32_16x16x32_bf16 v[108:111], v[140:143], v[168:171], v[108:111]
	ds_read_b128 v[216:219], v232 offset:6144
	s_add_u32 s98, s98, 24576
	s_cmp_eq_u32 s98, 73728
	s_cselect_b32 s98, 0, s98
	v_mfma_f32_16x16x32_bf16 v[112:115], v[128:131], v[172:175], v[112:115]
	v_mfma_f32_16x16x32_bf16 v[116:119], v[132:135], v[172:175], v[116:119]
	v_mfma_f32_16x16x32_bf16 v[120:123], v[136:139], v[172:175], v[120:123]
	v_mfma_f32_16x16x32_bf16 v[124:127], v[140:143], v[172:175], v[124:127]
	ds_read_b128 v[220:223], v232 offset:7168
	s_setprio 0
	s_waitcnt lgkmcnt(0)
	s_barrier
	s_setprio 1
	v_mfma_f32_16x16x32_bf16 v[0:3], v[176:179], v[192:195], v[0:3]
	v_mfma_f32_16x16x32_bf16 v[4:7], v[180:183], v[192:195], v[4:7]
	v_mfma_f32_16x16x32_bf16 v[8:11], v[184:187], v[192:195], v[8:11]
	v_mfma_f32_16x16x32_bf16 v[12:15], v[188:191], v[192:195], v[12:15]
	v_mfma_f32_16x16x32_bf16 v[16:19], v[176:179], v[196:199], v[16:19]
	v_mfma_f32_16x16x32_bf16 v[20:23], v[180:183], v[196:199], v[20:23]
	v_mfma_f32_16x16x32_bf16 v[24:27], v[184:187], v[196:199], v[24:27]
	v_mfma_f32_16x16x32_bf16 v[28:31], v[188:191], v[196:199], v[28:31]
	v_mfma_f32_16x16x32_bf16 v[32:35], v[176:179], v[200:203], v[32:35]
	v_mfma_f32_16x16x32_bf16 v[36:39], v[180:183], v[200:203], v[36:39]
	v_mfma_f32_16x16x32_bf16 v[40:43], v[184:187], v[200:203], v[40:43]
	v_mfma_f32_16x16x32_bf16 v[44:47], v[188:191], v[200:203], v[44:47]
	v_mfma_f32_16x16x32_bf16 v[48:51], v[176:179], v[204:207], v[48:51]
	v_mfma_f32_16x16x32_bf16 v[52:55], v[180:183], v[204:207], v[52:55]
	v_mfma_f32_16x16x32_bf16 v[56:59], v[184:187], v[204:207], v[56:59]
	v_mfma_f32_16x16x32_bf16 v[60:63], v[188:191], v[204:207], v[60:63]
	v_mfma_f32_16x16x32_bf16 v[64:67], v[176:179], v[208:211], v[64:67]
	v_mfma_f32_16x16x32_bf16 v[68:71], v[180:183], v[208:211], v[68:71]
	v_mfma_f32_16x16x32_bf16 v[72:75], v[184:187], v[208:211], v[72:75]
	v_mfma_f32_16x16x32_bf16 v[76:79], v[188:191], v[208:211], v[76:79]
	v_mfma_f32_16x16x32_bf16 v[80:83], v[176:179], v[212:215], v[80:83]
	v_mfma_f32_16x16x32_bf16 v[84:87], v[180:183], v[212:215], v[84:87]
	v_mfma_f32_16x16x32_bf16 v[88:91], v[184:187], v[212:215], v[88:91]
	v_mfma_f32_16x16x32_bf16 v[92:95], v[188:191], v[212:215], v[92:95]
	v_mfma_f32_16x16x32_bf16 v[96:99], v[176:179], v[216:219], v[96:99]
	v_mfma_f32_16x16x32_bf16 v[100:103], v[180:183], v[216:219], v[100:103]
	v_mfma_f32_16x16x32_bf16 v[104:107], v[184:187], v[216:219], v[104:107]
	v_mfma_f32_16x16x32_bf16 v[108:111], v[188:191], v[216:219], v[108:111]
	v_mfma_f32_16x16x32_bf16 v[112:115], v[176:179], v[220:223], v[112:115]
	v_mfma_f32_16x16x32_bf16 v[116:119], v[180:183], v[220:223], v[116:119]
	v_mfma_f32_16x16x32_bf16 v[120:123], v[184:187], v[220:223], v[120:123]
	v_mfma_f32_16x16x32_bf16 v[124:127], v[188:191], v[220:223], v[124:127]
	s_setprio 0
	s_branch .Lg8_epi

; #define PH(k) case k: if (ONLY_PHASE >= 0 && ONLY_PHASE != k) break;
; template <class Epi>
; DI void gemm_phase(char* smem, const bf16_t* A0, int lda0, int ksplit, const bf16_t* A1, int lda1, const bf16_t* Bt, int K, int nN, const Epi& epi, int tid) {
;   const int G = gridDim.x;
;   if ((G & 7) == 0) {
;     const int x = blockIdx.x & 7, l = blockIdx.x >> 3, L = G >> 3, per = 8 * nN, tot = 2 * per;
;     for (int q = l; q < tot; q += L) { const int rgl = q / per, rem = q % per, ct = rem >> 3, rt = (x * 2 + rgl) * 8 + (rem & 7);
;       gemm_tile(smem, A0, lda0, ksplit, A1, lda1, Bt, K, rt * 256, ct * 128, epi, tid); }
; template <int ph> DI void run_phase(const Ctx& c, char* smem) {
;     ...
;     PH(9) gemm_phase(smem, (const bf16_t*)(ws + OFF_R1), 4096, 1 << 30, XN, 1024, (const bf16_t*)(ws + OFF_W2), 4096, 8, EpiResid{p.out, p.out}, TIDX); break;
.LBB0_929:
	s_cmp_gt_i32 s94, 9
	s_cselect_b64 s[0:1], -1, 0
	s_cmp_lt_i32 s95, 10
	s_cselect_b64 s[2:3], -1, 0
	s_or_b64 s[0:1], s[0:1], s[2:3]
	s_and_b64 vcc, exec, s[0:1]
	s_cbranch_vccnz .LBB0_957
	s_load_dword s12, s[74:75], 0x180
	s_add_u32 s0, s92, 0x7800000
	s_addc_u32 s1, s93, 0
	s_add_u32 s2, s92, 0x1bc0000
	s_addc_u32 s3, s93, 0
	s_waitcnt lgkmcnt(0)
	s_and_b32 s14, s72, 0xffffffc0
	v_mbcnt_hi_u32_b32 v195, -1, v194
	s_and_b32 s13, s12, 7
	s_cmp_lg_u32 s13, 0
	s_waitcnt vmcnt(16)
	v_add_u32_e32 v196, s14, v195
	v_mbcnt_lo_u32_b32 v240, -1, 0
	v_mbcnt_hi_u32_b32 v240, -1, v240
	s_lshr_b32 s10, s72, 6
	s_lshl_b32 s101, s10, 10
	v_and_b32_e32 v241, 15, v240
	v_lshrrev_b32_e32 v242, 4, v240
	v_bfe_u32 v243, v240, 3, 1
	v_mul_u32_u24_e32 v243, 3, v243
	v_xor_b32_e32 v243, v242, v243
	v_lshlrev_b32_e32 v243, 4, v243
	v_lshl_add_u32 v243, v241, 6, v243
	s_lshr_b32 s9, s10, 1
	s_lshl_b32 s9, s9, 13
	v_add_u32_e32 v230, s9, v243
	s_and_b32 s9, s10, 1
	s_lshl_b32 s9, s9, 12
	s_add_u32 s9, s9, 16384
	v_add_u32_e32 v231, s9, v243
	s_lshr_b32 s9, s10, 1
	s_lshl_b32 s9, s9, 7
	v_add_u32_e32 v244, s9, v241
	s_and_b32 s9, s10, 1
	s_lshl_b32 s9, s9, 6
	v_lshl_add_u32 v245, v242, 2, s9
	s_movk_i32 s9, 0x1000
	v_mul_lo_u32 v246, v244, s9
	v_lshl_add_u32 v234, v245, 2, v246
	v_lshrrev_b32_e32 v241, 2, v240
	s_lshl_b32 s9, s10, 4
	v_add_u32_e32 v241, s9, v241
	v_bfe_u32 v242, v240, 5, 1
	v_mul_u32_u24_e32 v242, 3, v242
	v_and_b32_e32 v243, 3, v240
	v_xor_b32_e32 v243, v243, v242
	v_lshlrev_b32_e32 v243, 4, v243
	s_mov_b32 s9, 8192
	v_mad_u32_u24 v224, v241, s9, v243
	v_add_u32_e32 v225, 0x80000, v224
	v_add_u32_e32 v226, 0x100000, v224
	v_add_u32_e32 v227, 0x180000, v224
	s_mov_b32 s9, 8192
	v_mad_u32_u24 v228, v241, s9, v243
	v_add_u32_e32 v229, 0x80000, v228
	s_load_dwordx2 s[6:7], s[74:75], 0x168
	v_mbcnt_lo_u32_b32 v240, -1, 0
	v_mbcnt_hi_u32_b32 v240, -1, v240
	s_lshr_b32 s10, s72, 6
	s_mul_i32 s9, s10, 17408
	v_and_b32_e32 v241, 15, v240
	v_lshrrev_b32_e32 v242, 4, v240
	v_mul_u32_u24_e32 v243, 0x110, v241
	v_lshl_add_u32 v243, v242, 4, v243
	v_add_u32_e32 v245, s9, v243
	v_mul_u32_u24_e32 v243, 0x110, v242
	v_lshl_add_u32 v243, v241, 4, v243
	v_add_u32_e32 v246, s9, v243
	s_lshr_b32 s9, s10, 1
	s_lshl_b32 s9, s9, 7
	v_add_u32_e32 v243, s9, v242
	v_lshlrev_b32_e32 v243, 12, v243
	s_and_b32 s9, s10, 1
	s_lshl_b32 s9, s9, 8
	v_lshl_add_u32 v244, v241, 4, s9
	v_add_u32_e32 v247, v243, v244
	s_cmpk_gt_u32 s96, 0xff
	s_cbranch_scc0 .Lg9_prio
	s_setprio 1
.Lg9_prio:
	s_lshr_b32 s15, s96, 3
	s_and_b32 s18, s96, 7
	s_lshl_b32 s18, s18, 1
	s_waitcnt lgkmcnt(0)

; #define LWRITE(S, buf) do { bf16_t* sA_ = sbase + (buf) * BUF; bf16_t* sB_ = sA_ + 256 * PITCH; \
;     _Pragma("unroll") for (int i_ = 0; i_ < 4; ++i_) *(u32x4*)(sA_ + (sr + i_ * 64) * PITCH + scv * 8) = ra[S][i_]; \
;     _Pragma("unroll") for (int i_ = 0; i_ < 2; ++i_) *(u32x4*)(sB_ + (sr + i_ * 64) * PITCH + scv * 8) = rb[S][i_]; } while (0)
; template <class Epi>
; DI void gemm_tile(char* smem, const bf16_t* __restrict__ A0, int lda0, int ksplit, const bf16_t* __restrict__ A1, int lda1,
;                   const bf16_t* __restrict__ Bt, int K, int row0, int col0, const Epi& epi, int tid) {
;     ...
;   __syncthreads();
;   {
;     const int last = nk - 1;
;     GLOAD(0, 0);
;     __builtin_amdgcn_sched_barrier(0);
;     GLOAD(1, 1);
;     __builtin_amdgcn_sched_barrier(0);
;     LWRITE(0, 0);
;     __builtin_amdgcn_sched_barrier(0);
;     GLOAD(0, (2 < last ? 2 : last));
;     __builtin_amdgcn_sched_barrier(0);
;     __syncthreads();
;     for (int kt = 0; kt < nk; kt += 2) {
;       LWRITE(1, 1);
;       __builtin_amdgcn_sched_barrier(0);
;       GLOAD(1, (kt + 3 < last ? kt + 3 : last));
;       __builtin_amdgcn_sched_barrier(0);
;       COMPUTE(0);
;       __syncthreads();
;       LWRITE(0, 0);
;       __builtin_amdgcn_sched_barrier(0);
;       GLOAD(0, (kt + 4 < last ? kt + 4 : last));
;       __builtin_amdgcn_sched_barrier(0);
;       COMPUTE(1);
;       __syncthreads();
.Lg9_kloop:
	s_waitcnt vmcnt(6)
	s_waitcnt lgkmcnt(0)
	s_barrier
	v_add_u32_e32 v232, s98, v230
	v_add_u32_e32 v233, s98, v231
	s_add_u32 s9, s17, s101
	s_setprio 1
	v_mfma_f32_16x16x32_bf16 v[0:3], v[128:131], v[144:147], v[0:3]
	v_mfma_f32_16x16x32_bf16 v[4:7], v[132:135], v[144:147], v[4:7]
	v_mfma_f32_16x16x32_bf16 v[8:11], v[136:139], v[144:147], v[8:11]
	v_mfma_f32_16x16x32_bf16 v[12:15], v[140:143], v[144:147], v[12:15]
	ds_read_b128 v[176:179], v233 offset:0
	ds_read_b128 v[180:183], v233 offset:1024
	s_add_u32 m0, s9, 0
	s_nop 0
	global_load_lds_dwordx4 v224, s[0:1]
	v_mfma_f32_16x16x32_bf16 v[16:19], v[128:131], v[148:151], v[16:19]
	v_mfma_f32_16x16x32_bf16 v[20:23], v[132:135], v[148:151], v[20:23]
	v_mfma_f32_16x16x32_bf16 v[24:27], v[136:139], v[148:151], v[24:27]
	v_mfma_f32_16x16x32_bf16 v[28:31], v[140:143], v[148:151], v[28:31]
	ds_read_b128 v[184:187], v233 offset:2048
	ds_read_b128 v[188:191], v233 offset:3072
	s_add_u32 m0, s9, 4096
	s_nop 0
	global_load_lds_dwordx4 v225, s[0:1]
	v_mfma_f32_16x16x32_bf16 v[32:35], v[128:131], v[152:155], v[32:35]
	v_mfma_f32_16x16x32_bf16 v[36:39], v[132:135], v[152:155], v[36:39]
	v_mfma_f32_16x16x32_bf16 v[40:43], v[136:139], v[152:155], v[40:43]
	v_mfma_f32_16x16x32_bf16 v[44:47], v[140:143], v[152:155], v[44:47]
	ds_read_b128 v[192:195], v232 offset:0
	ds_read_b128 v[196:199], v232 offset:1024
	s_add_u32 m0, s9, 8192
	s_nop 0
	global_load_lds_dwordx4 v226, s[0:1]
	v_mfma_f32_16x16x32_bf16 v[48:51], v[128:131], v[156:159], v[48:51]
	v_mfma_f32_16x16x32_bf16 v[52:55], v[132:135], v[156:159], v[52:55]
	v_mfma_f32_16x16x32_bf16 v[56:59], v[136:139], v[156:159], v[56:59]
	v_mfma_f32_16x16x32_bf16 v[60:63], v[140:143], v[156:159], v[60:63]
	ds_read_b128 v[200:203], v232 offset:2048
	ds_read_b128 v[204:207], v232 offset:3072
	s_add_u32 m0, s9, 12288
	s_nop 0
	global_load_lds_dwordx4 v227, s[0:1]
	v_mfma_f32_16x16x32_bf16 v[64:67], v[128:131], v[160:163], v[64:67]
	v_mfma_f32_16x16x32_bf16 v[68:71], v[132:135], v[160:163], v[68:71]
	v_mfma_f32_16x16x32_bf16 v[72:75], v[136:139], v[160:163], v[72:75]
	v_mfma_f32_16x16x32_bf16 v[76:79], v[140:143], v[160:163], v[76:79]
	ds_read_b128 v[208:211], v232 offset:4096
	s_add_u32 m0, s9, 16384
	s_nop 0
	global_load_lds_dwordx4 v228, s[2:3]
	v_mfma_f32_16x16x32_bf16 v[80:83], v[128:131], v[164:167], v[80:83]
	v_mfma_f32_16x16x32_bf16 v[84:87], v[132:135], v[164:167], v[84:87]
	v_mfma_f32_16x16x32_bf16 v[88:91], v[136:139], v[164:167], v[88:91]
	v_mfma_f32_16x16x32_bf16 v[92:95], v[140:143], v[164:167], v[92:95]
	ds_read_b128 v[212:215], v232 offset:5120
	s_add_u32 m0, s9, 20480
	s_nop 0
	global_load_lds_dwordx4 v229, s[2:3]
	v_mfma_f32_16x16x32_bf16 v[96:99], v[128:131], v[168:171], v[96:99]
	v_mfma_f32_16x16x32_bf16 v[100:103], v[132:135], v[168:171], v[100:103]
	v_mfma_f32_16x16x32_bf16 v[104:107], v[136:139], v[168:171], v[104:107]
	v_mfma_f32_16x16x32_bf16 v[108:111], v[140:143], v[168:171], v[108:111]
	ds_read_b128 v[216:219], v232 offset:6144
	s_add_u32 s0, s0, 64
	s_addc_u32 s1, s1, 0
	s_add_u32 s2, s2, 64
	s_addc_u32 s3, s3, 0
	s_add_u32 s100, s100, 1
	s_add_u32 s17, s17, 24576
	s_cmp_eq_u32 s17, 73728
	s_cselect_b32 s17, 0, s17
	s_add_u32 s98, s98, 24576
	s_cmp_eq_u32 s98, 73728
	s_cselect_b32 s98, 0, s98
	v_mfma_f32_16x16x32_bf16 v[112:115], v[128:131], v[172:175], v[112:115]
	v_mfma_f32_16x16x32_bf16 v[116:119], v[132:135], v[172:175], v[116:119]
	v_mfma_f32_16x16x32_bf16 v[120:123], v[136:139], v[172:175], v[120:123]
	v_mfma_f32_16x16x32_bf16 v[124:127], v[140:143], v[172:175], v[124:127]
	ds_read_b128 v[220:223], v232 offset:7168
	s_setprio 0
	s_waitcnt vmcnt(6)
	s_waitcnt lgkmcnt(0)
	s_barrier
	v_add_u32_e32 v232, s98, v230
	v_add_u32_e32 v233, s98, v231
	s_add_u32 s9, s17, s101
	s_setprio 1
	v_mfma_f32_16x16x32_bf16 v[0:3], v[176:179], v[192:195], v[0:3]
	v_mfma_f32_16x16x32_bf16 v[4:7], v[180:183], v[192:195], v[4:7]
	v_mfma_f32_16x16x32_bf16 v[8:11], v[184:187], v[192:195], v[8:11]
	v_mfma_f32_16x16x32_bf16 v[12:15], v[188:191], v[192:195], v[12:15]
	ds_read_b128 v[128:131], v233 offset:0
	ds_read_b128 v[132:135], v233 offset:1024
	s_add_u32 m0, s9, 0
	s_nop 0
	global_load_lds_dwordx4 v224, s[0:1]
	v_mfma_f32_16x16x32_bf16 v[16:19], v[176:179], v[196:199], v[16:19]
	v_mfma_f32_16x16x32_bf16 v[20:23], v[180:183], v[196:199], v[20:23]
	v_mfma_f32_16x16x32_bf16 v[24:27], v[184:187], v[196:199], v[24:27]
	v_mfma_f32_16x16x32_bf16 v[28:31], v[188:191], v[196:199], v[28:31]
	ds_read_b128 v[136:139], v233 offset:2048
	ds_read_b128 v[140:143], v233 offset:3072
	s_add_u32 m0, s9, 4096
	s_nop 0
	global_load_lds_dwordx4 v225, s[0:1]
	v_mfma_f32_16x16x32_bf16 v[32:35], v[176:179], v[200:203], v[32:35]
	v_mfma_f32_16x16x32_bf16 v[36:39], v[180:183], v[200:203], v[36:39]
	v_mfma_f32_16x16x32_bf16 v[40:43], v[184:187], v[200:203], v[40:43]
	v_mfma_f32_16x16x32_bf16 v[44:47], v[188:191], v[200:203], v[44:47]
	ds_read_b128 v[144:147], v232 offset:0
	ds_read_b128 v[148:151], v232 offset:1024
	s_add_u32 m0, s9, 8192
	s_nop 0
	global_load_lds_dwordx4 v226, s[0:1]
	v_mfma_f32_16x16x32_bf16 v[48:51], v[176:179], v[204:207], v[48:51]
	v_mfma_f32_16x16x32_bf16 v[52:55], v[180:183], v[204:207], v[52:55]
	v_mfma_f32_16x16x32_bf16 v[56:59], v[184:187], v[204:207], v[56:59]
	v_mfma_f32_16x16x32_bf16 v[60:63], v[188:191], v[204:207], v[60:63]
	ds_read_b128 v[152:155], v232 offset:2048
	ds_read_b128 v[156:159], v232 offset:3072
	s_add_u32 m0, s9, 12288
	s_nop 0
	global_load_lds_dwordx4 v227, s[0:1]
	v_mfma_f32_16x16x32_bf16 v[64:67], v[176:179], v[208:211], v[64:67]
	v_mfma_f32_16x16x32_bf16 v[68:71], v[180:183], v[208:211], v[68:71]
; #define LWRITE(S, buf) do { bf16_t* sA_ = sbase + (buf) * BUF; bf16_t* sB_ = sA_ + 256 * PITCH; \
;     _Pragma("unroll") for (int i_ = 0; i_ < 4; ++i_) *(u32x4*)(sA_ + (sr + i_ * 64) * PITCH + scv * 8) = ra[S][i_]; \
;     _Pragma("unroll") for (int i_ = 0; i_ < 2; ++i_) *(u32x4*)(sB_ + (sr + i_ * 64) * PITCH + scv * 8) = rb[S][i_]; } while (0)
; template <class Epi>
; DI void gemm_tile(char* smem, const bf16_t* __restrict__ A0, int lda0, int ksplit, const bf16_t* __restrict__ A1, int lda1,
;                   const bf16_t* __restrict__ Bt, int K, int row0, int col0, const Epi& epi, int tid) {
;     ...
;   __syncthreads();
;   {
;     const int last = nk - 1;
;     GLOAD(0, 0);
;     __builtin_amdgcn_sched_barrier(0);
;     GLOAD(1, 1);
;     __builtin_amdgcn_sched_barrier(0);
;     LWRITE(0, 0);
;     __builtin_amdgcn_sched_barrier(0);
;     GLOAD(0, (2 < last ? 2 : last));
;     __builtin_amdgcn_sched_barrier(0);
;     __syncthreads();
;     for (int kt = 0; kt < nk; kt += 2) {
;       LWRITE(1, 1);
;       __builtin_amdgcn_sched_barrier(0);
;       GLOAD(1, (kt + 3 < last ? kt + 3 : last));
;       __builtin_amdgcn_sched_barrier(0);
;       COMPUTE(0);
;       __syncthreads();
;       LWRITE(0, 0);
;       __builtin_amdgcn_sched_barrier(0);
;       GLOAD(0, (kt + 4 < last ? kt + 4 : last));
;       __builtin_amdgcn_sched_barrier(0);
;       COMPUTE(1);
;       __syncthreads();
;     }
	v_mfma_f32_16x16x32_bf16 v[72:75], v[184:187], v[208:211], v[72:75]
	v_mfma_f32_16x16x32_bf16 v[76:79], v[188:191], v[208:211], v[76:79]
	ds_read_b128 v[160:163], v232 offset:4096
	s_add_u32 m0, s9, 16384
	s_nop 0
	global_load_lds_dwordx4 v228, s[2:3]
	v_mfma_f32_16x16x32_bf16 v[80:83], v[176:179], v[212:215], v[80:83]
	v_mfma_f32_16x16x32_bf16 v[84:87], v[180:183], v[212:215], v[84:87]
	v_mfma_f32_16x16x32_bf16 v[88:91], v[184:187], v[212:215], v[88:91]
	v_mfma_f32_16x16x32_bf16 v[92:95], v[188:191], v[212:215], v[92:95]
	ds_read_b128 v[164:167], v232 offset:5120
	s_add_u32 m0, s9, 20480
	s_nop 0
	global_load_lds_dwordx4 v229, s[2:3]
	v_mfma_f32_16x16x32_bf16 v[96:99], v[176:179], v[216:219], v[96:99]
	v_mfma_f32_16x16x32_bf16 v[100:103], v[180:183], v[216:219], v[100:103]
	v_mfma_f32_16x16x32_bf16 v[104:107], v[184:187], v[216:219], v[104:107]
	v_mfma_f32_16x16x32_bf16 v[108:111], v[188:191], v[216:219], v[108:111]
	ds_read_b128 v[168:171], v232 offset:6144
	s_add_u32 s0, s0, 64
	s_addc_u32 s1, s1, 0
	s_add_u32 s2, s2, 64
	s_addc_u32 s3, s3, 0
	s_add_u32 s100, s100, 1
	s_add_u32 s17, s17, 24576
	s_cmp_eq_u32 s17, 73728
	s_cselect_b32 s17, 0, s17
	s_add_u32 s98, s98, 24576
	s_cmp_eq_u32 s98, 73728
	s_cselect_b32 s98, 0, s98
	v_mfma_f32_16x16x32_bf16 v[112:115], v[176:179], v[220:223], v[112:115]
	v_mfma_f32_16x16x32_bf16 v[116:119], v[180:183], v[220:223], v[116:119]
	v_mfma_f32_16x16x32_bf16 v[120:123], v[184:187], v[220:223], v[120:123]
	v_mfma_f32_16x16x32_bf16 v[124:127], v[188:191], v[220:223], v[124:127]
	ds_read_b128 v[172:175], v232 offset:7168
	s_setprio 0
	s_add_u32 s99, s99, 2
	s_cmp_lt_u32 s99, 124
	s_cbranch_scc1 .Lg9_kloop
	s_waitcnt vmcnt(6)
	s_waitcnt lgkmcnt(0)
	s_barrier
	v_add_u32_e32 v232, s98, v230
	v_add_u32_e32 v233, s98, v231
	s_add_u32 s9, s17, s101
	s_setprio 1
	v_mfma_f32_16x16x32_bf16 v[0:3], v[128:131], v[144:147], v[0:3]
	v_mfma_f32_16x16x32_bf16 v[4:7], v[132:135], v[144:147], v[4:7]
	v_mfma_f32_16x16x32_bf16 v[8:11], v[136:139], v[144:147], v[8:11]
	v_mfma_f32_16x16x32_bf16 v[12:15], v[140:143], v[144:147], v[12:15]
	ds_read_b128 v[176:179], v233 offset:0
	ds_read_b128 v[180:183], v233 offset:1024
	s_add_u32 m0, s9, 0
	s_nop 0
	global_load_lds_dwordx4 v224, s[0:1]
	v_mfma_f32_16x16x32_bf16 v[16:19], v[128:131], v[148:151], v[16:19]
	v_mfma_f32_16x16x32_bf16 v[20:23], v[132:135], v[148:151], v[20:23]
	v_mfma_f32_16x16x32_bf16 v[24:27], v[136:139], v[148:151], v[24:27]
	v_mfma_f32_16x16x32_bf16 v[28:31], v[140:143], v[148:151], v[28:31]
	ds_read_b128 v[184:187], v233 offset:2048
	ds_read_b128 v[188:191], v233 offset:3072
	s_add_u32 m0, s9, 4096
	s_nop 0
	global_load_lds_dwordx4 v225, s[0:1]
	v_mfma_f32_16x16x32_bf16 v[32:35], v[128:131], v[152:155], v[32:35]
	v_mfma_f32_16x16x32_bf16 v[36:39], v[132:135], v[152:155], v[36:39]
	v_mfma_f32_16x16x32_bf16 v[40:43], v[136:139], v[152:155], v[40:43]
	v_mfma_f32_16x16x32_bf16 v[44:47], v[140:143], v[152:155], v[44:47]
	ds_read_b128 v[192:195], v232 offset:0
	ds_read_b128 v[196:199], v232 offset:1024
	s_add_u32 m0, s9, 8192
	s_nop 0
	global_load_lds_dwordx4 v226, s[0:1]
	v_mfma_f32_16x16x32_bf16 v[48:51], v[128:131], v[156:159], v[48:51]
	v_mfma_f32_16x16x32_bf16 v[52:55], v[132:135], v[156:159], v[52:55]
	v_mfma_f32_16x16x32_bf16 v[56:59], v[136:139], v[156:159], v[56:59]
	v_mfma_f32_16x16x32_bf16 v[60:63], v[140:143], v[156:159], v[60:63]
	ds_read_b128 v[200:203], v232 offset:2048
	ds_read_b128 v[204:207], v232 offset:3072
	s_add_u32 m0, s9, 12288
	s_nop 0
	global_load_lds_dwordx4 v227, s[0:1]
	v_mfma_f32_16x16x32_bf16 v[64:67], v[128:131], v[160:163], v[64:67]
	v_mfma_f32_16x16x32_bf16 v[68:71], v[132:135], v[160:163], v[68:71]
	v_mfma_f32_16x16x32_bf16 v[72:75], v[136:139], v[160:163], v[72:75]
	v_mfma_f32_16x16x32_bf16 v[76:79], v[140:143], v[160:163], v[76:79]
	ds_read_b128 v[208:211], v232 offset:4096
	s_add_u32 m0, s9, 16384
	s_nop 0
	global_load_lds_dwordx4 v228, s[2:3]
	v_mfma_f32_16x16x32_bf16 v[80:83], v[128:131], v[164:167], v[80:83]
	v_mfma_f32_16x16x32_bf16 v[84:87], v[132:135], v[164:167], v[84:87]
	v_mfma_f32_16x16x32_bf16 v[88:91], v[136:139], v[164:167], v[88:91]
	v_mfma_f32_16x16x32_bf16 v[92:95], v[140:143], v[164:167], v[92:95]
	ds_read_b128 v[212:215], v232 offset:5120
	s_add_u32 m0, s9, 20480
	s_nop 0
	global_load_lds_dwordx4 v229, s[2:3]
	v_mfma_f32_16x16x32_bf16 v[96:99], v[128:131], v[168:171], v[96:99]
	v_mfma_f32_16x16x32_bf16 v[100:103], v[132:135], v[168:171], v[100:103]
	v_mfma_f32_16x16x32_bf16 v[104:107], v[136:139], v[168:171], v[104:107]
	v_mfma_f32_16x16x32_bf16 v[108:111], v[140:143], v[168:171], v[108:111]
	ds_read_b128 v[216:219], v232 offset:6144
	s_add_u32 s0, s0, 64
	s_addc_u32 s1, s1, 0
	s_add_u32 s2, s2, 64
	s_addc_u32 s3, s3, 0
	s_add_u32 s100, s100, 1
	s_add_u32 s17, s17, 24576
	s_cmp_eq_u32 s17, 73728
	s_cselect_b32 s17, 0, s17
	s_add_u32 s98, s98, 24576
	s_cmp_eq_u32 s98, 73728
	s_cselect_b32 s98, 0, s98
	v_mfma_f32_16x16x32_bf16 v[112:115], v[128:131], v[172:175], v[112:115]
	v_mfma_f32_16x16x32_bf16 v[116:119], v[132:135], v[172:175], v[116:119]
	v_mfma_f32_16x16x32_bf16 v[120:123], v[136:139], v[172:175], v[120:123]
	v_mfma_f32_16x16x32_bf16 v[124:127], v[140:143], v[172:175], v[124:127]
	ds_read_b128 v[220:223], v232 offset:7168
	s_setprio 0
	s_waitcnt vmcnt(6)
	s_waitcnt lgkmcnt(0)
	s_barrier
; #define LWRITE(S, buf) do { bf16_t* sA_ = sbase + (buf) * BUF; bf16_t* sB_ = sA_ + 256 * PITCH; \
;     _Pragma("unroll") for (int i_ = 0; i_ < 4; ++i_) *(u32x4*)(sA_ + (sr + i_ * 64) * PITCH + scv * 8) = ra[S][i_]; \
;     _Pragma("unroll") for (int i_ = 0; i_ < 2; ++i_) *(u32x4*)(sB_ + (sr + i_ * 64) * PITCH + scv * 8) = rb[S][i_]; } while (0)
; template <class Epi>
; DI void gemm_tile(char* smem, const bf16_t* __restrict__ A0, int lda0, int ksplit, const bf16_t* __restrict__ A1, int lda1,
;                   const bf16_t* __restrict__ Bt, int K, int row0, int col0, const Epi& epi, int tid) {
;     ...
;   __syncthreads();
;   {
;     const int last = nk - 1;
;     GLOAD(0, 0);
;     __builtin_amdgcn_sched_barrier(0);
;     GLOAD(1, 1);
;     __builtin_amdgcn_sched_barrier(0);
;     LWRITE(0, 0);
;     __builtin_amdgcn_sched_barrier(0);
;     GLOAD(0, (2 < last ? 2 : last));
;     __builtin_amdgcn_sched_barrier(0);
;     __syncthreads();
;     for (int kt = 0; kt < nk; kt += 2) {
;       LWRITE(1, 1);
;       __builtin_amdgcn_sched_barrier(0);
;       GLOAD(1, (kt + 3 < last ? kt + 3 : last));
;       __builtin_amdgcn_sched_barrier(0);
;       COMPUTE(0);
;       __syncthreads();
;       LWRITE(0, 0);
;       __builtin_amdgcn_sched_barrier(0);
;       GLOAD(0, (kt + 4 < last ? kt + 4 : last));
;       __builtin_amdgcn_sched_barrier(0);
;       COMPUTE(1);
;       __syncthreads();
;     }
	v_add_u32_e32 v232, s98, v230
	v_add_u32_e32 v233, s98, v231
	s_setprio 1
	v_mfma_f32_16x16x32_bf16 v[0:3], v[176:179], v[192:195], v[0:3]
	v_mfma_f32_16x16x32_bf16 v[4:7], v[180:183], v[192:195], v[4:7]
	v_mfma_f32_16x16x32_bf16 v[8:11], v[184:187], v[192:195], v[8:11]
	v_mfma_f32_16x16x32_bf16 v[12:15], v[188:191], v[192:195], v[12:15]
	ds_read_b128 v[128:131], v233 offset:0
	ds_read_b128 v[132:135], v233 offset:1024
	v_mfma_f32_16x16x32_bf16 v[16:19], v[176:179], v[196:199], v[16:19]
	v_mfma_f32_16x16x32_bf16 v[20:23], v[180:183], v[196:199], v[20:23]
	v_mfma_f32_16x16x32_bf16 v[24:27], v[184:187], v[196:199], v[24:27]
	v_mfma_f32_16x16x32_bf16 v[28:31], v[188:191], v[196:199], v[28:31]
	ds_read_b128 v[136:139], v233 offset:2048
	ds_read_b128 v[140:143], v233 offset:3072
	v_mfma_f32_16x16x32_bf16 v[32:35], v[176:179], v[200:203], v[32:35]
	v_mfma_f32_16x16x32_bf16 v[36:39], v[180:183], v[200:203], v[36:39]
	v_mfma_f32_16x16x32_bf16 v[40:43], v[184:187], v[200:203], v[40:43]
	v_mfma_f32_16x16x32_bf16 v[44:47], v[188:191], v[200:203], v[44:47]
	ds_read_b128 v[144:147], v232 offset:0
	ds_read_b128 v[148:151], v232 offset:1024
	v_mfma_f32_16x16x32_bf16 v[48:51], v[176:179], v[204:207], v[48:51]
	v_mfma_f32_16x16x32_bf16 v[52:55], v[180:183], v[204:207], v[52:55]
	v_mfma_f32_16x16x32_bf16 v[56:59], v[184:187], v[204:207], v[56:59]
	v_mfma_f32_16x16x32_bf16 v[60:63], v[188:191], v[204:207], v[60:63]
	ds_read_b128 v[152:155], v232 offset:2048
	ds_read_b128 v[156:159], v232 offset:3072
	v_mfma_f32_16x16x32_bf16 v[64:67], v[176:179], v[208:211], v[64:67]
	v_mfma_f32_16x16x32_bf16 v[68:71], v[180:183], v[208:211], v[68:71]
	v_mfma_f32_16x16x32_bf16 v[72:75], v[184:187], v[208:211], v[72:75]
	v_mfma_f32_16x16x32_bf16 v[76:79], v[188:191], v[208:211], v[76:79]
	ds_read_b128 v[160:163], v232 offset:4096
	v_mfma_f32_16x16x32_bf16 v[80:83], v[176:179], v[212:215], v[80:83]
	v_mfma_f32_16x16x32_bf16 v[84:87], v[180:183], v[212:215], v[84:87]
	v_mfma_f32_16x16x32_bf16 v[88:91], v[184:187], v[212:215], v[88:91]
	v_mfma_f32_16x16x32_bf16 v[92:95], v[188:191], v[212:215], v[92:95]
	ds_read_b128 v[164:167], v232 offset:5120
	v_mfma_f32_16x16x32_bf16 v[96:99], v[176:179], v[216:219], v[96:99]
	v_mfma_f32_16x16x32_bf16 v[100:103], v[180:183], v[216:219], v[100:103]
	v_mfma_f32_16x16x32_bf16 v[104:107], v[184:187], v[216:219], v[104:107]
	v_mfma_f32_16x16x32_bf16 v[108:111], v[188:191], v[216:219], v[108:111]
	ds_read_b128 v[168:171], v232 offset:6144
	s_add_u32 s98, s98, 24576
	s_cmp_eq_u32 s98, 73728
	s_cselect_b32 s98, 0, s98
	v_mfma_f32_16x16x32_bf16 v[112:115], v[176:179], v[220:223], v[112:115]
	v_mfma_f32_16x16x32_bf16 v[116:119], v[180:183], v[220:223], v[116:119]
	v_mfma_f32_16x16x32_bf16 v[120:123], v[184:187], v[220:223], v[120:123]
	v_mfma_f32_16x16x32_bf16 v[124:127], v[188:191], v[220:223], v[124:127]
	ds_read_b128 v[172:175], v232 offset:7168
	s_setprio 0
	s_waitcnt vmcnt(0)
	s_waitcnt lgkmcnt(0)
	s_barrier
; #define LWRITE(S, buf) do { bf16_t* sA_ = sbase + (buf) * BUF; bf16_t* sB_ = sA_ + 256 * PITCH; \
;     _Pragma("unroll") for (int i_ = 0; i_ < 4; ++i_) *(u32x4*)(sA_ + (sr + i_ * 64) * PITCH + scv * 8) = ra[S][i_]; \
;     _Pragma("unroll") for (int i_ = 0; i_ < 2; ++i_) *(u32x4*)(sB_ + (sr + i_ * 64) * PITCH + scv * 8) = rb[S][i_]; } while (0)
; template <class Epi>
; DI void gemm_tile(char* smem, const bf16_t* __restrict__ A0, int lda0, int ksplit, const bf16_t* __restrict__ A1, int lda1,
;                   const bf16_t* __restrict__ Bt, int K, int row0, int col0, const Epi& epi, int tid) {
;     ...
;   __syncthreads();
;   {
;     const int last = nk - 1;
;     GLOAD(0, 0);
;     __builtin_amdgcn_sched_barrier(0);
;     GLOAD(1, 1);
;     __builtin_amdgcn_sched_barrier(0);
;     LWRITE(0, 0);
;     __builtin_amdgcn_sched_barrier(0);
;     GLOAD(0, (2 < last ? 2 : last));
;     __builtin_amdgcn_sched_barrier(0);
;     __syncthreads();
;     for (int kt = 0; kt < nk; kt += 2) {
;       LWRITE(1, 1);
;       __builtin_amdgcn_sched_barrier(0);
;       GLOAD(1, (kt + 3 < last ? kt + 3 : last));
;       __builtin_amdgcn_sched_barrier(0);
;       COMPUTE(0);
;       __syncthreads();
;       LWRITE(0, 0);
;       __builtin_amdgcn_sched_barrier(0);
;       GLOAD(0, (kt + 4 < last ? kt + 4 : last));
;       __builtin_amdgcn_sched_barrier(0);
;       COMPUTE(1);
;       __syncthreads();
;     }
	v_add_u32_e32 v232, s98, v230
	v_add_u32_e32 v233, s98, v231
	s_setprio 1
	v_mfma_f32_16x16x32_bf16 v[0:3], v[128:131], v[144:147], v[0:3]
	v_mfma_f32_16x16x32_bf16 v[4:7], v[132:135], v[144:147], v[4:7]
	v_mfma_f32_16x16x32_bf16 v[8:11], v[136:139], v[144:147], v[8:11]
	v_mfma_f32_16x16x32_bf16 v[12:15], v[140:143], v[144:147], v[12:15]
	ds_read_b128 v[176:179], v233 offset:0
	ds_read_b128 v[180:183], v233 offset:1024
	v_mfma_f32_16x16x32_bf16 v[16:19], v[128:131], v[148:151], v[16:19]
	v_mfma_f32_16x16x32_bf16 v[20:23], v[132:135], v[148:151], v[20:23]
	v_mfma_f32_16x16x32_bf16 v[24:27], v[136:139], v[148:151], v[24:27]
	v_mfma_f32_16x16x32_bf16 v[28:31], v[140:143], v[148:151], v[28:31]
	ds_read_b128 v[184:187], v233 offset:2048
	ds_read_b128 v[188:191], v233 offset:3072
	v_mfma_f32_16x16x32_bf16 v[32:35], v[128:131], v[152:155], v[32:35]
	v_mfma_f32_16x16x32_bf16 v[36:39], v[132:135], v[152:155], v[36:39]
	v_mfma_f32_16x16x32_bf16 v[40:43], v[136:139], v[152:155], v[40:43]
	v_mfma_f32_16x16x32_bf16 v[44:47], v[140:143], v[152:155], v[44:47]
	ds_read_b128 v[192:195], v232 offset:0
	ds_read_b128 v[196:199], v232 offset:1024
	v_mfma_f32_16x16x32_bf16 v[48:51], v[128:131], v[156:159], v[48:51]
	v_mfma_f32_16x16x32_bf16 v[52:55], v[132:135], v[156:159], v[52:55]
	v_mfma_f32_16x16x32_bf16 v[56:59], v[136:139], v[156:159], v[56:59]
	v_mfma_f32_16x16x32_bf16 v[60:63], v[140:143], v[156:159], v[60:63]
	ds_read_b128 v[200:203], v232 offset:2048
	ds_read_b128 v[204:207], v232 offset:3072
	v_mfma_f32_16x16x32_bf16 v[64:67], v[128:131], v[160:163], v[64:67]
	v_mfma_f32_16x16x32_bf16 v[68:71], v[132:135], v[160:163], v[68:71]
	v_mfma_f32_16x16x32_bf16 v[72:75], v[136:139], v[160:163], v[72:75]
	v_mfma_f32_16x16x32_bf16 v[76:79], v[140:143], v[160:163], v[76:79]
	ds_read_b128 v[208:211], v232 offset:4096
	v_mfma_f32_16x16x32_bf16 v[80:83], v[128:131], v[164:167], v[80:83]
	v_mfma_f32_16x16x32_bf16 v[84:87], v[132:135], v[164:167], v[84:87]
	v_mfma_f32_16x16x32_bf16 v[88:91], v[136:139], v[164:167], v[88:91]
	v_mfma_f32_16x16x32_bf16 v[92:95], v[140:143], v[164:167], v[92:95]
	ds_read_b128 v[212:215], v232 offset:5120
	v_mfma_f32_16x16x32_bf16 v[96:99], v[128:131], v[168:171], v[96:99]
	v_mfma_f32_16x16x32_bf16 v[100:103], v[132:135], v[168:171], v[100:103]
	v_mfma_f32_16x16x32_bf16 v[104:107], v[136:139], v[168:171], v[104:107]
	v_mfma_f32_16x16x32_bf16 v[108:111], v[140:143], v[168:171], v[108:111]
	ds_read_b128 v[216:219], v232 offset:6144
	s_add_u32 s98, s98, 24576
	s_cmp_eq_u32 s98, 73728
	s_cselect_b32 s98, 0, s98
	v_mfma_f32_16x16x32_bf16 v[112:115], v[128:131], v[172:175], v[112:115]
	v_mfma_f32_16x16x32_bf16 v[116:119], v[132:135], v[172:175], v[116:119]
	v_mfma_f32_16x16x32_bf16 v[120:123], v[136:139], v[172:175], v[120:123]
	v_mfma_f32_16x16x32_bf16 v[124:127], v[140:143], v[172:175], v[124:127]
	ds_read_b128 v[220:223], v232 offset:7168
	s_setprio 0
	s_waitcnt lgkmcnt(0)
	s_barrier
	s_setprio 1
	v_mfma_f32_16x16x32_bf16 v[0:3], v[176:179], v[192:195], v[0:3]
	v_mfma_f32_16x16x32_bf16 v[4:7], v[180:183], v[192:195], v[4:7]
	v_mfma_f32_16x16x32_bf16 v[8:11], v[184:187], v[192:195], v[8:11]
	v_mfma_f32_16x16x32_bf16 v[12:15], v[188:191], v[192:195], v[12:15]
	v_mfma_f32_16x16x32_bf16 v[16:19], v[176:179], v[196:199], v[16:19]
	v_mfma_f32_16x16x32_bf16 v[20:23], v[180:183], v[196:199], v[20:23]
	v_mfma_f32_16x16x32_bf16 v[24:27], v[184:187], v[196:199], v[24:27]
	v_mfma_f32_16x16x32_bf16 v[28:31], v[188:191], v[196:199], v[28:31]
	v_mfma_f32_16x16x32_bf16 v[32:35], v[176:179], v[200:203], v[32:35]
	v_mfma_f32_16x16x32_bf16 v[36:39], v[180:183], v[200:203], v[36:39]
	v_mfma_f32_16x16x32_bf16 v[40:43], v[184:187], v[200:203], v[40:43]
	v_mfma_f32_16x16x32_bf16 v[44:47], v[188:191], v[200:203], v[44:47]
	v_mfma_f32_16x16x32_bf16 v[48:51], v[176:179], v[204:207], v[48:51]
	v_mfma_f32_16x16x32_bf16 v[52:55], v[180:183], v[204:207], v[52:55]
	v_mfma_f32_16x16x32_bf16 v[56:59], v[184:187], v[204:207], v[56:59]
	v_mfma_f32_16x16x32_bf16 v[60:63], v[188:191], v[204:207], v[60:63]
	v_mfma_f32_16x16x32_bf16 v[64:67], v[176:179], v[208:211], v[64:67]
	v_mfma_f32_16x16x32_bf16 v[68:71], v[180:183], v[208:211], v[68:71]
	v_mfma_f32_16x16x32_bf16 v[72:75], v[184:187], v[208:211], v[72:75]
	v_mfma_f32_16x16x32_bf16 v[76:79], v[188:191], v[208:211], v[76:79]
	v_mfma_f32_16x16x32_bf16 v[80:83], v[176:179], v[212:215], v[80:83]
	v_mfma_f32_16x16x32_bf16 v[84:87], v[180:183], v[212:215], v[84:87]
	v_mfma_f32_16x16x32_bf16 v[88:91], v[184:187], v[212:215], v[88:91]
	v_mfma_f32_16x16x32_bf16 v[92:95], v[188:191], v[212:215], v[92:95]
	v_mfma_f32_16x16x32_bf16 v[96:99], v[176:179], v[216:219], v[96:99]
	v_mfma_f32_16x16x32_bf16 v[100:103], v[180:183], v[216:219], v[100:103]
	v_mfma_f32_16x16x32_bf16 v[104:107], v[184:187], v[216:219], v[104:107]
	v_mfma_f32_16x16x32_bf16 v[108:111], v[188:191], v[216:219], v[108:111]
	v_mfma_f32_16x16x32_bf16 v[112:115], v[176:179], v[220:223], v[112:115]
	v_mfma_f32_16x16x32_bf16 v[116:119], v[180:183], v[220:223], v[116:119]
	v_mfma_f32_16x16x32_bf16 v[120:123], v[184:187], v[220:223], v[120:123]
	v_mfma_f32_16x16x32_bf16 v[124:127], v[188:191], v[220:223], v[124:127]
	s_setprio 0
	s_branch .Lg9_epi

; #define PH(k) case k: if (ONLY_PHASE >= 0 && ONLY_PHASE != k) break;
; template <class Epi>
; DI void gemm_tile(char* smem, const bf16_t* __restrict__ A0, int lda0, int ksplit, const bf16_t* __restrict__ A1, int lda1,
;                   const bf16_t* __restrict__ Bt, int K, int row0, int col0, const Epi& epi, int tid) {
;   constexpr int BK = 32, PITCH = 40, BUF = (256 + 128) * PITCH;
;   bf16_t* sbase = (bf16_t*)smem;
;   const int lane = tid & 63, wid = tid >> 6, wr = wid >> 1, wc = wid & 1, fr = lane & 15, fq = lane >> 4;
;   f32x4 acc[8][4];
; #pragma unroll
;   for (int m = 0; m < 8; ++m)
; #pragma unroll
;     for (int n = 0; n < 4; ++n) acc[m][n] = (f32x4){0.f, 0.f, 0.f, 0.f};
;   u32x4 ra[2][4], rb[2][2];
;   const int nk = K / BK;
;   const int sr = tid >> 2, scv = tid & 3;
; template <int ph> DI void run_phase(const Ctx& c, char* smem) {
;     ...
;     PH(11) gemm_phase(smem, XN, 1024, 1 << 30, XN, 1024, (const bf16_t*)(ws + OFF_WCDIN), 1024, 21,
;                         EpiSplit{(bf16_t*)(ws + OFF_S5U), 512, 512, (bf16_t*)(ws + OFF_MLRAW), 2080, 2080}, TIDX); break;
.LBB0_975:
	s_cmp_gt_i32 s94, 11
	s_cselect_b64 s[0:1], -1, 0
	s_cmp_lt_i32 s95, 12
	s_cselect_b64 s[2:3], -1, 0
	s_or_b64 s[0:1], s[0:1], s[2:3]
	s_and_b64 vcc, exec, s[0:1]
	s_cbranch_vccnz .LBB0_1259
	s_load_dword s34, s[74:75], 0x180
	s_add_u32 s0, s92, 0x3800000
	s_addc_u32 s1, s93, 0
	s_add_u32 s10, s92, 0x2bc0000
	s_addc_u32 s11, s93, 0
	s_and_b32 s36, s72, 0xffffffc0
	v_mbcnt_hi_u32_b32 v195, -1, v194
	s_waitcnt lgkmcnt(0)
	s_and_b32 s35, s34, 7
	s_cmp_lg_u32 s35, 0
	s_waitcnt vmcnt(16)
	v_add_u32_e32 v196, s36, v195
	v_mbcnt_lo_u32_b32 v240, -1, 0
	v_mbcnt_hi_u32_b32 v240, -1, v240
	s_lshr_b32 s26, s72, 6
	s_lshl_b32 s99, s26, 10
	v_and_b32_e32 v241, 15, v240
	v_lshrrev_b32_e32 v242, 4, v240
	v_bfe_u32 v243, v240, 3, 1
	v_mul_u32_u24_e32 v243, 3, v243
	v_xor_b32_e32 v243, v242, v243
	v_lshlrev_b32_e32 v243, 4, v243
	v_lshl_add_u32 v243, v241, 6, v243
	s_lshr_b32 s25, s26, 1
	s_lshl_b32 s25, s25, 13
	v_add_u32_e32 v230, s25, v243
	s_and_b32 s25, s26, 1
	s_lshl_b32 s25, s25, 12
	s_add_u32 s25, s25, 16384
	v_add_u32_e32 v231, s25, v243
	s_lshr_b32 s25, s26, 1
	s_lshl_b32 s25, s25, 7
	v_add_u32_e32 v244, s25, v241
	s_and_b32 s25, s26, 1
	s_lshl_b32 s25, s25, 6
	v_lshl_add_u32 v245, v242, 2, s25
	s_movk_i32 s25, 1024
	v_mul_lo_u32 v246, v244, s25
	v_lshl_add_u32 v234, v245, 1, v246
	s_movk_i32 s25, 4160
	v_mul_lo_u32 v246, v244, s25
	v_lshl_add_u32 v235, v245, 1, v246
	s_mul_i32 s25, s26, 18432
	v_mul_u32_u24_e32 v246, 144, v241
	v_lshl_add_u32 v246, v242, 3, v246
	v_add_u32_e32 v236, s25, v246
	v_lshrrev_b32_e32 v246, 3, v240
	v_mul_u32_u24_e32 v246, 144, v246
	v_and_b32_e32 v247, 7, v240
	v_lshl_add_u32 v246, v247, 4, v246
	v_add_u32_e32 v237, s25, v246
	s_lshr_b32 s25, s26, 1
	s_lshl_b32 s25, s25, 7
	v_lshrrev_b32_e32 v246, 3, v240
	v_add_u32_e32 v246, s25, v246
	s_and_b32 s25, s26, 1
	s_lshl_b32 s25, s25, 6
	v_lshl_add_u32 v248, v247, 3, s25
	s_movk_i32 s25, 1024
	v_mul_lo_u32 v247, v246, s25
	v_lshl_add_u32 v238, v248, 1, v247
	s_movk_i32 s25, 4160
	v_mul_lo_u32 v247, v246, s25
	v_lshl_add_u32 v239, v248, 1, v247
	v_lshrrev_b32_e32 v241, 2, v240
	s_lshl_b32 s25, s26, 4
	v_add_u32_e32 v241, s25, v241
	v_bfe_u32 v242, v240, 5, 1
	v_mul_u32_u24_e32 v242, 3, v242
	v_and_b32_e32 v243, 3, v240
	v_xor_b32_e32 v243, v243, v242
	v_lshlrev_b32_e32 v243, 4, v243
	s_mov_b32 s25, 2048
	v_mad_u32_u24 v224, v241, s25, v243
	v_add_u32_e32 v225, 0x20000, v224
	v_add_u32_e32 v226, 0x40000, v224
	v_add_u32_e32 v227, 0x60000, v224
	s_mov_b32 s25, 2048
	v_mad_u32_u24 v228, v241, s25, v243
	v_add_u32_e32 v229, 0x20000, v228
	s_cmpk_gt_u32 s96, 0xff
	s_cbranch_scc0 .Lg11_prio
	s_setprio 1
.Lg11_prio:
	s_lshr_b32 s101, s96, 3
	s_and_b32 s100, s96, 7
	s_lshl_b32 s100, s100, 1
	s_waitcnt lgkmcnt(0)

; #define LWRITE(S, buf) do { bf16_t* sA_ = sbase + (buf) * BUF; bf16_t* sB_ = sA_ + 256 * PITCH; \
;     _Pragma("unroll") for (int i_ = 0; i_ < 4; ++i_) *(u32x4*)(sA_ + (sr + i_ * 64) * PITCH + scv * 8) = ra[S][i_]; \
;     _Pragma("unroll") for (int i_ = 0; i_ < 2; ++i_) *(u32x4*)(sB_ + (sr + i_ * 64) * PITCH + scv * 8) = rb[S][i_]; } while (0)
; template <class Epi>
; DI void gemm_tile(char* smem, const bf16_t* __restrict__ A0, int lda0, int ksplit, const bf16_t* __restrict__ A1, int lda1,
;                   const bf16_t* __restrict__ Bt, int K, int row0, int col0, const Epi& epi, int tid) {
;     ...
;   __syncthreads();
;   {
;     const int last = nk - 1;
;     GLOAD(0, 0);
;     __builtin_amdgcn_sched_barrier(0);
;     GLOAD(1, 1);
;     __builtin_amdgcn_sched_barrier(0);
;     LWRITE(0, 0);
;     __builtin_amdgcn_sched_barrier(0);
;     GLOAD(0, (2 < last ? 2 : last));
;     __builtin_amdgcn_sched_barrier(0);
;     __syncthreads();
;     for (int kt = 0; kt < nk; kt += 2) {
;       LWRITE(1, 1);
;       __builtin_amdgcn_sched_barrier(0);
;       GLOAD(1, (kt + 3 < last ? kt + 3 : last));
;       __builtin_amdgcn_sched_barrier(0);
;       COMPUTE(0);
;       __syncthreads();
;       LWRITE(0, 0);
;       __builtin_amdgcn_sched_barrier(0);
;       GLOAD(0, (kt + 4 < last ? kt + 4 : last));
;       __builtin_amdgcn_sched_barrier(0);
;       COMPUTE(1);
;       __syncthreads();
.Lg11_kloop:
	s_waitcnt vmcnt(6)
	s_waitcnt lgkmcnt(0)
	s_barrier
	v_add_u32_e32 v232, s30, v230
	v_add_u32_e32 v233, s30, v231
	s_add_u32 s25, s29, s99
	s_setprio 1
	v_mfma_f32_16x16x32_bf16 v[0:3], v[128:131], v[144:147], v[0:3]
	v_mfma_f32_16x16x32_bf16 v[4:7], v[132:135], v[144:147], v[4:7]
	v_mfma_f32_16x16x32_bf16 v[8:11], v[136:139], v[144:147], v[8:11]
	v_mfma_f32_16x16x32_bf16 v[12:15], v[140:143], v[144:147], v[12:15]
	ds_read_b128 v[176:179], v233 offset:0
	ds_read_b128 v[180:183], v233 offset:1024
	s_add_u32 m0, s25, 0
	s_nop 0
	global_load_lds_dwordx4 v224, s[0:1]
	v_mfma_f32_16x16x32_bf16 v[16:19], v[128:131], v[148:151], v[16:19]
	v_mfma_f32_16x16x32_bf16 v[20:23], v[132:135], v[148:151], v[20:23]
	v_mfma_f32_16x16x32_bf16 v[24:27], v[136:139], v[148:151], v[24:27]
	v_mfma_f32_16x16x32_bf16 v[28:31], v[140:143], v[148:151], v[28:31]
	ds_read_b128 v[184:187], v233 offset:2048
	ds_read_b128 v[188:191], v233 offset:3072
	s_add_u32 m0, s25, 4096
	s_nop 0
	global_load_lds_dwordx4 v225, s[0:1]
	v_mfma_f32_16x16x32_bf16 v[32:35], v[128:131], v[152:155], v[32:35]
	v_mfma_f32_16x16x32_bf16 v[36:39], v[132:135], v[152:155], v[36:39]
	v_mfma_f32_16x16x32_bf16 v[40:43], v[136:139], v[152:155], v[40:43]
	v_mfma_f32_16x16x32_bf16 v[44:47], v[140:143], v[152:155], v[44:47]
	ds_read_b128 v[192:195], v232 offset:0
	ds_read_b128 v[196:199], v232 offset:1024
	s_add_u32 m0, s25, 8192
	s_nop 0
	global_load_lds_dwordx4 v226, s[0:1]
	v_mfma_f32_16x16x32_bf16 v[48:51], v[128:131], v[156:159], v[48:51]
	v_mfma_f32_16x16x32_bf16 v[52:55], v[132:135], v[156:159], v[52:55]
	v_mfma_f32_16x16x32_bf16 v[56:59], v[136:139], v[156:159], v[56:59]
	v_mfma_f32_16x16x32_bf16 v[60:63], v[140:143], v[156:159], v[60:63]
	ds_read_b128 v[200:203], v232 offset:2048
	ds_read_b128 v[204:207], v232 offset:3072
	s_add_u32 m0, s25, 12288
	s_nop 0
	global_load_lds_dwordx4 v227, s[0:1]
	v_mfma_f32_16x16x32_bf16 v[64:67], v[128:131], v[160:163], v[64:67]
	v_mfma_f32_16x16x32_bf16 v[68:71], v[132:135], v[160:163], v[68:71]
	v_mfma_f32_16x16x32_bf16 v[72:75], v[136:139], v[160:163], v[72:75]
	v_mfma_f32_16x16x32_bf16 v[76:79], v[140:143], v[160:163], v[76:79]
	ds_read_b128 v[208:211], v232 offset:4096
	s_add_u32 m0, s25, 16384
	s_nop 0
	global_load_lds_dwordx4 v228, s[2:3]
	v_mfma_f32_16x16x32_bf16 v[80:83], v[128:131], v[164:167], v[80:83]
	v_mfma_f32_16x16x32_bf16 v[84:87], v[132:135], v[164:167], v[84:87]
	v_mfma_f32_16x16x32_bf16 v[88:91], v[136:139], v[164:167], v[88:91]
	v_mfma_f32_16x16x32_bf16 v[92:95], v[140:143], v[164:167], v[92:95]
	ds_read_b128 v[212:215], v232 offset:5120
	s_add_u32 m0, s25, 20480
	s_nop 0
	global_load_lds_dwordx4 v229, s[2:3]
	v_mfma_f32_16x16x32_bf16 v[96:99], v[128:131], v[168:171], v[96:99]
	v_mfma_f32_16x16x32_bf16 v[100:103], v[132:135], v[168:171], v[100:103]
	v_mfma_f32_16x16x32_bf16 v[104:107], v[136:139], v[168:171], v[104:107]
	v_mfma_f32_16x16x32_bf16 v[108:111], v[140:143], v[168:171], v[108:111]
	ds_read_b128 v[216:219], v232 offset:6144
	s_add_u32 s0, s0, 64
	s_addc_u32 s1, s1, 0
	s_add_u32 s2, s2, 64
	s_addc_u32 s3, s3, 0
	s_add_u32 s98, s98, 1
	s_add_u32 s29, s29, 24576
	s_cmp_eq_u32 s29, 73728
	s_cselect_b32 s29, 0, s29
	s_add_u32 s30, s30, 24576
	s_cmp_eq_u32 s30, 73728
	s_cselect_b32 s30, 0, s30
	v_mfma_f32_16x16x32_bf16 v[112:115], v[128:131], v[172:175], v[112:115]
	v_mfma_f32_16x16x32_bf16 v[116:119], v[132:135], v[172:175], v[116:119]
	v_mfma_f32_16x16x32_bf16 v[120:123], v[136:139], v[172:175], v[120:123]
	v_mfma_f32_16x16x32_bf16 v[124:127], v[140:143], v[172:175], v[124:127]
	ds_read_b128 v[220:223], v232 offset:7168
	s_setprio 0
	s_waitcnt vmcnt(6)
	s_waitcnt lgkmcnt(0)
	s_barrier
	v_add_u32_e32 v232, s30, v230
	v_add_u32_e32 v233, s30, v231
	s_add_u32 s25, s29, s99
	s_setprio 1
	v_mfma_f32_16x16x32_bf16 v[0:3], v[176:179], v[192:195], v[0:3]
	v_mfma_f32_16x16x32_bf16 v[4:7], v[180:183], v[192:195], v[4:7]
	v_mfma_f32_16x16x32_bf16 v[8:11], v[184:187], v[192:195], v[8:11]
	v_mfma_f32_16x16x32_bf16 v[12:15], v[188:191], v[192:195], v[12:15]
	ds_read_b128 v[128:131], v233 offset:0
	ds_read_b128 v[132:135], v233 offset:1024
	s_add_u32 m0, s25, 0
	s_nop 0
	global_load_lds_dwordx4 v224, s[0:1]
	v_mfma_f32_16x16x32_bf16 v[16:19], v[176:179], v[196:199], v[16:19]
	v_mfma_f32_16x16x32_bf16 v[20:23], v[180:183], v[196:199], v[20:23]
	v_mfma_f32_16x16x32_bf16 v[24:27], v[184:187], v[196:199], v[24:27]
	v_mfma_f32_16x16x32_bf16 v[28:31], v[188:191], v[196:199], v[28:31]
	ds_read_b128 v[136:139], v233 offset:2048
	ds_read_b128 v[140:143], v233 offset:3072
	s_add_u32 m0, s25, 4096
	s_nop 0
	global_load_lds_dwordx4 v225, s[0:1]
	v_mfma_f32_16x16x32_bf16 v[32:35], v[176:179], v[200:203], v[32:35]
	v_mfma_f32_16x16x32_bf16 v[36:39], v[180:183], v[200:203], v[36:39]
	v_mfma_f32_16x16x32_bf16 v[40:43], v[184:187], v[200:203], v[40:43]
	v_mfma_f32_16x16x32_bf16 v[44:47], v[188:191], v[200:203], v[44:47]
	ds_read_b128 v[144:147], v232 offset:0
	ds_read_b128 v[148:151], v232 offset:1024
	s_add_u32 m0, s25, 8192
	s_nop 0
	global_load_lds_dwordx4 v226, s[0:1]
	v_mfma_f32_16x16x32_bf16 v[48:51], v[176:179], v[204:207], v[48:51]
	v_mfma_f32_16x16x32_bf16 v[52:55], v[180:183], v[204:207], v[52:55]
	v_mfma_f32_16x16x32_bf16 v[56:59], v[184:187], v[204:207], v[56:59]
	v_mfma_f32_16x16x32_bf16 v[60:63], v[188:191], v[204:207], v[60:63]
	ds_read_b128 v[152:155], v232 offset:2048
	ds_read_b128 v[156:159], v232 offset:3072
	s_add_u32 m0, s25, 12288
	s_nop 0
	global_load_lds_dwordx4 v227, s[0:1]
	v_mfma_f32_16x16x32_bf16 v[64:67], v[176:179], v[208:211], v[64:67]
	v_mfma_f32_16x16x32_bf16 v[68:71], v[180:183], v[208:211], v[68:71]
; #define LWRITE(S, buf) do { bf16_t* sA_ = sbase + (buf) * BUF; bf16_t* sB_ = sA_ + 256 * PITCH; \
;     _Pragma("unroll") for (int i_ = 0; i_ < 4; ++i_) *(u32x4*)(sA_ + (sr + i_ * 64) * PITCH + scv * 8) = ra[S][i_]; \
;     _Pragma("unroll") for (int i_ = 0; i_ < 2; ++i_) *(u32x4*)(sB_ + (sr + i_ * 64) * PITCH + scv * 8) = rb[S][i_]; } while (0)
; template <class Epi>
; DI void gemm_tile(char* smem, const bf16_t* __restrict__ A0, int lda0, int ksplit, const bf16_t* __restrict__ A1, int lda1,
;                   const bf16_t* __restrict__ Bt, int K, int row0, int col0, const Epi& epi, int tid) {
;     ...
;   __syncthreads();
;   {
;     const int last = nk - 1;
;     GLOAD(0, 0);
;     __builtin_amdgcn_sched_barrier(0);
;     GLOAD(1, 1);
;     __builtin_amdgcn_sched_barrier(0);
;     LWRITE(0, 0);
;     __builtin_amdgcn_sched_barrier(0);
;     GLOAD(0, (2 < last ? 2 : last));
;     __builtin_amdgcn_sched_barrier(0);
;     __syncthreads();
;     for (int kt = 0; kt < nk; kt += 2) {
;       LWRITE(1, 1);
;       __builtin_amdgcn_sched_barrier(0);
;       GLOAD(1, (kt + 3 < last ? kt + 3 : last));
;       __builtin_amdgcn_sched_barrier(0);
;       COMPUTE(0);
;       __syncthreads();
;       LWRITE(0, 0);
;       __builtin_amdgcn_sched_barrier(0);
;       GLOAD(0, (kt + 4 < last ? kt + 4 : last));
;       __builtin_amdgcn_sched_barrier(0);
;       COMPUTE(1);
;       __syncthreads();
;     }
	v_mfma_f32_16x16x32_bf16 v[72:75], v[184:187], v[208:211], v[72:75]
	v_mfma_f32_16x16x32_bf16 v[76:79], v[188:191], v[208:211], v[76:79]
	ds_read_b128 v[160:163], v232 offset:4096
	s_add_u32 m0, s25, 16384
	s_nop 0
	global_load_lds_dwordx4 v228, s[2:3]
	v_mfma_f32_16x16x32_bf16 v[80:83], v[176:179], v[212:215], v[80:83]
	v_mfma_f32_16x16x32_bf16 v[84:87], v[180:183], v[212:215], v[84:87]
	v_mfma_f32_16x16x32_bf16 v[88:91], v[184:187], v[212:215], v[88:91]
	v_mfma_f32_16x16x32_bf16 v[92:95], v[188:191], v[212:215], v[92:95]
	ds_read_b128 v[164:167], v232 offset:5120
	s_add_u32 m0, s25, 20480
	s_nop 0
	global_load_lds_dwordx4 v229, s[2:3]
	v_mfma_f32_16x16x32_bf16 v[96:99], v[176:179], v[216:219], v[96:99]
	v_mfma_f32_16x16x32_bf16 v[100:103], v[180:183], v[216:219], v[100:103]
	v_mfma_f32_16x16x32_bf16 v[104:107], v[184:187], v[216:219], v[104:107]
	v_mfma_f32_16x16x32_bf16 v[108:111], v[188:191], v[216:219], v[108:111]
	ds_read_b128 v[168:171], v232 offset:6144
	s_add_u32 s0, s0, 64
	s_addc_u32 s1, s1, 0
	s_add_u32 s2, s2, 64
	s_addc_u32 s3, s3, 0
	s_add_u32 s98, s98, 1
	s_add_u32 s29, s29, 24576
	s_cmp_eq_u32 s29, 73728
	s_cselect_b32 s29, 0, s29
	s_add_u32 s30, s30, 24576
	s_cmp_eq_u32 s30, 73728
	s_cselect_b32 s30, 0, s30
	v_mfma_f32_16x16x32_bf16 v[112:115], v[176:179], v[220:223], v[112:115]
	v_mfma_f32_16x16x32_bf16 v[116:119], v[180:183], v[220:223], v[116:119]
	v_mfma_f32_16x16x32_bf16 v[120:123], v[184:187], v[220:223], v[120:123]
	v_mfma_f32_16x16x32_bf16 v[124:127], v[188:191], v[220:223], v[124:127]
	ds_read_b128 v[172:175], v232 offset:7168
	s_setprio 0
	s_add_u32 s31, s31, 2
	s_cmp_lt_u32 s31, 28
	s_cbranch_scc1 .Lg11_kloop
	s_waitcnt vmcnt(6)
	s_waitcnt lgkmcnt(0)
	s_barrier
	v_add_u32_e32 v232, s30, v230
	v_add_u32_e32 v233, s30, v231
	s_add_u32 s25, s29, s99
	s_setprio 1
	v_mfma_f32_16x16x32_bf16 v[0:3], v[128:131], v[144:147], v[0:3]
	v_mfma_f32_16x16x32_bf16 v[4:7], v[132:135], v[144:147], v[4:7]
	v_mfma_f32_16x16x32_bf16 v[8:11], v[136:139], v[144:147], v[8:11]
	v_mfma_f32_16x16x32_bf16 v[12:15], v[140:143], v[144:147], v[12:15]
	ds_read_b128 v[176:179], v233 offset:0
	ds_read_b128 v[180:183], v233 offset:1024
	s_add_u32 m0, s25, 0
	s_nop 0
	global_load_lds_dwordx4 v224, s[0:1]
	v_mfma_f32_16x16x32_bf16 v[16:19], v[128:131], v[148:151], v[16:19]
	v_mfma_f32_16x16x32_bf16 v[20:23], v[132:135], v[148:151], v[20:23]
	v_mfma_f32_16x16x32_bf16 v[24:27], v[136:139], v[148:151], v[24:27]
	v_mfma_f32_16x16x32_bf16 v[28:31], v[140:143], v[148:151], v[28:31]
	ds_read_b128 v[184:187], v233 offset:2048
	ds_read_b128 v[188:191], v233 offset:3072
	s_add_u32 m0, s25, 4096
	s_nop 0
	global_load_lds_dwordx4 v225, s[0:1]
	v_mfma_f32_16x16x32_bf16 v[32:35], v[128:131], v[152:155], v[32:35]
	v_mfma_f32_16x16x32_bf16 v[36:39], v[132:135], v[152:155], v[36:39]
	v_mfma_f32_16x16x32_bf16 v[40:43], v[136:139], v[152:155], v[40:43]
	v_mfma_f32_16x16x32_bf16 v[44:47], v[140:143], v[152:155], v[44:47]
	ds_read_b128 v[192:195], v232 offset:0
	ds_read_b128 v[196:199], v232 offset:1024
	s_add_u32 m0, s25, 8192
	s_nop 0
	global_load_lds_dwordx4 v226, s[0:1]
	v_mfma_f32_16x16x32_bf16 v[48:51], v[128:131], v[156:159], v[48:51]
	v_mfma_f32_16x16x32_bf16 v[52:55], v[132:135], v[156:159], v[52:55]
	v_mfma_f32_16x16x32_bf16 v[56:59], v[136:139], v[156:159], v[56:59]
	v_mfma_f32_16x16x32_bf16 v[60:63], v[140:143], v[156:159], v[60:63]
	ds_read_b128 v[200:203], v232 offset:2048
	ds_read_b128 v[204:207], v232 offset:3072
	s_add_u32 m0, s25, 12288
	s_nop 0
	global_load_lds_dwordx4 v227, s[0:1]
	v_mfma_f32_16x16x32_bf16 v[64:67], v[128:131], v[160:163], v[64:67]
	v_mfma_f32_16x16x32_bf16 v[68:71], v[132:135], v[160:163], v[68:71]
	v_mfma_f32_16x16x32_bf16 v[72:75], v[136:139], v[160:163], v[72:75]
	v_mfma_f32_16x16x32_bf16 v[76:79], v[140:143], v[160:163], v[76:79]
	ds_read_b128 v[208:211], v232 offset:4096
	s_add_u32 m0, s25, 16384
	s_nop 0
	global_load_lds_dwordx4 v228, s[2:3]
	v_mfma_f32_16x16x32_bf16 v[80:83], v[128:131], v[164:167], v[80:83]
	v_mfma_f32_16x16x32_bf16 v[84:87], v[132:135], v[164:167], v[84:87]
	v_mfma_f32_16x16x32_bf16 v[88:91], v[136:139], v[164:167], v[88:91]
	v_mfma_f32_16x16x32_bf16 v[92:95], v[140:143], v[164:167], v[92:95]
	ds_read_b128 v[212:215], v232 offset:5120
	s_add_u32 m0, s25, 20480
	s_nop 0
	global_load_lds_dwordx4 v229, s[2:3]
	v_mfma_f32_16x16x32_bf16 v[96:99], v[128:131], v[168:171], v[96:99]
	v_mfma_f32_16x16x32_bf16 v[100:103], v[132:135], v[168:171], v[100:103]
	v_mfma_f32_16x16x32_bf16 v[104:107], v[136:139], v[168:171], v[104:107]
	v_mfma_f32_16x16x32_bf16 v[108:111], v[140:143], v[168:171], v[108:111]
	ds_read_b128 v[216:219], v232 offset:6144
	s_add_u32 s0, s0, 64
	s_addc_u32 s1, s1, 0
	s_add_u32 s2, s2, 64
	s_addc_u32 s3, s3, 0
	s_add_u32 s98, s98, 1
	s_add_u32 s29, s29, 24576
	s_cmp_eq_u32 s29, 73728
	s_cselect_b32 s29, 0, s29
	s_add_u32 s30, s30, 24576
	s_cmp_eq_u32 s30, 73728
	s_cselect_b32 s30, 0, s30
	v_mfma_f32_16x16x32_bf16 v[112:115], v[128:131], v[172:175], v[112:115]
	v_mfma_f32_16x16x32_bf16 v[116:119], v[132:135], v[172:175], v[116:119]
	v_mfma_f32_16x16x32_bf16 v[120:123], v[136:139], v[172:175], v[120:123]
	v_mfma_f32_16x16x32_bf16 v[124:127], v[140:143], v[172:175], v[124:127]
	ds_read_b128 v[220:223], v232 offset:7168
	s_setprio 0
	s_waitcnt vmcnt(6)
	s_waitcnt lgkmcnt(0)
	s_barrier
; #define LWRITE(S, buf) do { bf16_t* sA_ = sbase + (buf) * BUF; bf16_t* sB_ = sA_ + 256 * PITCH; \
;     _Pragma("unroll") for (int i_ = 0; i_ < 4; ++i_) *(u32x4*)(sA_ + (sr + i_ * 64) * PITCH + scv * 8) = ra[S][i_]; \
;     _Pragma("unroll") for (int i_ = 0; i_ < 2; ++i_) *(u32x4*)(sB_ + (sr + i_ * 64) * PITCH + scv * 8) = rb[S][i_]; } while (0)
; template <class Epi>
; DI void gemm_tile(char* smem, const bf16_t* __restrict__ A0, int lda0, int ksplit, const bf16_t* __restrict__ A1, int lda1,
;                   const bf16_t* __restrict__ Bt, int K, int row0, int col0, const Epi& epi, int tid) {
;     ...
;   __syncthreads();
;   {
;     const int last = nk - 1;
;     GLOAD(0, 0);
;     __builtin_amdgcn_sched_barrier(0);
;     GLOAD(1, 1);
;     __builtin_amdgcn_sched_barrier(0);
;     LWRITE(0, 0);
;     __builtin_amdgcn_sched_barrier(0);
;     GLOAD(0, (2 < last ? 2 : last));
;     __builtin_amdgcn_sched_barrier(0);
;     __syncthreads();
;     for (int kt = 0; kt < nk; kt += 2) {
;       LWRITE(1, 1);
;       __builtin_amdgcn_sched_barrier(0);
;       GLOAD(1, (kt + 3 < last ? kt + 3 : last));
;       __builtin_amdgcn_sched_barrier(0);
;       COMPUTE(0);
;       __syncthreads();
;       LWRITE(0, 0);
;       __builtin_amdgcn_sched_barrier(0);
;       GLOAD(0, (kt + 4 < last ? kt + 4 : last));
;       __builtin_amdgcn_sched_barrier(0);
;       COMPUTE(1);
;       __syncthreads();
;     }
	v_add_u32_e32 v232, s30, v230
	v_add_u32_e32 v233, s30, v231
	s_setprio 1
	v_mfma_f32_16x16x32_bf16 v[0:3], v[176:179], v[192:195], v[0:3]
	v_mfma_f32_16x16x32_bf16 v[4:7], v[180:183], v[192:195], v[4:7]
	v_mfma_f32_16x16x32_bf16 v[8:11], v[184:187], v[192:195], v[8:11]
	v_mfma_f32_16x16x32_bf16 v[12:15], v[188:191], v[192:195], v[12:15]
	ds_read_b128 v[128:131], v233 offset:0
	ds_read_b128 v[132:135], v233 offset:1024
	v_mfma_f32_16x16x32_bf16 v[16:19], v[176:179], v[196:199], v[16:19]
	v_mfma_f32_16x16x32_bf16 v[20:23], v[180:183], v[196:199], v[20:23]
	v_mfma_f32_16x16x32_bf16 v[24:27], v[184:187], v[196:199], v[24:27]
	v_mfma_f32_16x16x32_bf16 v[28:31], v[188:191], v[196:199], v[28:31]
	ds_read_b128 v[136:139], v233 offset:2048
	ds_read_b128 v[140:143], v233 offset:3072
	v_mfma_f32_16x16x32_bf16 v[32:35], v[176:179], v[200:203], v[32:35]
	v_mfma_f32_16x16x32_bf16 v[36:39], v[180:183], v[200:203], v[36:39]
	v_mfma_f32_16x16x32_bf16 v[40:43], v[184:187], v[200:203], v[40:43]
	v_mfma_f32_16x16x32_bf16 v[44:47], v[188:191], v[200:203], v[44:47]
	ds_read_b128 v[144:147], v232 offset:0
	ds_read_b128 v[148:151], v232 offset:1024
	v_mfma_f32_16x16x32_bf16 v[48:51], v[176:179], v[204:207], v[48:51]
	v_mfma_f32_16x16x32_bf16 v[52:55], v[180:183], v[204:207], v[52:55]
	v_mfma_f32_16x16x32_bf16 v[56:59], v[184:187], v[204:207], v[56:59]
	v_mfma_f32_16x16x32_bf16 v[60:63], v[188:191], v[204:207], v[60:63]
	ds_read_b128 v[152:155], v232 offset:2048
	ds_read_b128 v[156:159], v232 offset:3072
	v_mfma_f32_16x16x32_bf16 v[64:67], v[176:179], v[208:211], v[64:67]
	v_mfma_f32_16x16x32_bf16 v[68:71], v[180:183], v[208:211], v[68:71]
	v_mfma_f32_16x16x32_bf16 v[72:75], v[184:187], v[208:211], v[72:75]
	v_mfma_f32_16x16x32_bf16 v[76:79], v[188:191], v[208:211], v[76:79]
	ds_read_b128 v[160:163], v232 offset:4096
	v_mfma_f32_16x16x32_bf16 v[80:83], v[176:179], v[212:215], v[80:83]
	v_mfma_f32_16x16x32_bf16 v[84:87], v[180:183], v[212:215], v[84:87]
	v_mfma_f32_16x16x32_bf16 v[88:91], v[184:187], v[212:215], v[88:91]
	v_mfma_f32_16x16x32_bf16 v[92:95], v[188:191], v[212:215], v[92:95]
	ds_read_b128 v[164:167], v232 offset:5120
	v_mfma_f32_16x16x32_bf16 v[96:99], v[176:179], v[216:219], v[96:99]
	v_mfma_f32_16x16x32_bf16 v[100:103], v[180:183], v[216:219], v[100:103]
	v_mfma_f32_16x16x32_bf16 v[104:107], v[184:187], v[216:219], v[104:107]
	v_mfma_f32_16x16x32_bf16 v[108:111], v[188:191], v[216:219], v[108:111]
	ds_read_b128 v[168:171], v232 offset:6144
	s_add_u32 s30, s30, 24576
	s_cmp_eq_u32 s30, 73728
	s_cselect_b32 s30, 0, s30
	v_mfma_f32_16x16x32_bf16 v[112:115], v[176:179], v[220:223], v[112:115]
	v_mfma_f32_16x16x32_bf16 v[116:119], v[180:183], v[220:223], v[116:119]
	v_mfma_f32_16x16x32_bf16 v[120:123], v[184:187], v[220:223], v[120:123]
	v_mfma_f32_16x16x32_bf16 v[124:127], v[188:191], v[220:223], v[124:127]
	ds_read_b128 v[172:175], v232 offset:7168
	s_setprio 0
	s_waitcnt vmcnt(0)
	s_waitcnt lgkmcnt(0)
	s_barrier
; #define LWRITE(S, buf) do { bf16_t* sA_ = sbase + (buf) * BUF; bf16_t* sB_ = sA_ + 256 * PITCH; \
;     _Pragma("unroll") for (int i_ = 0; i_ < 4; ++i_) *(u32x4*)(sA_ + (sr + i_ * 64) * PITCH + scv * 8) = ra[S][i_]; \
;     _Pragma("unroll") for (int i_ = 0; i_ < 2; ++i_) *(u32x4*)(sB_ + (sr + i_ * 64) * PITCH + scv * 8) = rb[S][i_]; } while (0)
; template <class Epi>
; DI void gemm_tile(char* smem, const bf16_t* __restrict__ A0, int lda0, int ksplit, const bf16_t* __restrict__ A1, int lda1,
;                   const bf16_t* __restrict__ Bt, int K, int row0, int col0, const Epi& epi, int tid) {
;     ...
;   __syncthreads();
;   {
;     const int last = nk - 1;
;     GLOAD(0, 0);
;     __builtin_amdgcn_sched_barrier(0);
;     GLOAD(1, 1);
;     __builtin_amdgcn_sched_barrier(0);
;     LWRITE(0, 0);
;     __builtin_amdgcn_sched_barrier(0);
;     GLOAD(0, (2 < last ? 2 : last));
;     __builtin_amdgcn_sched_barrier(0);
;     __syncthreads();
;     for (int kt = 0; kt < nk; kt += 2) {
;       LWRITE(1, 1);
;       __builtin_amdgcn_sched_barrier(0);
;       GLOAD(1, (kt + 3 < last ? kt + 3 : last));
;       __builtin_amdgcn_sched_barrier(0);
;       COMPUTE(0);
;       __syncthreads();
;       LWRITE(0, 0);
;       __builtin_amdgcn_sched_barrier(0);
;       GLOAD(0, (kt + 4 < last ? kt + 4 : last));
;       __builtin_amdgcn_sched_barrier(0);
;       COMPUTE(1);
;       __syncthreads();
;     }
	v_add_u32_e32 v232, s30, v230
	v_add_u32_e32 v233, s30, v231
	s_setprio 1
	v_mfma_f32_16x16x32_bf16 v[0:3], v[128:131], v[144:147], v[0:3]
	v_mfma_f32_16x16x32_bf16 v[4:7], v[132:135], v[144:147], v[4:7]
	v_mfma_f32_16x16x32_bf16 v[8:11], v[136:139], v[144:147], v[8:11]
	v_mfma_f32_16x16x32_bf16 v[12:15], v[140:143], v[144:147], v[12:15]
	ds_read_b128 v[176:179], v233 offset:0
	ds_read_b128 v[180:183], v233 offset:1024
	v_mfma_f32_16x16x32_bf16 v[16:19], v[128:131], v[148:151], v[16:19]
	v_mfma_f32_16x16x32_bf16 v[20:23], v[132:135], v[148:151], v[20:23]
	v_mfma_f32_16x16x32_bf16 v[24:27], v[136:139], v[148:151], v[24:27]
	v_mfma_f32_16x16x32_bf16 v[28:31], v[140:143], v[148:151], v[28:31]
	ds_read_b128 v[184:187], v233 offset:2048
	ds_read_b128 v[188:191], v233 offset:3072
	v_mfma_f32_16x16x32_bf16 v[32:35], v[128:131], v[152:155], v[32:35]
	v_mfma_f32_16x16x32_bf16 v[36:39], v[132:135], v[152:155], v[36:39]
	v_mfma_f32_16x16x32_bf16 v[40:43], v[136:139], v[152:155], v[40:43]
	v_mfma_f32_16x16x32_bf16 v[44:47], v[140:143], v[152:155], v[44:47]
	ds_read_b128 v[192:195], v232 offset:0
	ds_read_b128 v[196:199], v232 offset:1024
	v_mfma_f32_16x16x32_bf16 v[48:51], v[128:131], v[156:159], v[48:51]
	v_mfma_f32_16x16x32_bf16 v[52:55], v[132:135], v[156:159], v[52:55]
	v_mfma_f32_16x16x32_bf16 v[56:59], v[136:139], v[156:159], v[56:59]
	v_mfma_f32_16x16x32_bf16 v[60:63], v[140:143], v[156:159], v[60:63]
	ds_read_b128 v[200:203], v232 offset:2048
	ds_read_b128 v[204:207], v232 offset:3072
	v_mfma_f32_16x16x32_bf16 v[64:67], v[128:131], v[160:163], v[64:67]
	v_mfma_f32_16x16x32_bf16 v[68:71], v[132:135], v[160:163], v[68:71]
	v_mfma_f32_16x16x32_bf16 v[72:75], v[136:139], v[160:163], v[72:75]
	v_mfma_f32_16x16x32_bf16 v[76:79], v[140:143], v[160:163], v[76:79]
	ds_read_b128 v[208:211], v232 offset:4096
	v_mfma_f32_16x16x32_bf16 v[80:83], v[128:131], v[164:167], v[80:83]
	v_mfma_f32_16x16x32_bf16 v[84:87], v[132:135], v[164:167], v[84:87]
	v_mfma_f32_16x16x32_bf16 v[88:91], v[136:139], v[164:167], v[88:91]
	v_mfma_f32_16x16x32_bf16 v[92:95], v[140:143], v[164:167], v[92:95]
	ds_read_b128 v[212:215], v232 offset:5120
	v_mfma_f32_16x16x32_bf16 v[96:99], v[128:131], v[168:171], v[96:99]
	v_mfma_f32_16x16x32_bf16 v[100:103], v[132:135], v[168:171], v[100:103]
	v_mfma_f32_16x16x32_bf16 v[104:107], v[136:139], v[168:171], v[104:107]
	v_mfma_f32_16x16x32_bf16 v[108:111], v[140:143], v[168:171], v[108:111]
	ds_read_b128 v[216:219], v232 offset:6144
	s_add_u32 s30, s30, 24576
	s_cmp_eq_u32 s30, 73728
	s_cselect_b32 s30, 0, s30
	v_mfma_f32_16x16x32_bf16 v[112:115], v[128:131], v[172:175], v[112:115]
	v_mfma_f32_16x16x32_bf16 v[116:119], v[132:135], v[172:175], v[116:119]
	v_mfma_f32_16x16x32_bf16 v[120:123], v[136:139], v[172:175], v[120:123]
	v_mfma_f32_16x16x32_bf16 v[124:127], v[140:143], v[172:175], v[124:127]
	ds_read_b128 v[220:223], v232 offset:7168
	s_setprio 0
	s_waitcnt lgkmcnt(0)
	s_barrier
	s_setprio 1
	v_mfma_f32_16x16x32_bf16 v[0:3], v[176:179], v[192:195], v[0:3]
	v_mfma_f32_16x16x32_bf16 v[4:7], v[180:183], v[192:195], v[4:7]
	v_mfma_f32_16x16x32_bf16 v[8:11], v[184:187], v[192:195], v[8:11]
	v_mfma_f32_16x16x32_bf16 v[12:15], v[188:191], v[192:195], v[12:15]
	v_mfma_f32_16x16x32_bf16 v[16:19], v[176:179], v[196:199], v[16:19]
	v_mfma_f32_16x16x32_bf16 v[20:23], v[180:183], v[196:199], v[20:23]
	v_mfma_f32_16x16x32_bf16 v[24:27], v[184:187], v[196:199], v[24:27]
	v_mfma_f32_16x16x32_bf16 v[28:31], v[188:191], v[196:199], v[28:31]
	v_mfma_f32_16x16x32_bf16 v[32:35], v[176:179], v[200:203], v[32:35]
	v_mfma_f32_16x16x32_bf16 v[36:39], v[180:183], v[200:203], v[36:39]
	v_mfma_f32_16x16x32_bf16 v[40:43], v[184:187], v[200:203], v[40:43]
	v_mfma_f32_16x16x32_bf16 v[44:47], v[188:191], v[200:203], v[44:47]
	v_mfma_f32_16x16x32_bf16 v[48:51], v[176:179], v[204:207], v[48:51]
	v_mfma_f32_16x16x32_bf16 v[52:55], v[180:183], v[204:207], v[52:55]
	v_mfma_f32_16x16x32_bf16 v[56:59], v[184:187], v[204:207], v[56:59]
	v_mfma_f32_16x16x32_bf16 v[60:63], v[188:191], v[204:207], v[60:63]
	v_mfma_f32_16x16x32_bf16 v[64:67], v[176:179], v[208:211], v[64:67]
	v_mfma_f32_16x16x32_bf16 v[68:71], v[180:183], v[208:211], v[68:71]
	v_mfma_f32_16x16x32_bf16 v[72:75], v[184:187], v[208:211], v[72:75]
	v_mfma_f32_16x16x32_bf16 v[76:79], v[188:191], v[208:211], v[76:79]
	v_mfma_f32_16x16x32_bf16 v[80:83], v[176:179], v[212:215], v[80:83]
	v_mfma_f32_16x16x32_bf16 v[84:87], v[180:183], v[212:215], v[84:87]
	v_mfma_f32_16x16x32_bf16 v[88:91], v[184:187], v[212:215], v[88:91]
	v_mfma_f32_16x16x32_bf16 v[92:95], v[188:191], v[212:215], v[92:95]
	v_mfma_f32_16x16x32_bf16 v[96:99], v[176:179], v[216:219], v[96:99]
	v_mfma_f32_16x16x32_bf16 v[100:103], v[180:183], v[216:219], v[100:103]
	v_mfma_f32_16x16x32_bf16 v[104:107], v[184:187], v[216:219], v[104:107]
	v_mfma_f32_16x16x32_bf16 v[108:111], v[188:191], v[216:219], v[108:111]
	v_mfma_f32_16x16x32_bf16 v[112:115], v[176:179], v[220:223], v[112:115]
	v_mfma_f32_16x16x32_bf16 v[116:119], v[180:183], v[220:223], v[116:119]
	v_mfma_f32_16x16x32_bf16 v[120:123], v[184:187], v[220:223], v[120:123]
	v_mfma_f32_16x16x32_bf16 v[124:127], v[188:191], v[220:223], v[124:127]
	s_setprio 0
	s_branch .Lg11_epi

; #define PH(k) case k: if (ONLY_PHASE >= 0 && ONLY_PHASE != k) break;
; template <class Epi>
; DI void gemm_tile(char* smem, const bf16_t* __restrict__ A0, int lda0, int ksplit, const bf16_t* __restrict__ A1, int lda1,
;                   const bf16_t* __restrict__ Bt, int K, int row0, int col0, const Epi& epi, int tid) {
;   constexpr int BK = 32, PITCH = 40, BUF = (256 + 128) * PITCH;
;   bf16_t* sbase = (bf16_t*)smem;
;   const int lane = tid & 63, wid = tid >> 6, wr = wid >> 1, wc = wid & 1, fr = lane & 15, fq = lane >> 4;
;   f32x4 acc[8][4];
; #pragma unroll
;   for (int m = 0; m < 8; ++m)
; #pragma unroll
;     for (int n = 0; n < 4; ++n) acc[m][n] = (f32x4){0.f, 0.f, 0.f, 0.f};
;   u32x4 ra[2][4], rb[2][2];
;   const int nk = K / BK;
;   const int sr = tid >> 2, scv = tid & 3;
; template <int ph> DI void run_phase(const Ctx& c, char* smem) {
;     ...
;     PH(14) gemm_phase(smem, (const bf16_t*)(ws + OFF_YG), 512, 1 << 30, XN, 1024, (const bf16_t*)(ws + OFF_WGLU), 512, 4,
;                         EpiGlu{(const bf16_t*)(ws + OFF_YG), p.s5_glu_b, (bf16_t*)(ws + OFF_S5Y)}, TIDX); break;
.LBB0_1816:
	s_cmp_gt_i32 s94, 14
	s_cselect_b64 s[0:1], -1, 0
	s_cmp_lt_i32 s95, 15
	s_cselect_b64 s[2:3], -1, 0
	s_or_b64 s[0:1], s[0:1], s[2:3]
	v_readlane_b32 s36, v252, 8
	s_and_b64 vcc, exec, s[0:1]
	v_readlane_b32 s40, v252, 12
	v_readlane_b32 s41, v252, 13
	v_readlane_b32 s42, v252, 14
	v_readlane_b32 s43, v252, 15
	v_readlane_b32 s37, v252, 9
	v_readlane_b32 s38, v252, 10
	v_readlane_b32 s39, v252, 11
	v_readlane_b32 s44, v252, 16
	v_readlane_b32 s45, v252, 17
	v_readlane_b32 s46, v252, 18
	v_readlane_b32 s47, v252, 19
	v_readlane_b32 s48, v252, 20
	v_readlane_b32 s49, v252, 21
	v_readlane_b32 s50, v252, 22
	v_readlane_b32 s51, v252, 23
	s_cbranch_vccnz .LBB0_1844
	s_add_u32 s2, s92, 0x1da00000
	s_waitcnt lgkmcnt(0)
	s_load_dword s14, s[74:75], 0x180
	s_addc_u32 s3, s93, 0
	s_add_u32 s0, s92, 0x3400000
	s_addc_u32 s1, s93, 0
	s_add_u32 s4, s92, 0x11a00000
	s_addc_u32 s5, s93, 0
	s_and_b32 s16, s72, 0xffffffc0
	v_mbcnt_hi_u32_b32 v195, -1, v194
	s_waitcnt lgkmcnt(0)
	s_and_b32 s15, s14, 7
	s_cmp_lg_u32 s15, 0
	s_waitcnt vmcnt(16)
	v_add_u32_e32 v196, s16, v195
	v_mbcnt_lo_u32_b32 v240, -1, 0
	v_mbcnt_hi_u32_b32 v240, -1, v240
	s_lshr_b32 s12, s72, 6
	s_lshl_b32 s101, s12, 10
	v_and_b32_e32 v241, 15, v240
	v_lshrrev_b32_e32 v242, 4, v240
	v_bfe_u32 v243, v240, 3, 1
	v_mul_u32_u24_e32 v243, 3, v243
	v_xor_b32_e32 v243, v242, v243
	v_lshlrev_b32_e32 v243, 4, v243
	v_lshl_add_u32 v243, v241, 6, v243
	s_lshr_b32 s11, s12, 1
	s_lshl_b32 s11, s11, 13
	v_add_u32_e32 v230, s11, v243
	s_and_b32 s11, s12, 1
	s_lshl_b32 s11, s11, 12
	s_add_u32 s11, s11, 16384
	v_add_u32_e32 v231, s11, v243
	s_lshr_b32 s11, s12, 1
	s_lshl_b32 s11, s11, 7
	v_add_u32_e32 v244, s11, v241
	s_and_b32 s11, s12, 1
	s_lshl_b32 s11, s11, 6
	v_lshl_add_u32 v245, v242, 2, s11
	s_movk_i32 s11, 0x1000
	v_mul_lo_u32 v246, v244, s11
	v_lshl_add_u32 v234, v245, 2, v246
	v_lshrrev_b32_e32 v241, 2, v240
	s_lshl_b32 s11, s12, 4
	v_add_u32_e32 v241, s11, v241
	v_bfe_u32 v242, v240, 5, 1
	v_mul_u32_u24_e32 v242, 3, v242
	v_and_b32_e32 v243, 3, v240
	v_xor_b32_e32 v243, v243, v242
	v_lshlrev_b32_e32 v243, 4, v243
	s_mov_b32 s11, 1024
	v_mad_u32_u24 v224, v241, s11, v243
	v_add_u32_e32 v225, 0x10000, v224
	v_add_u32_e32 v226, 0x20000, v224
	v_add_u32_e32 v227, 0x30000, v224
	s_mov_b32 s11, 1024
	v_mad_u32_u24 v228, v241, s11, v243
	v_add_u32_e32 v229, 0x10000, v228
	s_load_dwordx2 s[6:7], s[74:75], 0x118
	v_mbcnt_lo_u32_b32 v240, -1, 0
	v_mbcnt_hi_u32_b32 v240, -1, v240
	s_lshr_b32 s12, s72, 6
	s_mul_i32 s11, s12, 17408
	v_and_b32_e32 v241, 15, v240
	v_lshrrev_b32_e32 v242, 4, v240
	v_mul_u32_u24_e32 v243, 0x110, v241
	v_lshl_add_u32 v243, v242, 4, v243
	v_add_u32_e32 v245, s11, v243
	v_mul_u32_u24_e32 v243, 0x110, v242
	v_lshl_add_u32 v243, v241, 4, v243
	v_add_u32_e32 v246, s11, v243
	s_lshr_b32 s11, s12, 1
	s_lshl_b32 s11, s11, 7
	v_add_u32_e32 v243, s11, v242
	v_lshlrev_b32_e32 v243, 12, v243
	s_and_b32 s11, s12, 1
	s_lshl_b32 s11, s11, 8
	v_lshl_add_u32 v244, v241, 4, s11
	v_add_u32_e32 v247, v243, v244
	v_lshrrev_b32_e32 v243, 2, v243
	v_lshrrev_b32_e32 v235, 1, v244
	v_add_u32_e32 v235, v243, v235
	v_mov_b32_e32 v234, v244
	s_cmpk_gt_u32 s96, 0xff
	s_cbranch_scc0 .Lg14_prio
	s_setprio 1

; #define LWRITE(S, buf) do { bf16_t* sA_ = sbase + (buf) * BUF; bf16_t* sB_ = sA_ + 256 * PITCH; \
;     _Pragma("unroll") for (int i_ = 0; i_ < 4; ++i_) *(u32x4*)(sA_ + (sr + i_ * 64) * PITCH + scv * 8) = ra[S][i_]; \
;     _Pragma("unroll") for (int i_ = 0; i_ < 2; ++i_) *(u32x4*)(sB_ + (sr + i_ * 64) * PITCH + scv * 8) = rb[S][i_]; } while (0)
; template <class Epi>
; DI void gemm_tile(char* smem, const bf16_t* __restrict__ A0, int lda0, int ksplit, const bf16_t* __restrict__ A1, int lda1,
;                   const bf16_t* __restrict__ Bt, int K, int row0, int col0, const Epi& epi, int tid) {
;     ...
;   __syncthreads();
;   {
;     const int last = nk - 1;
;     GLOAD(0, 0);
;     __builtin_amdgcn_sched_barrier(0);
;     GLOAD(1, 1);
;     __builtin_amdgcn_sched_barrier(0);
;     LWRITE(0, 0);
;     __builtin_amdgcn_sched_barrier(0);
;     GLOAD(0, (2 < last ? 2 : last));
;     __builtin_amdgcn_sched_barrier(0);
;     __syncthreads();
;     for (int kt = 0; kt < nk; kt += 2) {
;       LWRITE(1, 1);
;       __builtin_amdgcn_sched_barrier(0);
;       GLOAD(1, (kt + 3 < last ? kt + 3 : last));
;       __builtin_amdgcn_sched_barrier(0);
;       COMPUTE(0);
;       __syncthreads();
;       LWRITE(0, 0);
;       __builtin_amdgcn_sched_barrier(0);
;       GLOAD(0, (kt + 4 < last ? kt + 4 : last));
;       __builtin_amdgcn_sched_barrier(0);
;       COMPUTE(1);
;       __syncthreads();
.Lg14_kloop:
	s_waitcnt vmcnt(6)
	s_waitcnt lgkmcnt(0)
	s_barrier
	v_add_u32_e32 v232, s98, v230
	v_add_u32_e32 v233, s98, v231
	s_add_u32 s11, s19, s101
	s_setprio 1
	v_mfma_f32_16x16x32_bf16 v[0:3], v[128:131], v[144:147], v[0:3]
	v_mfma_f32_16x16x32_bf16 v[4:7], v[132:135], v[144:147], v[4:7]
	v_mfma_f32_16x16x32_bf16 v[8:11], v[136:139], v[144:147], v[8:11]
	v_mfma_f32_16x16x32_bf16 v[12:15], v[140:143], v[144:147], v[12:15]
	ds_read_b128 v[176:179], v233 offset:0
	ds_read_b128 v[180:183], v233 offset:1024
	s_add_u32 m0, s11, 0
	s_nop 0
	global_load_lds_dwordx4 v224, s[0:1]
	v_mfma_f32_16x16x32_bf16 v[16:19], v[128:131], v[148:151], v[16:19]
	v_mfma_f32_16x16x32_bf16 v[20:23], v[132:135], v[148:151], v[20:23]
	v_mfma_f32_16x16x32_bf16 v[24:27], v[136:139], v[148:151], v[24:27]
	v_mfma_f32_16x16x32_bf16 v[28:31], v[140:143], v[148:151], v[28:31]
	ds_read_b128 v[184:187], v233 offset:2048
	ds_read_b128 v[188:191], v233 offset:3072
	s_add_u32 m0, s11, 4096
	s_nop 0
	global_load_lds_dwordx4 v225, s[0:1]
	v_mfma_f32_16x16x32_bf16 v[32:35], v[128:131], v[152:155], v[32:35]
	v_mfma_f32_16x16x32_bf16 v[36:39], v[132:135], v[152:155], v[36:39]
	v_mfma_f32_16x16x32_bf16 v[40:43], v[136:139], v[152:155], v[40:43]
	v_mfma_f32_16x16x32_bf16 v[44:47], v[140:143], v[152:155], v[44:47]
	ds_read_b128 v[192:195], v232 offset:0
	ds_read_b128 v[196:199], v232 offset:1024
	s_add_u32 m0, s11, 8192
	s_nop 0
	global_load_lds_dwordx4 v226, s[0:1]
	v_mfma_f32_16x16x32_bf16 v[48:51], v[128:131], v[156:159], v[48:51]
	v_mfma_f32_16x16x32_bf16 v[52:55], v[132:135], v[156:159], v[52:55]
	v_mfma_f32_16x16x32_bf16 v[56:59], v[136:139], v[156:159], v[56:59]
	v_mfma_f32_16x16x32_bf16 v[60:63], v[140:143], v[156:159], v[60:63]
	ds_read_b128 v[200:203], v232 offset:2048
	ds_read_b128 v[204:207], v232 offset:3072
	s_add_u32 m0, s11, 12288
	s_nop 0
	global_load_lds_dwordx4 v227, s[0:1]
	v_mfma_f32_16x16x32_bf16 v[64:67], v[128:131], v[160:163], v[64:67]
	v_mfma_f32_16x16x32_bf16 v[68:71], v[132:135], v[160:163], v[68:71]
	v_mfma_f32_16x16x32_bf16 v[72:75], v[136:139], v[160:163], v[72:75]
	v_mfma_f32_16x16x32_bf16 v[76:79], v[140:143], v[160:163], v[76:79]
	ds_read_b128 v[208:211], v232 offset:4096
	s_add_u32 m0, s11, 16384
	s_nop 0
	global_load_lds_dwordx4 v228, s[2:3]
	v_mfma_f32_16x16x32_bf16 v[80:83], v[128:131], v[164:167], v[80:83]
	v_mfma_f32_16x16x32_bf16 v[84:87], v[132:135], v[164:167], v[84:87]
	v_mfma_f32_16x16x32_bf16 v[88:91], v[136:139], v[164:167], v[88:91]
	v_mfma_f32_16x16x32_bf16 v[92:95], v[140:143], v[164:167], v[92:95]
	ds_read_b128 v[212:215], v232 offset:5120
	s_add_u32 m0, s11, 20480
	s_nop 0
	global_load_lds_dwordx4 v229, s[2:3]
	v_mfma_f32_16x16x32_bf16 v[96:99], v[128:131], v[168:171], v[96:99]
	v_mfma_f32_16x16x32_bf16 v[100:103], v[132:135], v[168:171], v[100:103]
	v_mfma_f32_16x16x32_bf16 v[104:107], v[136:139], v[168:171], v[104:107]
	v_mfma_f32_16x16x32_bf16 v[108:111], v[140:143], v[168:171], v[108:111]
	ds_read_b128 v[216:219], v232 offset:6144
	s_add_u32 s0, s0, 64
	s_addc_u32 s1, s1, 0
	s_add_u32 s2, s2, 64
	s_addc_u32 s3, s3, 0
	s_add_u32 s100, s100, 1
	s_add_u32 s19, s19, 24576
	s_cmp_eq_u32 s19, 73728
	s_cselect_b32 s19, 0, s19
	s_add_u32 s98, s98, 24576
	s_cmp_eq_u32 s98, 73728
	s_cselect_b32 s98, 0, s98
	v_mfma_f32_16x16x32_bf16 v[112:115], v[128:131], v[172:175], v[112:115]
	v_mfma_f32_16x16x32_bf16 v[116:119], v[132:135], v[172:175], v[116:119]
	v_mfma_f32_16x16x32_bf16 v[120:123], v[136:139], v[172:175], v[120:123]
	v_mfma_f32_16x16x32_bf16 v[124:127], v[140:143], v[172:175], v[124:127]
	ds_read_b128 v[220:223], v232 offset:7168
	s_setprio 0
	s_waitcnt vmcnt(6)
	s_waitcnt lgkmcnt(0)
	s_barrier
	v_add_u32_e32 v232, s98, v230
	v_add_u32_e32 v233, s98, v231
	s_add_u32 s11, s19, s101
	s_setprio 1
	v_mfma_f32_16x16x32_bf16 v[0:3], v[176:179], v[192:195], v[0:3]
	v_mfma_f32_16x16x32_bf16 v[4:7], v[180:183], v[192:195], v[4:7]
	v_mfma_f32_16x16x32_bf16 v[8:11], v[184:187], v[192:195], v[8:11]
	v_mfma_f32_16x16x32_bf16 v[12:15], v[188:191], v[192:195], v[12:15]
	ds_read_b128 v[128:131], v233 offset:0
	ds_read_b128 v[132:135], v233 offset:1024
	s_add_u32 m0, s11, 0
	s_nop 0
	global_load_lds_dwordx4 v224, s[0:1]
	v_mfma_f32_16x16x32_bf16 v[16:19], v[176:179], v[196:199], v[16:19]
	v_mfma_f32_16x16x32_bf16 v[20:23], v[180:183], v[196:199], v[20:23]
	v_mfma_f32_16x16x32_bf16 v[24:27], v[184:187], v[196:199], v[24:27]
	v_mfma_f32_16x16x32_bf16 v[28:31], v[188:191], v[196:199], v[28:31]
	ds_read_b128 v[136:139], v233 offset:2048
	ds_read_b128 v[140:143], v233 offset:3072
	s_add_u32 m0, s11, 4096
	s_nop 0
	global_load_lds_dwordx4 v225, s[0:1]
	v_mfma_f32_16x16x32_bf16 v[32:35], v[176:179], v[200:203], v[32:35]
	v_mfma_f32_16x16x32_bf16 v[36:39], v[180:183], v[200:203], v[36:39]
	v_mfma_f32_16x16x32_bf16 v[40:43], v[184:187], v[200:203], v[40:43]
	v_mfma_f32_16x16x32_bf16 v[44:47], v[188:191], v[200:203], v[44:47]
	ds_read_b128 v[144:147], v232 offset:0
	ds_read_b128 v[148:151], v232 offset:1024
	s_add_u32 m0, s11, 8192
	s_nop 0
	global_load_lds_dwordx4 v226, s[0:1]
	v_mfma_f32_16x16x32_bf16 v[48:51], v[176:179], v[204:207], v[48:51]
	v_mfma_f32_16x16x32_bf16 v[52:55], v[180:183], v[204:207], v[52:55]
	v_mfma_f32_16x16x32_bf16 v[56:59], v[184:187], v[204:207], v[56:59]
	v_mfma_f32_16x16x32_bf16 v[60:63], v[188:191], v[204:207], v[60:63]
	ds_read_b128 v[152:155], v232 offset:2048
	ds_read_b128 v[156:159], v232 offset:3072
	s_add_u32 m0, s11, 12288
	s_nop 0
	global_load_lds_dwordx4 v227, s[0:1]
	v_mfma_f32_16x16x32_bf16 v[64:67], v[176:179], v[208:211], v[64:67]
	v_mfma_f32_16x16x32_bf16 v[68:71], v[180:183], v[208:211], v[68:71]
; #define LWRITE(S, buf) do { bf16_t* sA_ = sbase + (buf) * BUF; bf16_t* sB_ = sA_ + 256 * PITCH; \
;     _Pragma("unroll") for (int i_ = 0; i_ < 4; ++i_) *(u32x4*)(sA_ + (sr + i_ * 64) * PITCH + scv * 8) = ra[S][i_]; \
;     _Pragma("unroll") for (int i_ = 0; i_ < 2; ++i_) *(u32x4*)(sB_ + (sr + i_ * 64) * PITCH + scv * 8) = rb[S][i_]; } while (0)
; template <class Epi>
; DI void gemm_tile(char* smem, const bf16_t* __restrict__ A0, int lda0, int ksplit, const bf16_t* __restrict__ A1, int lda1,
;                   const bf16_t* __restrict__ Bt, int K, int row0, int col0, const Epi& epi, int tid) {
;     ...
;   __syncthreads();
;   {
;     const int last = nk - 1;
;     GLOAD(0, 0);
;     __builtin_amdgcn_sched_barrier(0);
;     GLOAD(1, 1);
;     __builtin_amdgcn_sched_barrier(0);
;     LWRITE(0, 0);
;     __builtin_amdgcn_sched_barrier(0);
;     GLOAD(0, (2 < last ? 2 : last));
;     __builtin_amdgcn_sched_barrier(0);
;     __syncthreads();
;     for (int kt = 0; kt < nk; kt += 2) {
;       LWRITE(1, 1);
;       __builtin_amdgcn_sched_barrier(0);
;       GLOAD(1, (kt + 3 < last ? kt + 3 : last));
;       __builtin_amdgcn_sched_barrier(0);
;       COMPUTE(0);
;       __syncthreads();
;       LWRITE(0, 0);
;       __builtin_amdgcn_sched_barrier(0);
;       GLOAD(0, (kt + 4 < last ? kt + 4 : last));
;       __builtin_amdgcn_sched_barrier(0);
;       COMPUTE(1);
;       __syncthreads();
;     }
	v_mfma_f32_16x16x32_bf16 v[72:75], v[184:187], v[208:211], v[72:75]
	v_mfma_f32_16x16x32_bf16 v[76:79], v[188:191], v[208:211], v[76:79]
	ds_read_b128 v[160:163], v232 offset:4096
	s_add_u32 m0, s11, 16384
	s_nop 0
	global_load_lds_dwordx4 v228, s[2:3]
	v_mfma_f32_16x16x32_bf16 v[80:83], v[176:179], v[212:215], v[80:83]
	v_mfma_f32_16x16x32_bf16 v[84:87], v[180:183], v[212:215], v[84:87]
	v_mfma_f32_16x16x32_bf16 v[88:91], v[184:187], v[212:215], v[88:91]
	v_mfma_f32_16x16x32_bf16 v[92:95], v[188:191], v[212:215], v[92:95]
	ds_read_b128 v[164:167], v232 offset:5120
	s_add_u32 m0, s11, 20480
	s_nop 0
	global_load_lds_dwordx4 v229, s[2:3]
	v_mfma_f32_16x16x32_bf16 v[96:99], v[176:179], v[216:219], v[96:99]
	v_mfma_f32_16x16x32_bf16 v[100:103], v[180:183], v[216:219], v[100:103]
	v_mfma_f32_16x16x32_bf16 v[104:107], v[184:187], v[216:219], v[104:107]
	v_mfma_f32_16x16x32_bf16 v[108:111], v[188:191], v[216:219], v[108:111]
	ds_read_b128 v[168:171], v232 offset:6144
	s_add_u32 s0, s0, 64
	s_addc_u32 s1, s1, 0
	s_add_u32 s2, s2, 64
	s_addc_u32 s3, s3, 0
	s_add_u32 s100, s100, 1
	s_add_u32 s19, s19, 24576
	s_cmp_eq_u32 s19, 73728
	s_cselect_b32 s19, 0, s19
	s_add_u32 s98, s98, 24576
	s_cmp_eq_u32 s98, 73728
	s_cselect_b32 s98, 0, s98
	v_mfma_f32_16x16x32_bf16 v[112:115], v[176:179], v[220:223], v[112:115]
	v_mfma_f32_16x16x32_bf16 v[116:119], v[180:183], v[220:223], v[116:119]
	v_mfma_f32_16x16x32_bf16 v[120:123], v[184:187], v[220:223], v[120:123]
	v_mfma_f32_16x16x32_bf16 v[124:127], v[188:191], v[220:223], v[124:127]
	ds_read_b128 v[172:175], v232 offset:7168
	s_setprio 0
	s_add_u32 s99, s99, 2
	s_cmp_lt_u32 s99, 12
	s_cbranch_scc1 .Lg14_kloop
	s_waitcnt vmcnt(6)
	s_waitcnt lgkmcnt(0)
	s_barrier
	v_add_u32_e32 v232, s98, v230
	v_add_u32_e32 v233, s98, v231
	s_add_u32 s11, s19, s101
	s_setprio 1
	v_mfma_f32_16x16x32_bf16 v[0:3], v[128:131], v[144:147], v[0:3]
	v_mfma_f32_16x16x32_bf16 v[4:7], v[132:135], v[144:147], v[4:7]
	v_mfma_f32_16x16x32_bf16 v[8:11], v[136:139], v[144:147], v[8:11]
	v_mfma_f32_16x16x32_bf16 v[12:15], v[140:143], v[144:147], v[12:15]
	ds_read_b128 v[176:179], v233 offset:0
	ds_read_b128 v[180:183], v233 offset:1024
	s_add_u32 m0, s11, 0
	s_nop 0
	global_load_lds_dwordx4 v224, s[0:1]
	v_mfma_f32_16x16x32_bf16 v[16:19], v[128:131], v[148:151], v[16:19]
	v_mfma_f32_16x16x32_bf16 v[20:23], v[132:135], v[148:151], v[20:23]
	v_mfma_f32_16x16x32_bf16 v[24:27], v[136:139], v[148:151], v[24:27]
	v_mfma_f32_16x16x32_bf16 v[28:31], v[140:143], v[148:151], v[28:31]
	ds_read_b128 v[184:187], v233 offset:2048
	ds_read_b128 v[188:191], v233 offset:3072
	s_add_u32 m0, s11, 4096
	s_nop 0
	global_load_lds_dwordx4 v225, s[0:1]
	v_mfma_f32_16x16x32_bf16 v[32:35], v[128:131], v[152:155], v[32:35]
	v_mfma_f32_16x16x32_bf16 v[36:39], v[132:135], v[152:155], v[36:39]
	v_mfma_f32_16x16x32_bf16 v[40:43], v[136:139], v[152:155], v[40:43]
	v_mfma_f32_16x16x32_bf16 v[44:47], v[140:143], v[152:155], v[44:47]
	ds_read_b128 v[192:195], v232 offset:0
	ds_read_b128 v[196:199], v232 offset:1024
	s_add_u32 m0, s11, 8192
	s_nop 0
	global_load_lds_dwordx4 v226, s[0:1]
	v_mfma_f32_16x16x32_bf16 v[48:51], v[128:131], v[156:159], v[48:51]
	v_mfma_f32_16x16x32_bf16 v[52:55], v[132:135], v[156:159], v[52:55]
	v_mfma_f32_16x16x32_bf16 v[56:59], v[136:139], v[156:159], v[56:59]
	v_mfma_f32_16x16x32_bf16 v[60:63], v[140:143], v[156:159], v[60:63]
	ds_read_b128 v[200:203], v232 offset:2048
	ds_read_b128 v[204:207], v232 offset:3072
	s_add_u32 m0, s11, 12288
	s_nop 0
	global_load_lds_dwordx4 v227, s[0:1]
	v_mfma_f32_16x16x32_bf16 v[64:67], v[128:131], v[160:163], v[64:67]
	v_mfma_f32_16x16x32_bf16 v[68:71], v[132:135], v[160:163], v[68:71]
	v_mfma_f32_16x16x32_bf16 v[72:75], v[136:139], v[160:163], v[72:75]
	v_mfma_f32_16x16x32_bf16 v[76:79], v[140:143], v[160:163], v[76:79]
	ds_read_b128 v[208:211], v232 offset:4096
	s_add_u32 m0, s11, 16384
	s_nop 0
	global_load_lds_dwordx4 v228, s[2:3]
	v_mfma_f32_16x16x32_bf16 v[80:83], v[128:131], v[164:167], v[80:83]
	v_mfma_f32_16x16x32_bf16 v[84:87], v[132:135], v[164:167], v[84:87]
	v_mfma_f32_16x16x32_bf16 v[88:91], v[136:139], v[164:167], v[88:91]
	v_mfma_f32_16x16x32_bf16 v[92:95], v[140:143], v[164:167], v[92:95]
	ds_read_b128 v[212:215], v232 offset:5120
	s_add_u32 m0, s11, 20480
	s_nop 0
	global_load_lds_dwordx4 v229, s[2:3]
	v_mfma_f32_16x16x32_bf16 v[96:99], v[128:131], v[168:171], v[96:99]
	v_mfma_f32_16x16x32_bf16 v[100:103], v[132:135], v[168:171], v[100:103]
	v_mfma_f32_16x16x32_bf16 v[104:107], v[136:139], v[168:171], v[104:107]
	v_mfma_f32_16x16x32_bf16 v[108:111], v[140:143], v[168:171], v[108:111]
	ds_read_b128 v[216:219], v232 offset:6144
	s_add_u32 s0, s0, 64
	s_addc_u32 s1, s1, 0
	s_add_u32 s2, s2, 64
	s_addc_u32 s3, s3, 0
	s_add_u32 s100, s100, 1
	s_add_u32 s19, s19, 24576
	s_cmp_eq_u32 s19, 73728
	s_cselect_b32 s19, 0, s19
	s_add_u32 s98, s98, 24576
	s_cmp_eq_u32 s98, 73728
	s_cselect_b32 s98, 0, s98
	v_mfma_f32_16x16x32_bf16 v[112:115], v[128:131], v[172:175], v[112:115]
	v_mfma_f32_16x16x32_bf16 v[116:119], v[132:135], v[172:175], v[116:119]
	v_mfma_f32_16x16x32_bf16 v[120:123], v[136:139], v[172:175], v[120:123]
	v_mfma_f32_16x16x32_bf16 v[124:127], v[140:143], v[172:175], v[124:127]
	ds_read_b128 v[220:223], v232 offset:7168
	s_setprio 0
	s_waitcnt vmcnt(6)
	s_waitcnt lgkmcnt(0)
	s_barrier
; #define LWRITE(S, buf) do { bf16_t* sA_ = sbase + (buf) * BUF; bf16_t* sB_ = sA_ + 256 * PITCH; \
;     _Pragma("unroll") for (int i_ = 0; i_ < 4; ++i_) *(u32x4*)(sA_ + (sr + i_ * 64) * PITCH + scv * 8) = ra[S][i_]; \
;     _Pragma("unroll") for (int i_ = 0; i_ < 2; ++i_) *(u32x4*)(sB_ + (sr + i_ * 64) * PITCH + scv * 8) = rb[S][i_]; } while (0)
; template <class Epi>
; DI void gemm_tile(char* smem, const bf16_t* __restrict__ A0, int lda0, int ksplit, const bf16_t* __restrict__ A1, int lda1,
;                   const bf16_t* __restrict__ Bt, int K, int row0, int col0, const Epi& epi, int tid) {
;     ...
;   __syncthreads();
;   {
;     const int last = nk - 1;
;     GLOAD(0, 0);
;     __builtin_amdgcn_sched_barrier(0);
;     GLOAD(1, 1);
;     __builtin_amdgcn_sched_barrier(0);
;     LWRITE(0, 0);
;     __builtin_amdgcn_sched_barrier(0);
;     GLOAD(0, (2 < last ? 2 : last));
;     __builtin_amdgcn_sched_barrier(0);
;     __syncthreads();
;     for (int kt = 0; kt < nk; kt += 2) {
;       LWRITE(1, 1);
;       __builtin_amdgcn_sched_barrier(0);
;       GLOAD(1, (kt + 3 < last ? kt + 3 : last));
;       __builtin_amdgcn_sched_barrier(0);
;       COMPUTE(0);
;       __syncthreads();
;       LWRITE(0, 0);
;       __builtin_amdgcn_sched_barrier(0);
;       GLOAD(0, (kt + 4 < last ? kt + 4 : last));
;       __builtin_amdgcn_sched_barrier(0);
;       COMPUTE(1);
;       __syncthreads();
;     }
	v_add_u32_e32 v232, s98, v230
	v_add_u32_e32 v233, s98, v231
	s_setprio 1
	v_mfma_f32_16x16x32_bf16 v[0:3], v[176:179], v[192:195], v[0:3]
	v_mfma_f32_16x16x32_bf16 v[4:7], v[180:183], v[192:195], v[4:7]
	v_mfma_f32_16x16x32_bf16 v[8:11], v[184:187], v[192:195], v[8:11]
	v_mfma_f32_16x16x32_bf16 v[12:15], v[188:191], v[192:195], v[12:15]
	ds_read_b128 v[128:131], v233 offset:0
	ds_read_b128 v[132:135], v233 offset:1024
	v_mfma_f32_16x16x32_bf16 v[16:19], v[176:179], v[196:199], v[16:19]
	v_mfma_f32_16x16x32_bf16 v[20:23], v[180:183], v[196:199], v[20:23]
	v_mfma_f32_16x16x32_bf16 v[24:27], v[184:187], v[196:199], v[24:27]
	v_mfma_f32_16x16x32_bf16 v[28:31], v[188:191], v[196:199], v[28:31]
	ds_read_b128 v[136:139], v233 offset:2048
	ds_read_b128 v[140:143], v233 offset:3072
	v_mfma_f32_16x16x32_bf16 v[32:35], v[176:179], v[200:203], v[32:35]
	v_mfma_f32_16x16x32_bf16 v[36:39], v[180:183], v[200:203], v[36:39]
	v_mfma_f32_16x16x32_bf16 v[40:43], v[184:187], v[200:203], v[40:43]
	v_mfma_f32_16x16x32_bf16 v[44:47], v[188:191], v[200:203], v[44:47]
	ds_read_b128 v[144:147], v232 offset:0
	ds_read_b128 v[148:151], v232 offset:1024
	v_mfma_f32_16x16x32_bf16 v[48:51], v[176:179], v[204:207], v[48:51]
	v_mfma_f32_16x16x32_bf16 v[52:55], v[180:183], v[204:207], v[52:55]
	v_mfma_f32_16x16x32_bf16 v[56:59], v[184:187], v[204:207], v[56:59]
	v_mfma_f32_16x16x32_bf16 v[60:63], v[188:191], v[204:207], v[60:63]
	ds_read_b128 v[152:155], v232 offset:2048
	ds_read_b128 v[156:159], v232 offset:3072
	v_mfma_f32_16x16x32_bf16 v[64:67], v[176:179], v[208:211], v[64:67]
	v_mfma_f32_16x16x32_bf16 v[68:71], v[180:183], v[208:211], v[68:71]
	v_mfma_f32_16x16x32_bf16 v[72:75], v[184:187], v[208:211], v[72:75]
	v_mfma_f32_16x16x32_bf16 v[76:79], v[188:191], v[208:211], v[76:79]
	ds_read_b128 v[160:163], v232 offset:4096
	v_mfma_f32_16x16x32_bf16 v[80:83], v[176:179], v[212:215], v[80:83]
	v_mfma_f32_16x16x32_bf16 v[84:87], v[180:183], v[212:215], v[84:87]
	v_mfma_f32_16x16x32_bf16 v[88:91], v[184:187], v[212:215], v[88:91]
	v_mfma_f32_16x16x32_bf16 v[92:95], v[188:191], v[212:215], v[92:95]
	ds_read_b128 v[164:167], v232 offset:5120
	v_mfma_f32_16x16x32_bf16 v[96:99], v[176:179], v[216:219], v[96:99]
	v_mfma_f32_16x16x32_bf16 v[100:103], v[180:183], v[216:219], v[100:103]
	v_mfma_f32_16x16x32_bf16 v[104:107], v[184:187], v[216:219], v[104:107]
	v_mfma_f32_16x16x32_bf16 v[108:111], v[188:191], v[216:219], v[108:111]
	ds_read_b128 v[168:171], v232 offset:6144
	s_add_u32 s98, s98, 24576
	s_cmp_eq_u32 s98, 73728
	s_cselect_b32 s98, 0, s98
	v_mfma_f32_16x16x32_bf16 v[112:115], v[176:179], v[220:223], v[112:115]
	v_mfma_f32_16x16x32_bf16 v[116:119], v[180:183], v[220:223], v[116:119]
	v_mfma_f32_16x16x32_bf16 v[120:123], v[184:187], v[220:223], v[120:123]
	v_mfma_f32_16x16x32_bf16 v[124:127], v[188:191], v[220:223], v[124:127]
	ds_read_b128 v[172:175], v232 offset:7168
	s_setprio 0
	s_waitcnt vmcnt(0)
	s_waitcnt lgkmcnt(0)
	s_barrier
; #define LWRITE(S, buf) do { bf16_t* sA_ = sbase + (buf) * BUF; bf16_t* sB_ = sA_ + 256 * PITCH; \
;     _Pragma("unroll") for (int i_ = 0; i_ < 4; ++i_) *(u32x4*)(sA_ + (sr + i_ * 64) * PITCH + scv * 8) = ra[S][i_]; \
;     _Pragma("unroll") for (int i_ = 0; i_ < 2; ++i_) *(u32x4*)(sB_ + (sr + i_ * 64) * PITCH + scv * 8) = rb[S][i_]; } while (0)
; template <class Epi>
; DI void gemm_tile(char* smem, const bf16_t* __restrict__ A0, int lda0, int ksplit, const bf16_t* __restrict__ A1, int lda1,
;                   const bf16_t* __restrict__ Bt, int K, int row0, int col0, const Epi& epi, int tid) {
;     ...
;   __syncthreads();
;   {
;     const int last = nk - 1;
;     GLOAD(0, 0);
;     __builtin_amdgcn_sched_barrier(0);
;     GLOAD(1, 1);
;     __builtin_amdgcn_sched_barrier(0);
;     LWRITE(0, 0);
;     __builtin_amdgcn_sched_barrier(0);
;     GLOAD(0, (2 < last ? 2 : last));
;     __builtin_amdgcn_sched_barrier(0);
;     __syncthreads();
;     for (int kt = 0; kt < nk; kt += 2) {
;       LWRITE(1, 1);
;       __builtin_amdgcn_sched_barrier(0);
;       GLOAD(1, (kt + 3 < last ? kt + 3 : last));
;       __builtin_amdgcn_sched_barrier(0);
;       COMPUTE(0);
;       __syncthreads();
;       LWRITE(0, 0);
;       __builtin_amdgcn_sched_barrier(0);
;       GLOAD(0, (kt + 4 < last ? kt + 4 : last));
;       __builtin_amdgcn_sched_barrier(0);
;       COMPUTE(1);
;       __syncthreads();
;     }
	v_add_u32_e32 v232, s98, v230
	v_add_u32_e32 v233, s98, v231
	s_setprio 1
	v_mfma_f32_16x16x32_bf16 v[0:3], v[128:131], v[144:147], v[0:3]
	v_mfma_f32_16x16x32_bf16 v[4:7], v[132:135], v[144:147], v[4:7]
	v_mfma_f32_16x16x32_bf16 v[8:11], v[136:139], v[144:147], v[8:11]
	v_mfma_f32_16x16x32_bf16 v[12:15], v[140:143], v[144:147], v[12:15]
	ds_read_b128 v[176:179], v233 offset:0
	ds_read_b128 v[180:183], v233 offset:1024
	v_mfma_f32_16x16x32_bf16 v[16:19], v[128:131], v[148:151], v[16:19]
	v_mfma_f32_16x16x32_bf16 v[20:23], v[132:135], v[148:151], v[20:23]
	v_mfma_f32_16x16x32_bf16 v[24:27], v[136:139], v[148:151], v[24:27]
	v_mfma_f32_16x16x32_bf16 v[28:31], v[140:143], v[148:151], v[28:31]
	ds_read_b128 v[184:187], v233 offset:2048
	ds_read_b128 v[188:191], v233 offset:3072
	v_mfma_f32_16x16x32_bf16 v[32:35], v[128:131], v[152:155], v[32:35]
	v_mfma_f32_16x16x32_bf16 v[36:39], v[132:135], v[152:155], v[36:39]
	v_mfma_f32_16x16x32_bf16 v[40:43], v[136:139], v[152:155], v[40:43]
	v_mfma_f32_16x16x32_bf16 v[44:47], v[140:143], v[152:155], v[44:47]
	ds_read_b128 v[192:195], v232 offset:0
	ds_read_b128 v[196:199], v232 offset:1024
	v_mfma_f32_16x16x32_bf16 v[48:51], v[128:131], v[156:159], v[48:51]
	v_mfma_f32_16x16x32_bf16 v[52:55], v[132:135], v[156:159], v[52:55]
	v_mfma_f32_16x16x32_bf16 v[56:59], v[136:139], v[156:159], v[56:59]
	v_mfma_f32_16x16x32_bf16 v[60:63], v[140:143], v[156:159], v[60:63]
	ds_read_b128 v[200:203], v232 offset:2048
	ds_read_b128 v[204:207], v232 offset:3072
	v_mfma_f32_16x16x32_bf16 v[64:67], v[128:131], v[160:163], v[64:67]
	v_mfma_f32_16x16x32_bf16 v[68:71], v[132:135], v[160:163], v[68:71]
	v_mfma_f32_16x16x32_bf16 v[72:75], v[136:139], v[160:163], v[72:75]
	v_mfma_f32_16x16x32_bf16 v[76:79], v[140:143], v[160:163], v[76:79]
	ds_read_b128 v[208:211], v232 offset:4096
	v_mfma_f32_16x16x32_bf16 v[80:83], v[128:131], v[164:167], v[80:83]
	v_mfma_f32_16x16x32_bf16 v[84:87], v[132:135], v[164:167], v[84:87]
	v_mfma_f32_16x16x32_bf16 v[88:91], v[136:139], v[164:167], v[88:91]
	v_mfma_f32_16x16x32_bf16 v[92:95], v[140:143], v[164:167], v[92:95]
	ds_read_b128 v[212:215], v232 offset:5120
	v_mfma_f32_16x16x32_bf16 v[96:99], v[128:131], v[168:171], v[96:99]
	v_mfma_f32_16x16x32_bf16 v[100:103], v[132:135], v[168:171], v[100:103]
	v_mfma_f32_16x16x32_bf16 v[104:107], v[136:139], v[168:171], v[104:107]
	v_mfma_f32_16x16x32_bf16 v[108:111], v[140:143], v[168:171], v[108:111]
	ds_read_b128 v[216:219], v232 offset:6144
	s_add_u32 s98, s98, 24576
	s_cmp_eq_u32 s98, 73728
	s_cselect_b32 s98, 0, s98
	v_mfma_f32_16x16x32_bf16 v[112:115], v[128:131], v[172:175], v[112:115]
	v_mfma_f32_16x16x32_bf16 v[116:119], v[132:135], v[172:175], v[116:119]
	v_mfma_f32_16x16x32_bf16 v[120:123], v[136:139], v[172:175], v[120:123]
	v_mfma_f32_16x16x32_bf16 v[124:127], v[140:143], v[172:175], v[124:127]
	ds_read_b128 v[220:223], v232 offset:7168
	s_setprio 0
	s_waitcnt lgkmcnt(0)
	s_barrier
	s_setprio 1
	v_mfma_f32_16x16x32_bf16 v[0:3], v[176:179], v[192:195], v[0:3]
	v_mfma_f32_16x16x32_bf16 v[4:7], v[180:183], v[192:195], v[4:7]
	v_mfma_f32_16x16x32_bf16 v[8:11], v[184:187], v[192:195], v[8:11]
	v_mfma_f32_16x16x32_bf16 v[12:15], v[188:191], v[192:195], v[12:15]
	v_mfma_f32_16x16x32_bf16 v[16:19], v[176:179], v[196:199], v[16:19]
	v_mfma_f32_16x16x32_bf16 v[20:23], v[180:183], v[196:199], v[20:23]
	v_mfma_f32_16x16x32_bf16 v[24:27], v[184:187], v[196:199], v[24:27]
	v_mfma_f32_16x16x32_bf16 v[28:31], v[188:191], v[196:199], v[28:31]
	v_mfma_f32_16x16x32_bf16 v[32:35], v[176:179], v[200:203], v[32:35]
	v_mfma_f32_16x16x32_bf16 v[36:39], v[180:183], v[200:203], v[36:39]
	v_mfma_f32_16x16x32_bf16 v[40:43], v[184:187], v[200:203], v[40:43]
	v_mfma_f32_16x16x32_bf16 v[44:47], v[188:191], v[200:203], v[44:47]
	v_mfma_f32_16x16x32_bf16 v[48:51], v[176:179], v[204:207], v[48:51]
	v_mfma_f32_16x16x32_bf16 v[52:55], v[180:183], v[204:207], v[52:55]
	v_mfma_f32_16x16x32_bf16 v[56:59], v[184:187], v[204:207], v[56:59]
	v_mfma_f32_16x16x32_bf16 v[60:63], v[188:191], v[204:207], v[60:63]
	v_mfma_f32_16x16x32_bf16 v[64:67], v[176:179], v[208:211], v[64:67]
	v_mfma_f32_16x16x32_bf16 v[68:71], v[180:183], v[208:211], v[68:71]
	v_mfma_f32_16x16x32_bf16 v[72:75], v[184:187], v[208:211], v[72:75]
	v_mfma_f32_16x16x32_bf16 v[76:79], v[188:191], v[208:211], v[76:79]
	v_mfma_f32_16x16x32_bf16 v[80:83], v[176:179], v[212:215], v[80:83]
	v_mfma_f32_16x16x32_bf16 v[84:87], v[180:183], v[212:215], v[84:87]
	v_mfma_f32_16x16x32_bf16 v[88:91], v[184:187], v[212:215], v[88:91]
	v_mfma_f32_16x16x32_bf16 v[92:95], v[188:191], v[212:215], v[92:95]
	v_mfma_f32_16x16x32_bf16 v[96:99], v[176:179], v[216:219], v[96:99]
	v_mfma_f32_16x16x32_bf16 v[100:103], v[180:183], v[216:219], v[100:103]
	v_mfma_f32_16x16x32_bf16 v[104:107], v[184:187], v[216:219], v[104:107]
	v_mfma_f32_16x16x32_bf16 v[108:111], v[188:191], v[216:219], v[108:111]
	v_mfma_f32_16x16x32_bf16 v[112:115], v[176:179], v[220:223], v[112:115]
	v_mfma_f32_16x16x32_bf16 v[116:119], v[180:183], v[220:223], v[116:119]
	v_mfma_f32_16x16x32_bf16 v[120:123], v[184:187], v[220:223], v[120:123]
	v_mfma_f32_16x16x32_bf16 v[124:127], v[188:191], v[220:223], v[124:127]
	s_setprio 0
	s_branch .Lg14_epi

; #define PH(k) case k: if (ONLY_PHASE >= 0 && ONLY_PHASE != k) break;
; template <class Epi>
; DI void gemm_tile(char* smem, const bf16_t* __restrict__ A0, int lda0, int ksplit, const bf16_t* __restrict__ A1, int lda1,
;                   const bf16_t* __restrict__ Bt, int K, int row0, int col0, const Epi& epi, int tid) {
;   constexpr int BK = 32, PITCH = 40, BUF = (256 + 128) * PITCH;
;   bf16_t* sbase = (bf16_t*)smem;
;   const int lane = tid & 63, wid = tid >> 6, wr = wid >> 1, wc = wid & 1, fr = lane & 15, fq = lane >> 4;
;   f32x4 acc[8][4];
; #pragma unroll
;   for (int m = 0; m < 8; ++m)
; #pragma unroll
;     for (int n = 0; n < 4; ++n) acc[m][n] = (f32x4){0.f, 0.f, 0.f, 0.f};
;   u32x4 ra[2][4], rb[2][2];
;   const int nk = K / BK;
;   const int sr = tid >> 2, scv = tid & 3;
; template <int ph> DI void run_phase(const Ctx& c, char* smem) {
;     ...
;     PH(15) gemm_phase(smem, (const bf16_t*)(ws + OFF_S5Y), 512, 512, (const bf16_t*)(ws + OFF_MLRAW) + 1024, 2080, (const bf16_t*)(ws + OFF_WCDOUT), 1536, 8, EpiResid{p.out, p.out}, TIDX); break;
.LBB0_1844:
	s_cmp_gt_i32 s94, 15
	s_cselect_b64 s[0:1], -1, 0
	s_cmp_lt_i32 s95, 16
	s_cselect_b64 s[2:3], -1, 0
	s_or_b64 s[0:1], s[0:1], s[2:3]
	s_and_b64 vcc, exec, s[0:1]
	s_cbranch_vccnz .LBB0_1872
	s_add_u32 s0, s92, 0x11a00000
	s_load_dword s12, s[74:75], 0x180
	s_addc_u32 s1, s93, 0
	s_add_u32 s6, s92, 0x9800800
	s_addc_u32 s7, s93, 0
	s_add_u32 s2, s92, 0x3100000
	s_addc_u32 s3, s93, 0
	s_and_b32 s8, s72, 0xffffffc0
	v_mbcnt_hi_u32_b32 v195, -1, v194
	s_waitcnt lgkmcnt(0)
	s_and_b32 s10, s12, 7
	s_cmp_lg_u32 s10, 0
	s_waitcnt vmcnt(16)
	v_add_u32_e32 v196, s8, v195
	v_mbcnt_lo_u32_b32 v240, -1, 0
	v_mbcnt_hi_u32_b32 v240, -1, v240
	s_lshr_b32 s20, s72, 6
	s_lshl_b32 s13, s20, 10
	v_and_b32_e32 v241, 15, v240
	v_lshrrev_b32_e32 v242, 4, v240
	v_bfe_u32 v243, v240, 3, 1
	v_mul_u32_u24_e32 v243, 3, v243
	v_xor_b32_e32 v243, v242, v243
	v_lshlrev_b32_e32 v243, 4, v243
	v_lshl_add_u32 v243, v241, 6, v243
	s_lshr_b32 s19, s20, 1
	s_lshl_b32 s19, s19, 13
	v_add_u32_e32 v230, s19, v243
	s_and_b32 s19, s20, 1
	s_lshl_b32 s19, s19, 12
	s_add_u32 s19, s19, 16384
	v_add_u32_e32 v231, s19, v243
	s_lshr_b32 s19, s20, 1
	s_lshl_b32 s19, s19, 7
	v_add_u32_e32 v244, s19, v241
	s_and_b32 s19, s20, 1
	s_lshl_b32 s19, s19, 6
	v_lshl_add_u32 v245, v242, 2, s19
	s_movk_i32 s19, 0x1000
	v_mul_lo_u32 v246, v244, s19
	v_lshl_add_u32 v234, v245, 2, v246
	v_lshrrev_b32_e32 v241, 2, v240
	s_lshl_b32 s19, s20, 4
	v_add_u32_e32 v241, s19, v241
	v_bfe_u32 v242, v240, 5, 1
	v_mul_u32_u24_e32 v242, 3, v242
	v_and_b32_e32 v243, 3, v240
	v_xor_b32_e32 v243, v243, v242
	v_lshlrev_b32_e32 v243, 4, v243
	s_mov_b32 s19, 1024
	v_mad_u32_u24 v224, v241, s19, v243
	v_add_u32_e32 v225, 0x10000, v224
	v_add_u32_e32 v226, 0x20000, v224
	v_add_u32_e32 v227, 0x30000, v224
	s_mov_b32 s19, 4160
	v_mad_u32_u24 v236, v241, s19, v243
	v_add_u32_e32 v237, 0x41000, v236
	v_add_u32_e32 v238, 0x82000, v236
	v_add_u32_e32 v239, 0xc3000, v236
	v_mov_b32_e32 v248, v224
	v_mov_b32_e32 v249, v225
	v_mov_b32_e32 v250, v226
	v_mov_b32_e32 v251, v227
	s_mov_b32 s19, 3072
	v_mad_u32_u24 v228, v241, s19, v243
	v_add_u32_e32 v229, 0x30000, v228
	s_load_dwordx2 s[6:7], s[74:75], 0x168
	v_mbcnt_lo_u32_b32 v240, -1, 0
	v_mbcnt_hi_u32_b32 v240, -1, v240
	s_lshr_b32 s20, s72, 6
	s_mul_i32 s19, s20, 17408
	v_and_b32_e32 v241, 15, v240
	v_lshrrev_b32_e32 v242, 4, v240
	v_mul_u32_u24_e32 v243, 0x110, v241
	v_lshl_add_u32 v243, v242, 4, v243
	v_add_u32_e32 v245, s19, v243
	v_mul_u32_u24_e32 v243, 0x110, v242
	v_lshl_add_u32 v243, v241, 4, v243
	v_add_u32_e32 v246, s19, v243
	s_lshr_b32 s19, s20, 1
	s_lshl_b32 s19, s19, 7
	v_add_u32_e32 v243, s19, v242
	v_lshlrev_b32_e32 v243, 12, v243
	s_and_b32 s19, s20, 1
	s_lshl_b32 s19, s19, 8
	v_lshl_add_u32 v244, v241, 4, s19
	v_add_u32_e32 v247, v243, v244
	s_cmpk_gt_u32 s96, 0xff
	s_cbranch_scc0 .Lg15_prio
	s_setprio 1

; #define PH(k) case k: if (ONLY_PHASE >= 0 && ONLY_PHASE != k) break;
; template <class Epi>
; DI void gemm_tile(char* smem, const bf16_t* __restrict__ A0, int lda0, int ksplit, const bf16_t* __restrict__ A1, int lda1,
;                   const bf16_t* __restrict__ Bt, int K, int row0, int col0, const Epi& epi, int tid) {
;   constexpr int BK = 32, PITCH = 40, BUF = (256 + 128) * PITCH;
;   bf16_t* sbase = (bf16_t*)smem;
;   const int lane = tid & 63, wid = tid >> 6, wr = wid >> 1, wc = wid & 1, fr = lane & 15, fq = lane >> 4;
;   f32x4 acc[8][4];
; #pragma unroll
;   for (int m = 0; m < 8; ++m)
; #pragma unroll
;     for (int n = 0; n < 4; ++n) acc[m][n] = (f32x4){0.f, 0.f, 0.f, 0.f};
;   u32x4 ra[2][4], rb[2][2];
;   const int nk = K / BK;
;   const int sr = tid >> 2, scv = tid & 3;
; template <int ph> DI void run_phase(const Ctx& c, char* smem) {
;     ...
;     PH(17) gemm_phase(smem, XN, 1024, 1 << 30, XN, 1024, (const bf16_t*)(ws + OFF_W1) + 4096ull * 1024, 1024, 32, EpiRelu2{(bf16_t*)(ws + OFF_R1)}, TIDX); break;
.LBB0_1890:
	s_cmp_gt_i32 s94, 17
	s_cselect_b64 s[0:1], -1, 0
	s_cmp_lt_i32 s95, 18
	s_cselect_b64 s[2:3], -1, 0
	s_or_b64 s[0:1], s[0:1], s[2:3]
	s_and_b64 vcc, exec, s[0:1]
	s_cbranch_vccnz .LBB0_1918
	s_add_u32 s2, s92, 0x3800000
	s_waitcnt lgkmcnt(0)
	s_load_dword s14, s[74:75], 0x180
	s_addc_u32 s3, s93, 0
	s_add_u32 s4, s92, 0x13c0000
	s_addc_u32 s5, s93, 0
	s_add_u32 s0, s92, 0x7800000
	s_addc_u32 s1, s93, 0
	s_and_b32 s16, s72, 0xffffffc0
	v_mbcnt_hi_u32_b32 v195, -1, v194
	s_waitcnt lgkmcnt(0)
	s_and_b32 s15, s14, 7
	s_cmp_lg_u32 s15, 0
	s_waitcnt vmcnt(16)
	v_add_u32_e32 v196, s16, v195
	v_mbcnt_lo_u32_b32 v240, -1, 0
	v_mbcnt_hi_u32_b32 v240, -1, v240
	s_lshr_b32 s12, s72, 6
	s_lshl_b32 s101, s12, 10
	v_and_b32_e32 v241, 15, v240
	v_lshrrev_b32_e32 v242, 4, v240
	v_bfe_u32 v243, v240, 3, 1
	v_mul_u32_u24_e32 v243, 3, v243
	v_xor_b32_e32 v243, v242, v243
	v_lshlrev_b32_e32 v243, 4, v243
	v_lshl_add_u32 v243, v241, 6, v243
	s_lshr_b32 s11, s12, 1
	s_lshl_b32 s11, s11, 13
	v_add_u32_e32 v230, s11, v243
	s_and_b32 s11, s12, 1
	s_lshl_b32 s11, s11, 12
	s_add_u32 s11, s11, 16384
	v_add_u32_e32 v231, s11, v243
	s_lshr_b32 s11, s12, 1
	s_lshl_b32 s11, s11, 7
	v_add_u32_e32 v244, s11, v241
	s_and_b32 s11, s12, 1
	s_lshl_b32 s11, s11, 6
	v_lshl_add_u32 v245, v242, 2, s11
	s_movk_i32 s11, 0x2000
	v_mul_lo_u32 v246, v244, s11
	v_lshl_add_u32 v234, v245, 1, v246
	s_mul_i32 s11, s12, 18432
	v_mul_u32_u24_e32 v246, 144, v241
	v_lshl_add_u32 v246, v242, 3, v246
	v_add_u32_e32 v236, s11, v246
	v_lshrrev_b32_e32 v246, 3, v240
	v_mul_u32_u24_e32 v246, 144, v246
	v_and_b32_e32 v247, 7, v240
	v_lshl_add_u32 v246, v247, 4, v246
	v_add_u32_e32 v237, s11, v246
	s_lshr_b32 s11, s12, 1
	s_lshl_b32 s11, s11, 7
	v_lshrrev_b32_e32 v246, 3, v240
	v_add_u32_e32 v246, s11, v246
	s_and_b32 s11, s12, 1
	s_lshl_b32 s11, s11, 6
	v_lshl_add_u32 v248, v247, 3, s11
	s_movk_i32 s11, 8192
	v_mul_lo_u32 v247, v246, s11
	v_lshl_add_u32 v238, v248, 1, v247
	v_lshrrev_b32_e32 v241, 2, v240
	s_lshl_b32 s11, s12, 4
	v_add_u32_e32 v241, s11, v241
	v_bfe_u32 v242, v240, 5, 1
	v_mul_u32_u24_e32 v242, 3, v242
	v_and_b32_e32 v243, 3, v240
	v_xor_b32_e32 v243, v243, v242
	v_lshlrev_b32_e32 v243, 4, v243
	s_mov_b32 s11, 2048
	v_mad_u32_u24 v224, v241, s11, v243
	v_add_u32_e32 v225, 0x20000, v224
	v_add_u32_e32 v226, 0x40000, v224
	v_add_u32_e32 v227, 0x60000, v224
	s_mov_b32 s11, 2048
	v_mad_u32_u24 v228, v241, s11, v243
	v_add_u32_e32 v229, 0x20000, v228
	s_cmpk_gt_u32 s96, 0xff
	s_cbranch_scc0 .Lg17_prio
	s_setprio 1

; #define PH(k) case k: if (ONLY_PHASE >= 0 && ONLY_PHASE != k) break;
; template <class Epi>
; DI void gemm_tile(char* smem, const bf16_t* __restrict__ A0, int lda0, int ksplit, const bf16_t* __restrict__ A1, int lda1,
;                   const bf16_t* __restrict__ Bt, int K, int row0, int col0, const Epi& epi, int tid) {
;   constexpr int BK = 32, PITCH = 40, BUF = (256 + 128) * PITCH;
;   bf16_t* sbase = (bf16_t*)smem;
;   const int lane = tid & 63, wid = tid >> 6, wr = wid >> 1, wc = wid & 1, fr = lane & 15, fq = lane >> 4;
;   f32x4 acc[8][4];
; #pragma unroll
;   for (int m = 0; m < 8; ++m)
; #pragma unroll
;     for (int n = 0; n < 4; ++n) acc[m][n] = (f32x4){0.f, 0.f, 0.f, 0.f};
;   u32x4 ra[2][4], rb[2][2];
;   const int nk = K / BK;
;   const int sr = tid >> 2, scv = tid & 3;
; template <int ph> DI void run_phase(const Ctx& c, char* smem) {
;     ...
;     PH(18) gemm_phase(smem, (const bf16_t*)(ws + OFF_R1), 4096, 1 << 30, XN, 1024, (const bf16_t*)(ws + OFF_W2) + 4096ull * 1024, 4096, 8, EpiResid{p.out, p.out}, TIDX); break;
.LBB0_1918:
	s_cmp_gt_i32 s94, 18
	s_cselect_b64 s[0:1], -1, 0
	s_cmp_lt_i32 s95, 19
	s_cselect_b64 s[2:3], -1, 0
	s_or_b64 s[0:1], s[0:1], s[2:3]
	s_and_b64 vcc, exec, s[0:1]
	s_cbranch_vccnz .LBB0_1946
	s_load_dword s12, s[74:75], 0x180
	s_add_u32 s0, s92, 0x7800000
	s_addc_u32 s1, s93, 0
	s_add_u32 s2, s92, 0x23c0000
	s_addc_u32 s3, s93, 0
	s_waitcnt lgkmcnt(0)
	s_and_b32 s14, s72, 0xffffffc0
	v_mbcnt_hi_u32_b32 v195, -1, v194
	s_and_b32 s13, s12, 7
	s_cmp_lg_u32 s13, 0
	s_waitcnt vmcnt(16)
	v_add_u32_e32 v196, s14, v195
	v_mbcnt_lo_u32_b32 v240, -1, 0
	v_mbcnt_hi_u32_b32 v240, -1, v240
	s_lshr_b32 s10, s72, 6
	s_lshl_b32 s101, s10, 10
	v_and_b32_e32 v241, 15, v240
	v_lshrrev_b32_e32 v242, 4, v240
	v_bfe_u32 v243, v240, 3, 1
	v_mul_u32_u24_e32 v243, 3, v243
	v_xor_b32_e32 v243, v242, v243
	v_lshlrev_b32_e32 v243, 4, v243
	v_lshl_add_u32 v243, v241, 6, v243
	s_lshr_b32 s9, s10, 1
	s_lshl_b32 s9, s9, 13
	v_add_u32_e32 v230, s9, v243
	s_and_b32 s9, s10, 1
	s_lshl_b32 s9, s9, 12
	s_add_u32 s9, s9, 16384
	v_add_u32_e32 v231, s9, v243
	s_lshr_b32 s9, s10, 1
	s_lshl_b32 s9, s9, 7
	v_add_u32_e32 v244, s9, v241
	s_and_b32 s9, s10, 1
	s_lshl_b32 s9, s9, 6
	v_lshl_add_u32 v245, v242, 2, s9
	s_movk_i32 s9, 0x1000
	v_mul_lo_u32 v246, v244, s9
	v_lshl_add_u32 v234, v245, 2, v246
	v_lshrrev_b32_e32 v241, 2, v240
	s_lshl_b32 s9, s10, 4
	v_add_u32_e32 v241, s9, v241
	v_bfe_u32 v242, v240, 5, 1
	v_mul_u32_u24_e32 v242, 3, v242
	v_and_b32_e32 v243, 3, v240
	v_xor_b32_e32 v243, v243, v242
	v_lshlrev_b32_e32 v243, 4, v243
	s_mov_b32 s9, 8192
	v_mad_u32_u24 v224, v241, s9, v243
	v_add_u32_e32 v225, 0x80000, v224
	v_add_u32_e32 v226, 0x100000, v224
	v_add_u32_e32 v227, 0x180000, v224
	s_mov_b32 s9, 8192
	v_mad_u32_u24 v228, v241, s9, v243
	v_add_u32_e32 v229, 0x80000, v228
	s_load_dwordx2 s[6:7], s[74:75], 0x168
	v_mbcnt_lo_u32_b32 v240, -1, 0
	v_mbcnt_hi_u32_b32 v240, -1, v240
	s_lshr_b32 s10, s72, 6
	s_mul_i32 s9, s10, 17408
	v_and_b32_e32 v241, 15, v240
	v_lshrrev_b32_e32 v242, 4, v240
	v_mul_u32_u24_e32 v243, 0x110, v241
	v_lshl_add_u32 v243, v242, 4, v243
	v_add_u32_e32 v245, s9, v243
	v_mul_u32_u24_e32 v243, 0x110, v242
	v_lshl_add_u32 v243, v241, 4, v243
	v_add_u32_e32 v246, s9, v243
	s_lshr_b32 s9, s10, 1
	s_lshl_b32 s9, s9, 7
	v_add_u32_e32 v243, s9, v242
	v_lshlrev_b32_e32 v243, 12, v243
	s_and_b32 s9, s10, 1
	s_lshl_b32 s9, s9, 8
	v_lshl_add_u32 v244, v241, 4, s9
	v_add_u32_e32 v247, v243, v244
	s_cmpk_gt_u32 s96, 0xff
	s_cbranch_scc0 .Lg18_prio
	s_setprio 1
